# speedup vs baseline: 1.0030x; 1.0030x over previous
.LBB0_489:
	s_or_b64 exec, exec, s[2:3]
	v_ashrrev_i32_e32 v1, 2, v88
	v_add_u32_e32 v197, v18, v1
	s_waitcnt vmcnt(2)
	v_lshlrev_b32_e32 v1, 16, v52
	v_mul_f32_e32 v5, v94, v89
	v_and_b32_e32 v2, 0xffff0000, v52
	v_fmac_f32_e32 v5, v96, v1
	v_fmac_f32_e32 v5, v95, v2
	v_lshlrev_b32_e32 v3, 16, v53
	v_add_f32_e32 v89, v93, v5
	v_mul_f32_e32 v5, v96, v2
	v_fmac_f32_e32 v5, v94, v1
	v_mul_f32_e32 v1, v96, v3
	v_and_b32_e32 v4, 0xffff0000, v53
	v_fmac_f32_e32 v1, v94, v2
	v_fmac_f32_e32 v1, v95, v4
	v_add_f32_e32 v85, v93, v1
	v_mul_f32_e32 v1, v96, v4
	v_fmac_f32_e32 v1, v94, v3
	v_fmac_f32_e32 v5, v95, v3
	v_fmac_f32_e32 v1, v95, v105
	v_add_f32_e32 v91, v93, v5
	v_add_f32_e32 v87, v93, v1
	v_lshlrev_b32_e32 v1, 16, v50
	v_mul_f32_e32 v5, v94, v90
	v_and_b32_e32 v2, 0xffff0000, v50
	v_fmac_f32_e32 v5, v96, v1
	v_fmac_f32_e32 v5, v95, v2
	v_lshlrev_b32_e32 v3, 16, v51
	v_add_f32_e32 v88, v93, v5
	v_mul_f32_e32 v5, v96, v2
	v_fmac_f32_e32 v5, v94, v1
	v_mul_f32_e32 v1, v96, v3
	v_and_b32_e32 v4, 0xffff0000, v51
	v_fmac_f32_e32 v1, v94, v2
	v_fmac_f32_e32 v1, v95, v4
	v_add_f32_e32 v84, v93, v1
	v_mul_f32_e32 v1, v96, v4
	v_fmac_f32_e32 v1, v94, v3
	v_fmac_f32_e32 v1, v95, v104
	v_add_f32_e32 v86, v93, v1
	v_lshlrev_b32_e32 v1, 16, v48
	v_mul_f32_e32 v4, v101, v97
	v_and_b32_e32 v2, 0xffff0000, v48
	v_fmac_f32_e32 v4, v102, v1
	v_fmac_f32_e32 v4, v100, v2
	v_fmac_f32_e32 v5, v95, v3
	v_lshlrev_b32_e32 v8, 16, v49
	v_add_f32_e32 v95, v98, v4
	v_mul_f32_e32 v4, v102, v2
	v_fmac_f32_e32 v4, v101, v1
	v_mul_f32_e32 v1, v102, v8
	v_mov_b32_e32 v52, v180
	v_fmac_f32_e32 v1, v101, v2
	s_waitcnt lgkmcnt(0)
	s_barrier
	v_and_b32_e32 v3, 0xffff0000, v49
	v_ashrrev_i32_e32 v2, 31, v52
	v_add_u32_sdwa v2, v52, v2 dst_sel:DWORD dst_unused:UNUSED_PAD src0_sel:DWORD src1_sel:BYTE_3
	v_fmac_f32_e32 v1, v100, v3
	v_ashrrev_i32_e32 v2, 8, v2
	v_add_f32_e32 v90, v93, v5
	v_add_f32_e32 v93, v98, v1
	v_mul_f32_e32 v1, v102, v3
	v_mul_i32_i24_e32 v3, 0x100, v2
	v_sub_u32_e32 v3, v52, v3
	v_mul_i32_i24_e32 v48, 0x220, v2
	v_ashrrev_i32_e32 v2, 4, v3
	v_add_u32_e32 v49, 0x100, v3
	v_fmac_f32_e32 v4, v100, v8
	v_add_u32_e32 v2, v2, v3
	v_lshrrev_b32_e32 v50, 4, v49
	v_add_f32_e32 v97, v98, v4
	v_add_lshl_u32 v53, v2, v48, 3
	v_add3_u32 v4, v48, v3, v50
	v_add_u32_e32 v2, 0, v53
	v_lshl_add_u32 v4, v4, 3, 0
	v_lshl_add_u32 v6, v3, 3, 0
	ds_read_b64 v[2:3], v2 offset:6272
	ds_read_b64 v[4:5], v4 offset:8320
	ds_read_b64 v[6:7], v6 offset:4224
	v_fmac_f32_e32 v1, v101, v8
	v_fmac_f32_e32 v1, v100, v99
	v_add_f32_e32 v99, v98, v1
	v_add3_u32 v1, v48, v49, v50
	s_waitcnt lgkmcnt(0)
	v_pk_mul_f32 v[48:49], v[4:5], v[6:7] op_sel:[1,1] op_sel_hi:[1,0]
	v_lshl_add_u32 v1, v1, 3, s18
	v_pk_fma_f32 v[50:51], v[4:5], v[6:7], v[48:49] op_sel_hi:[0,1,1] neg_lo:[0,0,1]
	v_pk_add_f32 v[4:5], v[2:3], v[50:51]
	v_add_u32_e32 v6, s18, v53
	v_pk_add_f32 v[2:3], v[2:3], v[50:51] neg_lo:[0,1] neg_hi:[0,1]
	ds_write_b64 v6, v[4:5]
	ds_write_b64 v1, v[2:3]
	v_add_u32_e32 v1, 0x200, v52
	v_ashrrev_i32_e32 v2, 31, v1
	v_add_u32_sdwa v2, v1, v2 dst_sel:DWORD dst_unused:UNUSED_PAD src0_sel:DWORD src1_sel:BYTE_3
	v_ashrrev_i32_e32 v2, 8, v2
	v_mul_i32_i24_e32 v3, 0x100, v2
	v_sub_u32_e32 v1, v1, v3
	v_mul_i32_i24_e32 v8, 0x220, v2
	v_ashrrev_i32_e32 v2, 4, v1
	v_add_u32_e32 v48, 0x100, v1
	v_add_u32_e32 v2, v2, v1
	v_lshrrev_b32_e32 v49, 4, v48
	v_add_lshl_u32 v53, v2, v8, 3
	v_add3_u32 v3, v8, v1, v49
	v_add_u32_e32 v2, 0, v53
	v_lshl_add_u32 v4, v3, 3, 0
	v_lshl_add_u32 v1, v1, 3, 0
	ds_read_b64 v[2:3], v2 offset:6272
	ds_read_b64 v[4:5], v4 offset:8320
	ds_read_b64 v[6:7], v1 offset:4224
	v_add3_u32 v8, v8, v48, v49
	v_lshlrev_b32_e32 v1, 16, v46
	v_and_b32_e32 v54, 0xffff0000, v46
	v_lshlrev_b32_e32 v55, 16, v47
	s_waitcnt lgkmcnt(0)
	v_pk_mul_f32 v[48:49], v[4:5], v[6:7] op_sel:[1,1] op_sel_hi:[1,0]
	v_add_u32_e32 v0, 0x100, v18
	v_pk_fma_f32 v[50:51], v[4:5], v[6:7], v[48:49] op_sel_hi:[0,1,1] neg_lo:[0,0,1]
	v_pk_add_f32 v[4:5], v[2:3], v[50:51]
	v_add_u32_e32 v6, s18, v53
	ds_write_b64 v6, v[4:5]
	v_pk_add_f32 v[2:3], v[2:3], v[50:51] neg_lo:[0,1] neg_hi:[0,1]
	v_lshl_add_u32 v4, v8, 3, s18
	ds_write_b64 v4, v[2:3]
	v_add_u32_e32 v2, 0x400, v52
	v_ashrrev_i32_e32 v3, 31, v2
	v_add_u32_sdwa v3, v2, v3 dst_sel:DWORD dst_unused:UNUSED_PAD src0_sel:DWORD src1_sel:BYTE_3
	v_ashrrev_i32_e32 v3, 8, v3
	v_mul_i32_i24_e32 v4, 0x100, v3
	v_sub_u32_e32 v2, v2, v4
	v_mul_i32_i24_e32 v8, 0x220, v3
	v_ashrrev_i32_e32 v3, 4, v2
	v_add_u32_e32 v46, 0x100, v2
	v_add_u32_e32 v3, v3, v2
	v_lshrrev_b32_e32 v48, 4, v46
	v_add_lshl_u32 v50, v3, v8, 3
	v_add3_u32 v4, v8, v2, v48
	v_add_u32_e32 v3, 0, v50
	v_lshl_add_u32 v4, v4, 3, 0
	v_lshl_add_u32 v6, v2, 3, 0
	ds_read_b64 v[2:3], v3 offset:6272
	ds_read_b64 v[4:5], v4 offset:8320
	ds_read_b64 v[6:7], v6 offset:4224
	v_and_b32_e32 v51, 0xffff0000, v47
	v_add3_u32 v8, v8, v46, v48
	v_mul_f32_e32 v53, v101, v92
	v_fmac_f32_e32 v53, v102, v1
	s_waitcnt lgkmcnt(0)
	v_pk_mul_f32 v[46:47], v[4:5], v[6:7] op_sel:[1,1] op_sel_hi:[1,0]
	v_fmac_f32_e32 v53, v100, v54
	v_pk_fma_f32 v[48:49], v[4:5], v[6:7], v[46:47] op_sel_hi:[0,1,1] neg_lo:[0,0,1]
	v_pk_add_f32 v[4:5], v[2:3], v[48:49]
	v_add_u32_e32 v6, s18, v50
	ds_write_b64 v6, v[4:5]
	v_pk_add_f32 v[2:3], v[2:3], v[48:49] neg_lo:[0,1] neg_hi:[0,1]
	v_lshl_add_u32 v4, v8, 3, s18
	ds_write_b64 v4, v[2:3]
	v_add_u32_e32 v2, 0x600, v52
	v_ashrrev_i32_e32 v3, 31, v2
	v_add_u32_sdwa v3, v2, v3 dst_sel:DWORD dst_unused:UNUSED_PAD src0_sel:DWORD src1_sel:BYTE_3
	v_ashrrev_i32_e32 v3, 8, v3
	v_mul_i32_i24_e32 v4, 0x100, v3
	v_sub_u32_e32 v2, v2, v4
	v_mul_i32_i24_e32 v8, 0x220, v3
	v_ashrrev_i32_e32 v3, 4, v2
	v_add_u32_e32 v46, 0x100, v2
	v_add_u32_e32 v3, v3, v2
	v_lshrrev_b32_e32 v47, 4, v46
	v_add_lshl_u32 v50, v3, v8, 3
	v_add3_u32 v4, v8, v2, v47
	v_add_u32_e32 v3, 0, v50
	v_lshl_add_u32 v4, v4, 3, 0
	v_lshl_add_u32 v6, v2, 3, 0
	ds_read_b64 v[2:3], v3 offset:6272
	ds_read_b64 v[4:5], v4 offset:8320
	ds_read_b64 v[6:7], v6 offset:4224
	v_add3_u32 v8, v8, v46, v47
	v_add_f32_e32 v94, v98, v53
	v_mul_f32_e32 v53, v102, v54
	v_fmac_f32_e32 v53, v101, v1
	s_waitcnt lgkmcnt(0)
	v_pk_mul_f32 v[46:47], v[4:5], v[6:7] op_sel:[1,1] op_sel_hi:[1,0]
	v_fmac_f32_e32 v53, v100, v55
	v_pk_fma_f32 v[48:49], v[4:5], v[6:7], v[46:47] op_sel_hi:[0,1,1] neg_lo:[0,0,1]
	v_pk_add_f32 v[4:5], v[2:3], v[48:49]
	v_add_u32_e32 v6, s18, v50
	ds_write_b64 v6, v[4:5]
	v_pk_add_f32 v[2:3], v[2:3], v[48:49] neg_lo:[0,1] neg_hi:[0,1]
	v_lshl_add_u32 v4, v8, 3, s18
	ds_write_b64 v4, v[2:3]
	v_add_u32_e32 v2, 0x800, v52
	v_ashrrev_i32_e32 v3, 31, v2
	v_add_u32_sdwa v3, v2, v3 dst_sel:DWORD dst_unused:UNUSED_PAD src0_sel:DWORD src1_sel:BYTE_3
	v_ashrrev_i32_e32 v3, 8, v3
	v_mul_i32_i24_e32 v4, 0x100, v3
	v_sub_u32_e32 v2, v2, v4
	v_mul_i32_i24_e32 v8, 0x220, v3
	v_ashrrev_i32_e32 v3, 4, v2
	v_add_u32_e32 v46, 0x100, v2
	v_add_u32_e32 v3, v3, v2
	v_lshrrev_b32_e32 v47, 4, v46
	v_add_lshl_u32 v50, v3, v8, 3
	v_add3_u32 v4, v8, v2, v47
	v_add_u32_e32 v3, 0, v50
	v_lshl_add_u32 v4, v4, 3, 0
	v_lshl_add_u32 v6, v2, 3, 0
	ds_read_b64 v[2:3], v3 offset:6272
	ds_read_b64 v[4:5], v4 offset:8320
	ds_read_b64 v[6:7], v6 offset:4224
	v_add3_u32 v1, v8, v46, v47
	v_lshl_add_u32 v1, v1, 3, s18
	v_add_f32_e32 v96, v98, v53
	v_mul_lo_u32 v196, v132, s17
	s_waitcnt lgkmcnt(0)
	v_pk_mul_f32 v[46:47], v[4:5], v[6:7] op_sel:[1,1] op_sel_hi:[1,0]
	v_lshrrev_b32_e32 v0, 1, v0
	v_pk_fma_f32 v[48:49], v[4:5], v[6:7], v[46:47] op_sel_hi:[0,1,1] neg_lo:[0,0,1]
	v_pk_add_f32 v[4:5], v[2:3], v[48:49]
	v_add_u32_e32 v6, s18, v50
	v_pk_add_f32 v[2:3], v[2:3], v[48:49] neg_lo:[0,1] neg_hi:[0,1]
	ds_write_b64 v6, v[4:5]
	ds_write_b64 v1, v[2:3]
	v_add_u32_e32 v1, 0xa00, v52
	v_ashrrev_i32_e32 v2, 31, v1
	v_add_u32_sdwa v2, v1, v2 dst_sel:DWORD dst_unused:UNUSED_PAD src0_sel:DWORD src1_sel:BYTE_3
	v_ashrrev_i32_e32 v2, 8, v2
	v_mul_i32_i24_e32 v3, 0x100, v2
	v_sub_u32_e32 v1, v1, v3
	v_mul_i32_i24_e32 v8, 0x220, v2
	v_ashrrev_i32_e32 v2, 4, v1
	v_add_u32_e32 v46, 0x100, v1
	v_add_u32_e32 v2, v2, v1
	v_lshrrev_b32_e32 v47, 4, v46
	v_add_lshl_u32 v50, v2, v8, 3
	v_add3_u32 v3, v8, v1, v47
	v_add_u32_e32 v2, 0, v50
	v_lshl_add_u32 v4, v3, 3, 0
	v_lshl_add_u32 v1, v1, 3, 0
	ds_read_b64 v[2:3], v2 offset:6272
	ds_read_b64 v[4:5], v4 offset:8320
	ds_read_b64 v[6:7], v1 offset:4224
	v_add3_u32 v8, v8, v46, v47
	v_mul_f32_e32 v1, v102, v55
	v_fmac_f32_e32 v1, v101, v54
	v_fmac_f32_e32 v1, v100, v51
	s_waitcnt lgkmcnt(0)
	v_pk_mul_f32 v[46:47], v[4:5], v[6:7] op_sel:[1,1] op_sel_hi:[1,0]
	v_add_f32_e32 v92, v98, v1
	v_pk_fma_f32 v[48:49], v[4:5], v[6:7], v[46:47] op_sel_hi:[0,1,1] neg_lo:[0,0,1]
	v_pk_add_f32 v[4:5], v[2:3], v[48:49]
	v_add_u32_e32 v6, s18, v50
	ds_write_b64 v6, v[4:5]
	v_pk_add_f32 v[2:3], v[2:3], v[48:49] neg_lo:[0,1] neg_hi:[0,1]
	v_lshl_add_u32 v4, v8, 3, s18
	ds_write_b64 v4, v[2:3]
	v_add_u32_e32 v2, 0xc00, v52
	v_ashrrev_i32_e32 v3, 31, v2
	v_add_u32_sdwa v3, v2, v3 dst_sel:DWORD dst_unused:UNUSED_PAD src0_sel:DWORD src1_sel:BYTE_3
	v_ashrrev_i32_e32 v3, 8, v3
	v_mul_i32_i24_e32 v4, 0x100, v3
	v_sub_u32_e32 v2, v2, v4
	v_mul_i32_i24_e32 v8, 0x220, v3
	v_ashrrev_i32_e32 v3, 4, v2
	v_add_u32_e32 v46, 0x100, v2
	v_add_u32_e32 v3, v3, v2
	v_lshrrev_b32_e32 v47, 4, v46
	v_add_lshl_u32 v50, v3, v8, 3
	v_add3_u32 v4, v8, v2, v47
	v_add_u32_e32 v3, 0, v50
	v_lshl_add_u32 v4, v4, 3, 0
	v_lshl_add_u32 v6, v2, 3, 0
	ds_read_b64 v[2:3], v3 offset:6272
	ds_read_b64 v[4:5], v4 offset:8320
	ds_read_b64 v[6:7], v6 offset:4224
	v_add3_u32 v8, v8, v46, v47
	v_mul_f32_e32 v1, v102, v51
	v_fmac_f32_e32 v1, v101, v55
	v_fmac_f32_e32 v1, v100, v103
	s_waitcnt lgkmcnt(0)
	v_pk_mul_f32 v[46:47], v[4:5], v[6:7] op_sel:[1,1] op_sel_hi:[1,0]
	v_add_f32_e32 v98, v98, v1
	v_pk_fma_f32 v[48:49], v[4:5], v[6:7], v[46:47] op_sel_hi:[0,1,1] neg_lo:[0,0,1]
	v_pk_add_f32 v[4:5], v[2:3], v[48:49]
	v_add_u32_e32 v6, s18, v50
	ds_write_b64 v6, v[4:5]
	v_pk_add_f32 v[2:3], v[2:3], v[48:49] neg_lo:[0,1] neg_hi:[0,1]
	v_lshl_add_u32 v4, v8, 3, s18
	ds_write_b64 v4, v[2:3]
	v_add_u32_e32 v2, 0xe00, v52
	v_ashrrev_i32_e32 v3, 31, v2
	v_add_u32_sdwa v3, v2, v3 dst_sel:DWORD dst_unused:UNUSED_PAD src0_sel:DWORD src1_sel:BYTE_3
	v_ashrrev_i32_e32 v3, 8, v3
	v_mul_i32_i24_e32 v4, 0x100, v3
	v_sub_u32_e32 v2, v2, v4
	v_mul_i32_i24_e32 v8, 0x220, v3
	v_ashrrev_i32_e32 v3, 4, v2
	v_add_u32_e32 v46, 0x100, v2
	v_add_u32_e32 v3, v3, v2
	v_lshrrev_b32_e32 v47, 4, v46
	v_add_lshl_u32 v50, v3, v8, 3
	v_add3_u32 v4, v8, v2, v47
	v_add_u32_e32 v3, 0, v50
	v_lshl_add_u32 v4, v4, 3, 0
	v_lshl_add_u32 v6, v2, 3, 0
	ds_read_b64 v[2:3], v3 offset:6272
	ds_read_b64 v[4:5], v4 offset:8320
	ds_read_b64 v[6:7], v6 offset:4224
	v_add3_u32 v8, v8, v46, v47
	v_mov_b32_e32 v1, s18
	v_and_b32_e32 v0, 0x7ffffff8, v0
	s_waitcnt lgkmcnt(0)
	v_pk_mul_f32 v[46:47], v[4:5], v[6:7] op_sel:[1,1] op_sel_hi:[1,0]
	s_nop 0
	v_pk_fma_f32 v[48:49], v[4:5], v[6:7], v[46:47] op_sel_hi:[0,1,1] neg_lo:[0,0,1]
	v_pk_add_f32 v[4:5], v[2:3], v[48:49]
	v_add_u32_e32 v6, s18, v50
	ds_write_b64 v6, v[4:5]
	v_pk_add_f32 v[2:3], v[2:3], v[48:49] neg_lo:[0,1] neg_hi:[0,1]
	v_lshl_add_u32 v4, v8, 3, s18
	ds_write_b64 v4, v[2:3]
	v_lshrrev_b32_e32 v2, 27, v45
	v_add_u32_e32 v2, v44, v2
	v_and_b32_e32 v2, 0xffffffe0, v2
	v_lshrrev_b32_e32 v3, 5, v44
	v_sub_u32_e32 v2, v44, v2
	v_and_b32_e32 v3, 0xfffff8, v3
	v_mad_u32_u24 v1, v3, s17, v1
	v_ashrrev_i32_e32 v3, 4, v2
	v_add_u32_e32 v4, 32, v2
	v_add_u32_e32 v3, v3, v2
	v_lshrrev_b32_e32 v4, 4, v4
	v_lshl_add_u32 v3, v3, 3, v1
	v_add_u32_e32 v4, v4, v2
	s_waitcnt lgkmcnt(0)
	s_barrier
	v_lshl_add_u32 v4, v4, 3, v1
	ds_read_b64 v[100:101], v3
	ds_read_b64 v[44:45], v3 offset:4352
	ds_read_b64 v[102:103], v4 offset:256
	ds_read_b64 v[46:47], v4 offset:4608
	v_add_u32_e32 v3, 64, v2
	v_lshrrev_b32_e32 v3, 4, v3
	v_add_u32_e32 v4, 0x60, v2
	v_add_u32_e32 v3, v3, v2
	v_lshrrev_b32_e32 v4, 4, v4
	v_lshl_add_u32 v3, v3, 3, v1
	v_add_u32_e32 v4, v4, v2
	v_lshl_add_u32 v4, v4, 3, v1
	ds_read_b64 v[104:105], v3 offset:512
	ds_read_b64 v[48:49], v3 offset:4864
	ds_read_b64 v[106:107], v4 offset:768
	ds_read_b64 v[50:51], v4 offset:5120
	v_add_u32_e32 v3, 0x80, v2
	v_lshrrev_b32_e32 v3, 4, v3
	v_add_u32_e32 v4, 0xa0, v2
	v_add_u32_e32 v3, v3, v2
	v_lshrrev_b32_e32 v4, 4, v4
	v_lshl_add_u32 v3, v3, 3, v1
	v_add_u32_e32 v4, v4, v2
	v_lshl_add_u32 v4, v4, 3, v1
	ds_read_b64 v[108:109], v3 offset:1024
	ds_read_b64 v[52:53], v3 offset:5376
	ds_read_b64 v[110:111], v4 offset:1280
	ds_read_b64 v[54:55], v4 offset:5632
	v_add_u32_e32 v3, 0xc0, v2
	v_lshrrev_b32_e32 v3, 4, v3
	v_add_u32_e32 v4, 0xe0, v2
	v_add_u32_e32 v3, v3, v2
	v_lshrrev_b32_e32 v4, 4, v4
	v_lshl_add_u32 v3, v3, 3, v1
	v_add_u32_e32 v4, v4, v2
	v_lshl_add_u32 v4, v4, 3, v1
	ds_read_b64 v[112:113], v3 offset:1536
	ds_read_b64 v[56:57], v3 offset:5888
	ds_read_b64 v[114:115], v4 offset:1792
	ds_read_b64 v[58:59], v4 offset:6144
	v_add_u32_e32 v3, 0x100, v2
	v_lshrrev_b32_e32 v3, 4, v3
	v_add_u32_e32 v4, 0x120, v2
	v_add_u32_e32 v3, v3, v2
	v_lshrrev_b32_e32 v4, 4, v4
	v_lshl_add_u32 v3, v3, 3, v1
	v_add_u32_e32 v4, v4, v2
	v_lshl_add_u32 v4, v4, 3, v1
	ds_read_b64 v[116:117], v3 offset:2048
	ds_read_b64 v[60:61], v3 offset:6400
	ds_read_b64 v[118:119], v4 offset:2304
	ds_read_b64 v[62:63], v4 offset:6656
	v_add_u32_e32 v3, 0x140, v2
	v_lshrrev_b32_e32 v3, 4, v3
	v_add_u32_e32 v4, 0x160, v2
	v_add_u32_e32 v3, v3, v2
	v_lshrrev_b32_e32 v4, 4, v4
	v_lshl_add_u32 v3, v3, 3, v1
	v_add_u32_e32 v4, v4, v2
	v_lshl_add_u32 v4, v4, 3, v1
	ds_read_b64 v[120:121], v3 offset:2560
	ds_read_b64 v[64:65], v3 offset:6912
	ds_read_b64 v[122:123], v4 offset:2816
	ds_read_b64 v[66:67], v4 offset:7168
	v_add_u32_e32 v3, 0x180, v2
	v_lshrrev_b32_e32 v3, 4, v3
	v_add_u32_e32 v4, 0x1a0, v2
	v_add_u32_e32 v3, v3, v2
	v_lshrrev_b32_e32 v4, 4, v4
	v_lshl_add_u32 v3, v3, 3, v1
	v_add_u32_e32 v4, v4, v2
	v_lshl_add_u32 v4, v4, 3, v1
	ds_read_b64 v[124:125], v3 offset:3072
	ds_read_b64 v[70:71], v3 offset:7424
	ds_read_b64 v[126:127], v4 offset:3328
	ds_read_b64 v[72:73], v4 offset:7680
	v_add_u32_e32 v3, 0x1c0, v2
	v_lshrrev_b32_e32 v3, 4, v3
	v_add_u32_e32 v4, 0x1e0, v2
	v_add_u32_e32 v3, v3, v2
	v_lshrrev_b32_e32 v4, 4, v4
	v_lshl_add_u32 v3, v3, 3, v1
	v_add_u32_e32 v2, v4, v2
	v_lshl_add_u32 v1, v2, 3, v1
	ds_read_b64 v[128:129], v3 offset:3584
	ds_read_b64 v[74:75], v3 offset:7936
	ds_read_b64 v[130:131], v1 offset:3840
	ds_read_b64 v[76:77], v1 offset:8192
	v_add_u32_e32 v1, 0, v196
	v_lshlrev_b32_e32 v2, 3, v18
	v_lshl_add_u32 v8, v197, 3, v1
	v_add3_u32 v195, v1, v2, v0
	v_mov_b32_e32 v0, v180
	s_waitcnt lgkmcnt(0)
	s_barrier
	ds_write_b64 v8, v[94:95] offset:6272
	ds_write_b64 v195, v[202:203] offset:8320
	ds_write_b64 v8, v[96:97] offset:6280
	ds_write_b64 v195, v[202:203] offset:8328
	ds_write_b64 v8, v[92:93] offset:6288
	ds_write_b64 v195, v[202:203] offset:8336
	ds_write_b64 v8, v[98:99] offset:6296
	ds_write_b64 v195, v[202:203] offset:8344
	ds_write_b64 v8, v[88:89] offset:41088
	ds_write_b64 v195, v[202:203] offset:43136
	ds_write_b64 v8, v[90:91] offset:41096
	ds_write_b64 v195, v[202:203] offset:43144
	ds_write_b64 v8, v[84:85] offset:41104
	ds_write_b64 v195, v[202:203] offset:43152
	ds_write_b64 v8, v[86:87] offset:41112
	ds_write_b64 v195, v[202:203] offset:43160
	s_waitcnt lgkmcnt(0)
	s_barrier
	s_nop 0
	v_cmp_gt_i32_e32 vcc, s16, v0
	s_and_saveexec_b64 s[2:3], vcc
	s_cbranch_execz .LBB0_491
	v_ashrrev_i32_e32 v1, 31, v0
	v_lshrrev_b32_e32 v1, 27, v1
	v_add_u32_e32 v1, v0, v1
	v_lshrrev_b32_e32 v2, 5, v1
	v_and_b32_e32 v1, 0xffffffe0, v1
	v_sub_u32_e32 v181, v0, v1
	v_mul_lo_u32 v206, v2, s17
	v_ashrrev_i32_e32 v1, 4, v181
	v_add_u32_e32 v0, 0, v206
	v_lshlrev_b32_e32 v207, 3, v181
	v_lshlrev_b32_e32 v1, 3, v1
	v_add3_u32 v152, v0, v207, v1
	v_add_u32_e32 v136, 0x1800, v152
	v_add_u32_e32 v148, 0x2000, v152
	ds_read2_b64 v[0:3], v136 offset0:16 offset1:50
	ds_read2_b64 v[4:7], v136 offset0:84 offset1:118
	ds_read2_b64 v[132:135], v136 offset0:152 offset1:186
	ds_read2_b64 v[136:139], v136 offset0:220 offset1:254
	ds_read2_b64 v[140:143], v148 offset0:32 offset1:66
	ds_read2_b64 v[144:147], v148 offset0:100 offset1:134
	ds_read2_b64 v[148:151], v148 offset0:168 offset1:202
	v_add_u32_e32 v152, 0x2400, v152
	ds_read2_b64 v[152:155], v152 offset0:108 offset1:142
	s_waitcnt lgkmcnt(3)
	v_pk_add_f32 v[156:157], v[0:1], v[140:141]
	v_pk_add_f32 v[0:1], v[0:1], v[140:141] neg_lo:[0,1] neg_hi:[0,1]
	s_waitcnt lgkmcnt(1)
	v_pk_add_f32 v[140:141], v[132:133], v[148:149]
	v_pk_add_f32 v[132:133], v[132:133], v[148:149] neg_lo:[0,1] neg_hi:[0,1]
	s_mov_b32 s31, s28
	v_xor_b32_e32 v149, 0x80000000, v132
	v_mov_b32_e32 v148, v133
	v_pk_add_f32 v[198:199], v[0:1], v[148:149]
	v_pk_add_f32 v[0:1], v[0:1], v[148:149] neg_lo:[0,1] neg_hi:[0,1]
	v_pk_add_f32 v[148:149], v[2:3], v[142:143]
	v_pk_add_f32 v[2:3], v[2:3], v[142:143] neg_lo:[0,1] neg_hi:[0,1]
	v_pk_add_f32 v[142:143], v[134:135], v[150:151]
	v_pk_add_f32 v[134:135], v[134:135], v[150:151] neg_lo:[0,1] neg_hi:[0,1]
	v_pk_add_f32 v[132:133], v[156:157], v[140:141]
	v_xor_b32_e32 v151, 0x80000000, v134
	v_mov_b32_e32 v150, v135
	v_pk_add_f32 v[134:135], v[148:149], v[142:143]
	v_pk_add_f32 v[142:143], v[148:149], v[142:143] neg_lo:[0,1] neg_hi:[0,1]
	v_pk_add_f32 v[148:149], v[4:5], v[144:145]
	v_pk_add_f32 v[4:5], v[4:5], v[144:145] neg_lo:[0,1] neg_hi:[0,1]
	s_waitcnt lgkmcnt(0)
	v_pk_add_f32 v[144:145], v[136:137], v[152:153]
	v_pk_add_f32 v[136:137], v[136:137], v[152:153] neg_lo:[0,1] neg_hi:[0,1]
	v_pk_add_f32 v[140:141], v[156:157], v[140:141] neg_lo:[0,1] neg_hi:[0,1]
	v_pk_add_f32 v[156:157], v[2:3], v[150:151]
	v_pk_add_f32 v[2:3], v[2:3], v[150:151] neg_lo:[0,1] neg_hi:[0,1]
	v_xor_b32_e32 v151, 0x80000000, v136
	v_mov_b32_e32 v150, v137
	v_pk_add_f32 v[136:137], v[148:149], v[144:145]
	v_pk_add_f32 v[144:145], v[148:149], v[144:145] neg_lo:[0,1] neg_hi:[0,1]
	v_pk_add_f32 v[148:149], v[6:7], v[146:147]
	v_pk_add_f32 v[6:7], v[6:7], v[146:147] neg_lo:[0,1] neg_hi:[0,1]
	v_pk_add_f32 v[146:147], v[138:139], v[154:155]
	v_pk_add_f32 v[138:139], v[138:139], v[154:155] neg_lo:[0,1] neg_hi:[0,1]
	v_pk_add_f32 v[152:153], v[4:5], v[150:151]
	v_pk_add_f32 v[4:5], v[4:5], v[150:151] neg_lo:[0,1] neg_hi:[0,1]
	v_xor_b32_e32 v151, 0x80000000, v138
	v_mov_b32_e32 v150, v139
	v_pk_add_f32 v[138:139], v[148:149], v[146:147]
	v_pk_add_f32 v[146:147], v[148:149], v[146:147] neg_lo:[0,1] neg_hi:[0,1]
	v_pk_mul_f32 v[148:149], v[156:157], s[14:15] op_sel_hi:[1,0]
	v_pk_add_f32 v[154:155], v[6:7], v[150:151]
	v_pk_add_f32 v[6:7], v[6:7], v[150:151] neg_lo:[0,1] neg_hi:[0,1]
	v_pk_fma_f32 v[150:151], v[156:157], s[22:23], v[148:149] op_sel:[0,0,1] op_sel_hi:[1,0,0] neg_hi:[0,0,1]
	s_mov_b32 s29, s14
	v_pk_mul_f32 v[148:149], v[142:143], s[24:25] op_sel_hi:[1,0]
	s_nop 0
	v_pk_fma_f32 v[156:157], v[142:143], s[24:25], v[148:149] op_sel:[0,0,1] op_sel_hi:[1,0,0] neg_hi:[0,0,1]
	v_pk_mul_f32 v[148:149], v[2:3], s[22:23] op_sel_hi:[1,0]
	v_pk_fma_f32 v[200:201], v[2:3], s[14:15], v[148:149] op_sel:[0,0,1] op_sel_hi:[1,0,0] neg_hi:[0,0,1]
	s_nop 0
	v_pk_mul_f32 v[2:3], v[152:153], s[24:25] op_sel_hi:[1,0]
	s_nop 0
	v_pk_fma_f32 v[148:149], v[152:153], s[24:25], v[2:3] op_sel:[0,0,1] op_sel_hi:[1,0,0] neg_hi:[0,0,1]
	s_nop 0
	v_pk_fma_f32 v[2:3], v[144:145], 0, v[144:145] op_sel:[0,0,1] op_sel_hi:[1,0,0] neg_hi:[0,0,1]
	s_nop 0
	v_pk_mul_f32 v[144:145], v[4:5], s[26:27] op_sel_hi:[1,0]
	s_nop 0
	v_pk_fma_f32 v[152:153], v[4:5], s[26:27], v[144:145] op_sel:[0,0,1] op_sel_hi:[1,0,0] neg_lo:[0,0,1]
	v_pk_mul_f32 v[144:145], v[154:155], s[22:23] op_sel_hi:[1,0]
	v_pk_fma_f32 v[204:205], v[154:155], s[14:15], v[144:145] op_sel:[0,0,1] op_sel_hi:[1,0,0] neg_hi:[0,0,1]
	v_pk_add_f32 v[4:5], v[0:1], v[152:153]
	v_pk_mul_f32 v[144:145], v[146:147], s[26:27] op_sel_hi:[1,0]
	v_pk_add_f32 v[0:1], v[0:1], v[152:153] neg_lo:[0,1] neg_hi:[0,1]
	v_pk_fma_f32 v[154:155], v[146:147], s[26:27], v[144:145] op_sel:[0,0,1] op_sel_hi:[1,0,0] neg_lo:[0,0,1]
	s_nop 0
	v_pk_mul_f32 v[144:145], v[6:7], s[30:31] op_sel:[1,0]
	v_pk_add_f32 v[142:143], v[156:157], v[154:155] neg_lo:[0,1] neg_hi:[0,1]
	v_pk_fma_f32 v[6:7], v[6:7], s[28:29], v[144:145] op_sel_hi:[0,1,1]
	v_pk_add_f32 v[144:145], v[132:133], v[136:137]
	v_pk_add_f32 v[132:133], v[132:133], v[136:137] neg_lo:[0,1] neg_hi:[0,1]
	v_pk_add_f32 v[136:137], v[134:135], v[138:139]
	v_pk_add_f32 v[134:135], v[134:135], v[138:139] neg_lo:[0,1] neg_hi:[0,1]
	s_nop 0
	v_xor_b32_e32 v139, 0x80000000, v134
	v_mov_b32_e32 v138, v135
	v_pk_add_f32 v[134:135], v[144:145], v[136:137]
	v_pk_add_f32 v[146:147], v[132:133], v[138:139]
	v_pk_add_f32 v[136:137], v[144:145], v[136:137] neg_lo:[0,1] neg_hi:[0,1]
	v_pk_add_f32 v[132:133], v[132:133], v[138:139] neg_lo:[0,1] neg_hi:[0,1]
	v_pk_add_f32 v[138:139], v[198:199], v[148:149]
	v_pk_add_f32 v[144:145], v[198:199], v[148:149] neg_lo:[0,1] neg_hi:[0,1]
	v_pk_add_f32 v[148:149], v[150:151], v[204:205]
	v_pk_add_f32 v[150:151], v[150:151], v[204:205] neg_lo:[0,1] neg_hi:[0,1]
	s_nop 0
	v_xor_b32_e32 v199, 0x80000000, v150
	v_mov_b32_e32 v198, v151
	v_pk_add_f32 v[150:151], v[138:139], v[148:149]
	v_pk_add_f32 v[138:139], v[138:139], v[148:149] neg_lo:[0,1] neg_hi:[0,1]
	v_pk_add_f32 v[148:149], v[140:141], v[2:3]
	v_pk_add_f32 v[2:3], v[140:141], v[2:3] neg_lo:[0,1] neg_hi:[0,1]
	v_pk_add_f32 v[140:141], v[156:157], v[154:155]
	v_xor_b32_e32 v155, 0x80000000, v142
	v_mov_b32_e32 v154, v143
	v_pk_add_f32 v[142:143], v[148:149], v[140:141]
	v_pk_add_f32 v[140:141], v[148:149], v[140:141] neg_lo:[0,1] neg_hi:[0,1]
	v_pk_add_f32 v[148:149], v[200:201], v[6:7]
	v_pk_add_f32 v[6:7], v[200:201], v[6:7] neg_lo:[0,1] neg_hi:[0,1]
	v_pk_add_f32 v[204:205], v[144:145], v[198:199]
	v_xor_b32_e32 v153, 0x80000000, v6
	v_mov_b32_e32 v152, v7
	v_pk_add_f32 v[6:7], v[4:5], v[148:149]
	v_pk_add_f32 v[4:5], v[4:5], v[148:149] neg_lo:[0,1] neg_hi:[0,1]
	v_add_u32_e32 v148, s18, v206
	v_lshlrev_b32_e32 v149, 7, v181
	v_add3_u32 v148, v148, v149, v207
	v_pk_add_f32 v[144:145], v[144:145], v[198:199] neg_lo:[0,1] neg_hi:[0,1]
	v_pk_add_f32 v[156:157], v[2:3], v[154:155]
	v_pk_add_f32 v[2:3], v[2:3], v[154:155] neg_lo:[0,1] neg_hi:[0,1]
	v_pk_add_f32 v[154:155], v[0:1], v[152:153]
	v_pk_add_f32 v[0:1], v[0:1], v[152:153] neg_lo:[0,1] neg_hi:[0,1]
	ds_write2_b64 v148, v[134:135], v[150:151] offset1:1
	ds_write2_b64 v148, v[142:143], v[6:7] offset0:2 offset1:3
	ds_write2_b64 v148, v[146:147], v[204:205] offset0:4 offset1:5
	ds_write2_b64 v148, v[156:157], v[154:155] offset0:6 offset1:7
	ds_write2_b64 v148, v[136:137], v[138:139] offset0:8 offset1:9
	ds_write2_b64 v148, v[140:141], v[4:5] offset0:10 offset1:11
	ds_write2_b64 v148, v[132:133], v[144:145] offset0:12 offset1:13
	ds_write2_b64 v148, v[2:3], v[0:1] offset0:14 offset1:15
.LBB0_491:
	s_or_b64 exec, exec, s[2:3]
	v_mov_b32_e32 v0, v180
	s_waitcnt lgkmcnt(0)
	s_barrier
	s_nop 0
	v_cmp_gt_i32_e32 vcc, s16, v0
	s_and_saveexec_b64 s[2:3], vcc
	s_cbranch_execz .LBB0_493
	v_ashrrev_i32_e32 v1, 31, v0
	v_lshrrev_b32_e32 v1, 27, v1
	v_add_u32_e32 v1, v0, v1
	v_lshrrev_b32_e32 v2, 5, v1
	v_and_b32_e32 v1, 0xffffffe0, v1
	v_sub_u32_e32 v0, v0, v1
	v_lshrrev_b16_sdwa v1, v175, sext(v0) dst_sel:DWORD dst_unused:UNUSED_PAD src0_sel:DWORD src1_sel:BYTE_0
	v_and_b32_e32 v1, 15, v1
	v_add_u16_e32 v1, v0, v1
	v_ashrrev_i16_sdwa v198, v176, sext(v1) dst_sel:DWORD dst_unused:UNUSED_PAD src0_sel:DWORD src1_sel:BYTE_0
	v_and_b32_e32 v1, 0xf0, v1
	v_sub_u16_e32 v132, v0, v1
	v_mul_lo_u32 v199, v2, s17
	v_lshlrev_b32_e32 v2, 3, v0
	v_ashrrev_i32_e32 v0, 4, v0
	v_add_u32_e32 v1, s18, v199
	v_lshlrev_b32_e32 v0, 3, v0
	v_bfe_i32 v200, v132, 0, 8
	v_add3_u32 v4, v1, v2, v0
	v_mad_i32_i24 v181, v200, s19, 0
	ds_read2_b64 v[0:3], v4 offset1:34
	ds_read2_b64 v[136:139], v4 offset0:68 offset1:102
	ds_read2_b64 v[144:147], v4 offset0:136 offset1:170
	ds_read2_b64 v[148:151], v4 offset0:204 offset1:238
	v_add_u32_e32 v4, 0x800, v4
	v_add_u32_e32 v132, 0x808, v181
	ds_read2_b64 v[152:155], v4 offset0:16 offset1:50
	ds_read2_b64 v[204:207], v4 offset0:84 offset1:118
	ds_read2_b64 v[208:211], v4 offset0:152 offset1:186
	ds_read2_b64 v[4:7], v4 offset0:220 offset1:254
	ds_read2_b64 v[140:143], v132 offset1:1
	s_mov_b32 s31, s28
	s_mov_b32 s29, s14
	s_waitcnt lgkmcnt(0)
	v_pk_mul_f32 v[132:133], v[2:3], v[140:141] op_sel:[1,1] op_sel_hi:[1,0]
	s_nop 0
	v_pk_fma_f32 v[134:135], v[2:3], v[140:141], v[132:133] op_sel_hi:[0,1,1] neg_lo:[0,0,1]
	v_pk_mul_f32 v[2:3], v[136:137], v[142:143] op_sel:[1,1] op_sel_hi:[1,0]
	s_nop 0
	v_pk_fma_f32 v[132:133], v[136:137], v[142:143], v[2:3] op_sel_hi:[0,1,1] neg_lo:[0,0,1]
	v_add_u32_e32 v2, 0x818, v181
	ds_read2_b64 v[212:215], v2 offset1:1
	s_waitcnt lgkmcnt(0)
	v_pk_mul_f32 v[136:137], v[138:139], v[212:213] op_sel:[1,1] op_sel_hi:[1,0]
	s_nop 0
	v_pk_fma_f32 v[2:3], v[138:139], v[212:213], v[136:137] op_sel_hi:[0,1,1] neg_lo:[0,0,1]
	v_pk_mul_f32 v[136:137], v[144:145], v[214:215] op_sel:[1,1] op_sel_hi:[1,0]
	s_nop 0
	v_pk_fma_f32 v[142:143], v[144:145], v[214:215], v[136:137] op_sel_hi:[0,1,1] neg_lo:[0,0,1]
	v_add_u32_e32 v136, 0x828, v181
	ds_read2_b64 v[212:215], v136 offset1:1
	s_waitcnt lgkmcnt(0)
	v_pk_mul_f32 v[136:137], v[146:147], v[212:213] op_sel:[1,1] op_sel_hi:[1,0]
	s_nop 0
	v_pk_fma_f32 v[140:141], v[146:147], v[212:213], v[136:137] op_sel_hi:[0,1,1] neg_lo:[0,0,1]
	v_pk_mul_f32 v[136:137], v[148:149], v[214:215] op_sel:[1,1] op_sel_hi:[1,0]
	s_nop 0
	v_pk_fma_f32 v[138:139], v[148:149], v[214:215], v[136:137] op_sel_hi:[0,1,1] neg_lo:[0,0,1]
	v_add_u32_e32 v136, 0x838, v181
	ds_read2_b64 v[144:147], v136 offset1:1
	s_waitcnt lgkmcnt(0)
	v_pk_mul_f32 v[148:149], v[150:151], v[144:145] op_sel:[1,1] op_sel_hi:[1,0]
	s_nop 0
	v_pk_fma_f32 v[136:137], v[150:151], v[144:145], v[148:149] op_sel_hi:[0,1,1] neg_lo:[0,0,1]
	v_pk_mul_f32 v[144:145], v[152:153], v[146:147] op_sel:[1,1] op_sel_hi:[1,0]
	s_nop 0
	v_pk_fma_f32 v[150:151], v[152:153], v[146:147], v[144:145] op_sel_hi:[0,1,1] neg_lo:[0,0,1]
	v_add_u32_e32 v144, 0x848, v181
	ds_read2_b64 v[212:215], v144 offset1:1
	s_waitcnt lgkmcnt(0)
	v_pk_mul_f32 v[144:145], v[154:155], v[212:213] op_sel:[1,1] op_sel_hi:[1,0]
	s_nop 0
	v_pk_fma_f32 v[148:149], v[154:155], v[212:213], v[144:145] op_sel_hi:[0,1,1] neg_lo:[0,0,1]
	v_pk_mul_f32 v[144:145], v[204:205], v[214:215] op_sel:[1,1] op_sel_hi:[1,0]
	s_nop 0
	v_pk_fma_f32 v[146:147], v[204:205], v[214:215], v[144:145] op_sel_hi:[0,1,1] neg_lo:[0,0,1]
	v_add_u32_e32 v144, 0x858, v181
	ds_read2_b64 v[152:155], v144 offset1:1
	s_waitcnt lgkmcnt(0)
	v_pk_mul_f32 v[156:157], v[206:207], v[152:153] op_sel:[1,1] op_sel_hi:[1,0]
	s_nop 0
	v_pk_fma_f32 v[144:145], v[206:207], v[152:153], v[156:157] op_sel_hi:[0,1,1] neg_lo:[0,0,1]
	v_pk_mul_f32 v[152:153], v[208:209], v[154:155] op_sel:[1,1] op_sel_hi:[1,0]
	s_nop 0
	v_pk_fma_f32 v[156:157], v[208:209], v[154:155], v[152:153] op_sel_hi:[0,1,1] neg_lo:[0,0,1]
	v_add_u32_e32 v152, 0x868, v181
	ds_read2_b64 v[204:207], v152 offset1:1
	s_waitcnt lgkmcnt(0)
	v_pk_mul_f32 v[152:153], v[210:211], v[204:205] op_sel:[1,1] op_sel_hi:[1,0]
	s_nop 0
	v_pk_fma_f32 v[154:155], v[210:211], v[204:205], v[152:153] op_sel_hi:[0,1,1] neg_lo:[0,0,1]
	v_pk_mul_f32 v[204:205], v[4:5], v[206:207] op_sel:[1,1] op_sel_hi:[1,0]
	v_pk_fma_f32 v[152:153], v[4:5], v[206:207], v[204:205] op_sel_hi:[0,1,1] neg_lo:[0,0,1]
	ds_read_b64 v[4:5], v181 offset:2168
	s_waitcnt lgkmcnt(0)
	v_pk_mul_f32 v[204:205], v[6:7], v[4:5] op_sel:[1,1] op_sel_hi:[1,0]
	s_nop 0
	v_pk_fma_f32 v[206:207], v[6:7], v[4:5], v[204:205] op_sel_hi:[0,1,1] neg_lo:[0,0,1]
	v_pk_add_f32 v[4:5], v[0:1], v[150:151]
	v_pk_add_f32 v[6:7], v[142:143], v[156:157]
	v_pk_add_f32 v[142:143], v[142:143], v[156:157] neg_lo:[0,1] neg_hi:[0,1]
	v_pk_add_f32 v[0:1], v[0:1], v[150:151] neg_lo:[0,1] neg_hi:[0,1]
	v_xor_b32_e32 v151, 0x80000000, v142
	v_mov_b32_e32 v150, v143
	v_pk_add_f32 v[142:143], v[4:5], v[6:7]
	v_pk_add_f32 v[4:5], v[4:5], v[6:7] neg_lo:[0,1] neg_hi:[0,1]
	v_pk_add_f32 v[6:7], v[134:135], v[148:149]
	v_pk_add_f32 v[134:135], v[134:135], v[148:149] neg_lo:[0,1] neg_hi:[0,1]
	v_pk_add_f32 v[148:149], v[140:141], v[154:155]
	v_pk_add_f32 v[140:141], v[140:141], v[154:155] neg_lo:[0,1] neg_hi:[0,1]
	v_pk_add_f32 v[156:157], v[0:1], v[150:151]
	v_pk_add_f32 v[0:1], v[0:1], v[150:151] neg_lo:[0,1] neg_hi:[0,1]
	v_xor_b32_e32 v151, 0x80000000, v140
	v_mov_b32_e32 v150, v141
	v_pk_add_f32 v[140:141], v[6:7], v[148:149]
	v_pk_add_f32 v[6:7], v[6:7], v[148:149] neg_lo:[0,1] neg_hi:[0,1]
	v_pk_add_f32 v[148:149], v[132:133], v[146:147]
	v_pk_add_f32 v[132:133], v[132:133], v[146:147] neg_lo:[0,1] neg_hi:[0,1]
	v_pk_add_f32 v[146:147], v[138:139], v[152:153]
	v_pk_add_f32 v[138:139], v[138:139], v[152:153] neg_lo:[0,1] neg_hi:[0,1]
	v_pk_add_f32 v[154:155], v[134:135], v[150:151]
	v_pk_add_f32 v[134:135], v[134:135], v[150:151] neg_lo:[0,1] neg_hi:[0,1]
	v_xor_b32_e32 v151, 0x80000000, v138
	v_mov_b32_e32 v150, v139
	v_pk_add_f32 v[138:139], v[148:149], v[146:147]
	v_pk_add_f32 v[146:147], v[148:149], v[146:147] neg_lo:[0,1] neg_hi:[0,1]
	v_pk_add_f32 v[148:149], v[2:3], v[144:145]
	v_pk_add_f32 v[2:3], v[2:3], v[144:145] neg_lo:[0,1] neg_hi:[0,1]
	v_pk_add_f32 v[144:145], v[136:137], v[206:207]
	v_pk_add_f32 v[136:137], v[136:137], v[206:207] neg_lo:[0,1] neg_hi:[0,1]
	v_pk_add_f32 v[152:153], v[132:133], v[150:151]
	v_pk_add_f32 v[132:133], v[132:133], v[150:151] neg_lo:[0,1] neg_hi:[0,1]
	v_xor_b32_e32 v151, 0x80000000, v136
	v_mov_b32_e32 v150, v137
	v_pk_add_f32 v[136:137], v[148:149], v[144:145]
	v_pk_add_f32 v[144:145], v[148:149], v[144:145] neg_lo:[0,1] neg_hi:[0,1]
	v_pk_mul_f32 v[148:149], v[154:155], s[14:15] op_sel_hi:[1,0]
	v_pk_add_f32 v[204:205], v[2:3], v[150:151]
	v_pk_add_f32 v[2:3], v[2:3], v[150:151] neg_lo:[0,1] neg_hi:[0,1]
	v_pk_fma_f32 v[150:151], v[154:155], s[22:23], v[148:149] op_sel:[0,0,1] op_sel_hi:[1,0,0] neg_hi:[0,0,1]
	s_nop 0
	v_pk_mul_f32 v[148:149], v[6:7], s[24:25] op_sel_hi:[1,0]
	s_nop 0
	v_pk_fma_f32 v[154:155], v[6:7], s[24:25], v[148:149] op_sel:[0,0,1] op_sel_hi:[1,0,0] neg_hi:[0,0,1]
	v_pk_mul_f32 v[148:149], v[134:135], s[22:23] op_sel_hi:[1,0]
	v_pk_fma_f32 v[206:207], v[134:135], s[14:15], v[148:149] op_sel:[0,0,1] op_sel_hi:[1,0,0] neg_hi:[0,0,1]
	s_nop 0
	v_pk_mul_f32 v[134:135], v[152:153], s[24:25] op_sel_hi:[1,0]
	s_nop 0
	v_pk_fma_f32 v[148:149], v[152:153], s[24:25], v[134:135] op_sel:[0,0,1] op_sel_hi:[1,0,0] neg_hi:[0,0,1]
	s_nop 0
	v_pk_fma_f32 v[134:135], v[146:147], 0, v[146:147] op_sel:[0,0,1] op_sel_hi:[1,0,0] neg_hi:[0,0,1]
	s_nop 0
	v_pk_mul_f32 v[146:147], v[132:133], s[26:27] op_sel_hi:[1,0]
	s_nop 0
	v_pk_fma_f32 v[152:153], v[132:133], s[26:27], v[146:147] op_sel:[0,0,1] op_sel_hi:[1,0,0] neg_lo:[0,0,1]
	v_pk_mul_f32 v[146:147], v[204:205], s[22:23] op_sel_hi:[1,0]
	v_pk_fma_f32 v[208:209], v[204:205], s[14:15], v[146:147] op_sel:[0,0,1] op_sel_hi:[1,0,0] neg_hi:[0,0,1]
	v_pk_add_f32 v[132:133], v[0:1], v[152:153]
	v_pk_mul_f32 v[146:147], v[144:145], s[26:27] op_sel_hi:[1,0]
	v_pk_add_f32 v[0:1], v[0:1], v[152:153] neg_lo:[0,1] neg_hi:[0,1]
	v_pk_fma_f32 v[204:205], v[144:145], s[26:27], v[146:147] op_sel:[0,0,1] op_sel_hi:[1,0,0] neg_lo:[0,0,1]
	s_nop 0
	v_pk_mul_f32 v[144:145], v[2:3], s[30:31] op_sel:[1,0]
	v_pk_add_f32 v[6:7], v[154:155], v[204:205]
	v_pk_fma_f32 v[2:3], v[2:3], s[28:29], v[144:145] op_sel_hi:[0,1,1]
	v_pk_add_f32 v[144:145], v[142:143], v[138:139]
	v_pk_add_f32 v[138:139], v[142:143], v[138:139] neg_lo:[0,1] neg_hi:[0,1]
	v_pk_add_f32 v[142:143], v[140:141], v[136:137]
	v_pk_add_f32 v[136:137], v[140:141], v[136:137] neg_lo:[0,1] neg_hi:[0,1]
	s_nop 0
	v_xor_b32_e32 v141, 0x80000000, v136
	v_mov_b32_e32 v140, v137
	v_pk_add_f32 v[136:137], v[144:145], v[142:143]
	v_pk_add_f32 v[146:147], v[138:139], v[140:141]
	v_pk_add_f32 v[142:143], v[144:145], v[142:143] neg_lo:[0,1] neg_hi:[0,1]
	v_pk_add_f32 v[138:139], v[138:139], v[140:141] neg_lo:[0,1] neg_hi:[0,1]
	v_pk_add_f32 v[140:141], v[156:157], v[148:149]
	v_pk_add_f32 v[144:145], v[156:157], v[148:149] neg_lo:[0,1] neg_hi:[0,1]
	v_pk_add_f32 v[148:149], v[150:151], v[208:209]
	v_pk_add_f32 v[150:151], v[150:151], v[208:209] neg_lo:[0,1] neg_hi:[0,1]
	s_nop 0
	v_xor_b32_e32 v157, 0x80000000, v150
	v_mov_b32_e32 v156, v151
	v_pk_add_f32 v[150:151], v[140:141], v[148:149]
	v_pk_add_f32 v[140:141], v[140:141], v[148:149] neg_lo:[0,1] neg_hi:[0,1]
	v_pk_add_f32 v[148:149], v[4:5], v[134:135]
	v_pk_add_f32 v[4:5], v[4:5], v[134:135] neg_lo:[0,1] neg_hi:[0,1]
	v_pk_add_f32 v[134:135], v[154:155], v[204:205] neg_lo:[0,1] neg_hi:[0,1]
	v_pk_add_f32 v[208:209], v[144:145], v[156:157]
	v_xor_b32_e32 v155, 0x80000000, v134
	v_mov_b32_e32 v154, v135
	v_pk_add_f32 v[134:135], v[148:149], v[6:7]
	v_pk_add_f32 v[6:7], v[148:149], v[6:7] neg_lo:[0,1] neg_hi:[0,1]
	v_pk_add_f32 v[148:149], v[206:207], v[2:3]
	v_pk_add_f32 v[2:3], v[206:207], v[2:3] neg_lo:[0,1] neg_hi:[0,1]
	v_pk_add_f32 v[144:145], v[144:145], v[156:157] neg_lo:[0,1] neg_hi:[0,1]
	v_xor_b32_e32 v153, 0x80000000, v2
	v_mov_b32_e32 v152, v3
	v_pk_add_f32 v[2:3], v[132:133], v[148:149]
	v_pk_add_f32 v[132:133], v[132:133], v[148:149] neg_lo:[0,1] neg_hi:[0,1]
	v_bfe_i32 v148, v198, 0, 16
	v_lshl_add_u32 v148, v148, 8, v200
	v_pk_add_f32 v[156:157], v[4:5], v[154:155]
	v_pk_add_f32 v[4:5], v[4:5], v[154:155] neg_lo:[0,1] neg_hi:[0,1]
	v_pk_add_f32 v[154:155], v[0:1], v[152:153]
	v_pk_add_f32 v[0:1], v[0:1], v[152:153] neg_lo:[0,1] neg_hi:[0,1]
	v_lshlrev_b32_e32 v152, 3, v148
	v_ashrrev_i32_e32 v148, 4, v148
	v_add_u32_e32 v149, 0, v199
	v_lshlrev_b32_e32 v148, 3, v148
	v_add3_u32 v148, v149, v152, v148
	v_add_u32_e32 v149, 0x1800, v148
	ds_write2_b64 v149, v[136:137], v[150:151] offset0:16 offset1:33
	ds_write2_b64 v149, v[134:135], v[2:3] offset0:50 offset1:67
	ds_write2_b64 v149, v[146:147], v[208:209] offset0:84 offset1:101
	ds_write2_b64 v149, v[156:157], v[154:155] offset0:118 offset1:135
	ds_write2_b64 v149, v[142:143], v[140:141] offset0:152 offset1:169
	ds_write2_b64 v149, v[6:7], v[132:133] offset0:186 offset1:203
	ds_write2_b64 v149, v[138:139], v[144:145] offset0:220 offset1:237
	v_add_u32_e32 v2, 0x1c00, v148
	ds_write2_b64 v2, v[4:5], v[0:1] offset0:126 offset1:143
.LBB0_493:
	s_or_b64 exec, exec, s[2:3]
	v_mov_b32_e32 v134, v180
	s_waitcnt lgkmcnt(0)
	s_barrier
	s_nop 0
	v_ashrrev_i32_e32 v0, 31, v134
	v_add_u32_sdwa v0, v134, v0 dst_sel:DWORD dst_unused:UNUSED_PAD src0_sel:DWORD src1_sel:BYTE_3
	v_ashrrev_i32_e32 v0, 8, v0
	v_mul_i32_i24_e32 v1, 0x100, v0
	v_sub_u32_e32 v1, v134, v1
	v_add_u32_e32 v7, 0x100, v1
	v_mul_i32_i24_e32 v6, 0x220, v0
	v_ashrrev_i32_e32 v0, 4, v1
	v_lshrrev_b32_e32 v132, 4, v7
	v_add_u32_e32 v4, v0, v1
	v_add3_u32 v0, v6, v1, v132
	v_lshl_add_u32 v0, v0, 3, 0
	v_lshl_add_u32 v2, v1, 3, 0
	ds_read_b64 v[0:1], v0 offset:8320
	ds_read_b64 v[2:3], v2 offset:4224
	v_add_lshl_u32 v135, v4, v6, 3
	v_add_u32_e32 v4, 0, v135
	ds_read_b64 v[4:5], v4 offset:6272
	v_add3_u32 v136, v6, v7, v132
	s_waitcnt lgkmcnt(1)
	v_pk_mul_f32 v[6:7], v[0:1], v[2:3] op_sel:[1,1] op_sel_hi:[1,0]
	s_nop 0
	v_pk_fma_f32 v[132:133], v[0:1], v[2:3], v[6:7] op_sel_hi:[0,1,1] neg_lo:[0,0,1]
	s_waitcnt lgkmcnt(0)
	v_pk_add_f32 v[0:1], v[4:5], v[132:133]
	v_add_u32_e32 v2, s18, v135
	ds_write_b64 v2, v[0:1]
	v_pk_add_f32 v[0:1], v[4:5], v[132:133] neg_lo:[0,1] neg_hi:[0,1]
	v_lshl_add_u32 v2, v136, 3, s18
	ds_write_b64 v2, v[0:1]
	v_add_u32_e32 v0, 0x200, v134
	v_ashrrev_i32_e32 v1, 31, v0
	v_add_u32_sdwa v1, v0, v1 dst_sel:DWORD dst_unused:UNUSED_PAD src0_sel:DWORD src1_sel:BYTE_3
	v_ashrrev_i32_e32 v1, 8, v1
	v_mul_i32_i24_e32 v2, 0x100, v1
	v_sub_u32_e32 v0, v0, v2
	v_add_u32_e32 v7, 0x100, v0
	v_mul_i32_i24_e32 v6, 0x220, v1
	v_ashrrev_i32_e32 v1, 4, v0
	v_lshrrev_b32_e32 v132, 4, v7
	v_add_u32_e32 v4, v1, v0
	v_add3_u32 v1, v6, v0, v132
	v_lshl_add_u32 v1, v1, 3, 0
	v_lshl_add_u32 v2, v0, 3, 0
	ds_read_b64 v[0:1], v1 offset:8320
	ds_read_b64 v[2:3], v2 offset:4224
	v_add_lshl_u32 v135, v4, v6, 3
	v_add_u32_e32 v4, 0, v135
	ds_read_b64 v[4:5], v4 offset:6272
	v_add3_u32 v136, v6, v7, v132
	s_waitcnt lgkmcnt(1)
	v_pk_mul_f32 v[6:7], v[0:1], v[2:3] op_sel:[1,1] op_sel_hi:[1,0]
	s_nop 0
	v_pk_fma_f32 v[132:133], v[0:1], v[2:3], v[6:7] op_sel_hi:[0,1,1] neg_lo:[0,0,1]
	s_waitcnt lgkmcnt(0)
	v_pk_add_f32 v[0:1], v[4:5], v[132:133]
	v_add_u32_e32 v2, s18, v135
	ds_write_b64 v2, v[0:1]
	v_pk_add_f32 v[0:1], v[4:5], v[132:133] neg_lo:[0,1] neg_hi:[0,1]
	v_lshl_add_u32 v2, v136, 3, s18
	ds_write_b64 v2, v[0:1]
	v_add_u32_e32 v0, 0x400, v134
	v_ashrrev_i32_e32 v1, 31, v0
	v_add_u32_sdwa v1, v0, v1 dst_sel:DWORD dst_unused:UNUSED_PAD src0_sel:DWORD src1_sel:BYTE_3
	v_ashrrev_i32_e32 v1, 8, v1
	v_mul_i32_i24_e32 v2, 0x100, v1
	v_sub_u32_e32 v0, v0, v2
	v_add_u32_e32 v7, 0x100, v0
	v_mul_i32_i24_e32 v6, 0x220, v1
	v_ashrrev_i32_e32 v1, 4, v0
	v_lshrrev_b32_e32 v132, 4, v7
	v_add_u32_e32 v4, v1, v0
	v_add3_u32 v1, v6, v0, v132
	v_lshl_add_u32 v1, v1, 3, 0
	v_lshl_add_u32 v2, v0, 3, 0
	ds_read_b64 v[0:1], v1 offset:8320
	ds_read_b64 v[2:3], v2 offset:4224
	v_add_lshl_u32 v135, v4, v6, 3
	v_add_u32_e32 v4, 0, v135
	ds_read_b64 v[4:5], v4 offset:6272
	v_add3_u32 v136, v6, v7, v132
	s_waitcnt lgkmcnt(1)
	v_pk_mul_f32 v[6:7], v[0:1], v[2:3] op_sel:[1,1] op_sel_hi:[1,0]
	s_nop 0
	v_pk_fma_f32 v[132:133], v[0:1], v[2:3], v[6:7] op_sel_hi:[0,1,1] neg_lo:[0,0,1]
	s_waitcnt lgkmcnt(0)
	v_pk_add_f32 v[0:1], v[4:5], v[132:133]
	v_add_u32_e32 v2, s18, v135
	ds_write_b64 v2, v[0:1]
	v_pk_add_f32 v[0:1], v[4:5], v[132:133] neg_lo:[0,1] neg_hi:[0,1]
	v_lshl_add_u32 v2, v136, 3, s18
	ds_write_b64 v2, v[0:1]
	v_add_u32_e32 v0, 0x600, v134
	v_ashrrev_i32_e32 v1, 31, v0
	v_add_u32_sdwa v1, v0, v1 dst_sel:DWORD dst_unused:UNUSED_PAD src0_sel:DWORD src1_sel:BYTE_3
	v_ashrrev_i32_e32 v1, 8, v1
	v_mul_i32_i24_e32 v2, 0x100, v1
	v_sub_u32_e32 v0, v0, v2
	v_add_u32_e32 v7, 0x100, v0
	v_mul_i32_i24_e32 v6, 0x220, v1
	v_ashrrev_i32_e32 v1, 4, v0
	v_lshrrev_b32_e32 v132, 4, v7
	v_add_u32_e32 v4, v1, v0
	v_add3_u32 v1, v6, v0, v132
	v_lshl_add_u32 v1, v1, 3, 0
	v_lshl_add_u32 v2, v0, 3, 0
	ds_read_b64 v[0:1], v1 offset:8320
	ds_read_b64 v[2:3], v2 offset:4224
	v_add_lshl_u32 v135, v4, v6, 3
	v_add_u32_e32 v4, 0, v135
	ds_read_b64 v[4:5], v4 offset:6272
	v_add3_u32 v136, v6, v7, v132
	s_waitcnt lgkmcnt(1)
	v_pk_mul_f32 v[6:7], v[0:1], v[2:3] op_sel:[1,1] op_sel_hi:[1,0]
	s_nop 0
	v_pk_fma_f32 v[132:133], v[0:1], v[2:3], v[6:7] op_sel_hi:[0,1,1] neg_lo:[0,0,1]
	s_waitcnt lgkmcnt(0)
	v_pk_add_f32 v[0:1], v[4:5], v[132:133]
	v_add_u32_e32 v2, s18, v135
	ds_write_b64 v2, v[0:1]
	v_pk_add_f32 v[0:1], v[4:5], v[132:133] neg_lo:[0,1] neg_hi:[0,1]
	v_lshl_add_u32 v2, v136, 3, s18
	ds_write_b64 v2, v[0:1]
	v_add_u32_e32 v0, 0x800, v134
	v_ashrrev_i32_e32 v1, 31, v0
	v_add_u32_sdwa v1, v0, v1 dst_sel:DWORD dst_unused:UNUSED_PAD src0_sel:DWORD src1_sel:BYTE_3
	v_ashrrev_i32_e32 v1, 8, v1
	v_mul_i32_i24_e32 v2, 0x100, v1
	v_sub_u32_e32 v0, v0, v2
	v_add_u32_e32 v7, 0x100, v0
	v_mul_i32_i24_e32 v6, 0x220, v1
	v_ashrrev_i32_e32 v1, 4, v0
	v_lshrrev_b32_e32 v132, 4, v7
	v_add_u32_e32 v4, v1, v0
	v_add3_u32 v1, v6, v0, v132
	v_lshl_add_u32 v1, v1, 3, 0
	v_lshl_add_u32 v2, v0, 3, 0
	ds_read_b64 v[0:1], v1 offset:8320
	ds_read_b64 v[2:3], v2 offset:4224
	v_add_lshl_u32 v135, v4, v6, 3
	v_add_u32_e32 v4, 0, v135
	ds_read_b64 v[4:5], v4 offset:6272
	v_add3_u32 v136, v6, v7, v132
	s_waitcnt lgkmcnt(1)
	v_pk_mul_f32 v[6:7], v[0:1], v[2:3] op_sel:[1,1] op_sel_hi:[1,0]
	s_nop 0
	v_pk_fma_f32 v[132:133], v[0:1], v[2:3], v[6:7] op_sel_hi:[0,1,1] neg_lo:[0,0,1]
	s_waitcnt lgkmcnt(0)
	v_pk_add_f32 v[0:1], v[4:5], v[132:133]
	v_add_u32_e32 v2, s18, v135
	ds_write_b64 v2, v[0:1]
	v_pk_add_f32 v[0:1], v[4:5], v[132:133] neg_lo:[0,1] neg_hi:[0,1]
	v_lshl_add_u32 v2, v136, 3, s18
	ds_write_b64 v2, v[0:1]
	v_add_u32_e32 v0, 0xa00, v134
	v_ashrrev_i32_e32 v1, 31, v0
	v_add_u32_sdwa v1, v0, v1 dst_sel:DWORD dst_unused:UNUSED_PAD src0_sel:DWORD src1_sel:BYTE_3
	v_ashrrev_i32_e32 v1, 8, v1
	v_mul_i32_i24_e32 v2, 0x100, v1
	v_sub_u32_e32 v0, v0, v2
	v_add_u32_e32 v7, 0x100, v0
	v_mul_i32_i24_e32 v6, 0x220, v1
	v_ashrrev_i32_e32 v1, 4, v0
	v_lshrrev_b32_e32 v132, 4, v7
	v_add_u32_e32 v4, v1, v0
	v_add3_u32 v1, v6, v0, v132
	v_lshl_add_u32 v1, v1, 3, 0
	v_lshl_add_u32 v2, v0, 3, 0
	ds_read_b64 v[0:1], v1 offset:8320
	ds_read_b64 v[2:3], v2 offset:4224
	v_add_lshl_u32 v135, v4, v6, 3
	v_add_u32_e32 v4, 0, v135
	ds_read_b64 v[4:5], v4 offset:6272
	v_add3_u32 v136, v6, v7, v132
	s_waitcnt lgkmcnt(1)
	v_pk_mul_f32 v[6:7], v[0:1], v[2:3] op_sel:[1,1] op_sel_hi:[1,0]
	s_nop 0
	v_pk_fma_f32 v[132:133], v[0:1], v[2:3], v[6:7] op_sel_hi:[0,1,1] neg_lo:[0,0,1]
	s_waitcnt lgkmcnt(0)
	v_pk_add_f32 v[0:1], v[4:5], v[132:133]
	v_add_u32_e32 v2, s18, v135
	ds_write_b64 v2, v[0:1]
	v_pk_add_f32 v[0:1], v[4:5], v[132:133] neg_lo:[0,1] neg_hi:[0,1]
	v_lshl_add_u32 v2, v136, 3, s18
	ds_write_b64 v2, v[0:1]
	v_add_u32_e32 v0, 0xc00, v134
	v_ashrrev_i32_e32 v1, 31, v0
	v_add_u32_sdwa v1, v0, v1 dst_sel:DWORD dst_unused:UNUSED_PAD src0_sel:DWORD src1_sel:BYTE_3
	v_ashrrev_i32_e32 v1, 8, v1
	v_mul_i32_i24_e32 v2, 0x100, v1
	v_sub_u32_e32 v0, v0, v2
	v_add_u32_e32 v7, 0x100, v0
	v_mul_i32_i24_e32 v6, 0x220, v1
	v_ashrrev_i32_e32 v1, 4, v0
	v_lshrrev_b32_e32 v132, 4, v7
	v_add_u32_e32 v4, v1, v0
	v_add3_u32 v1, v6, v0, v132
	v_lshl_add_u32 v1, v1, 3, 0
	v_lshl_add_u32 v2, v0, 3, 0
	ds_read_b64 v[0:1], v1 offset:8320
	ds_read_b64 v[2:3], v2 offset:4224
	v_add_lshl_u32 v135, v4, v6, 3
	v_add_u32_e32 v4, 0, v135
	ds_read_b64 v[4:5], v4 offset:6272
	v_add3_u32 v136, v6, v7, v132
	s_waitcnt lgkmcnt(1)
	v_pk_mul_f32 v[6:7], v[0:1], v[2:3] op_sel:[1,1] op_sel_hi:[1,0]
	s_nop 0
	v_pk_fma_f32 v[132:133], v[0:1], v[2:3], v[6:7] op_sel_hi:[0,1,1] neg_lo:[0,0,1]
	s_waitcnt lgkmcnt(0)
	v_pk_add_f32 v[0:1], v[4:5], v[132:133]
	v_add_u32_e32 v2, s18, v135
	ds_write_b64 v2, v[0:1]
	v_pk_add_f32 v[0:1], v[4:5], v[132:133] neg_lo:[0,1] neg_hi:[0,1]
	v_lshl_add_u32 v2, v136, 3, s18
	ds_write_b64 v2, v[0:1]
	v_add_u32_e32 v0, 0xe00, v134
	v_ashrrev_i32_e32 v1, 31, v0
	v_add_u32_sdwa v1, v0, v1 dst_sel:DWORD dst_unused:UNUSED_PAD src0_sel:DWORD src1_sel:BYTE_3
	v_ashrrev_i32_e32 v1, 8, v1
	v_mul_i32_i24_e32 v2, 0x100, v1
	v_sub_u32_e32 v0, v0, v2
	v_add_u32_e32 v7, 0x100, v0
	v_mul_i32_i24_e32 v6, 0x220, v1
	v_ashrrev_i32_e32 v1, 4, v0
	v_lshrrev_b32_e32 v132, 4, v7
	v_add_u32_e32 v4, v1, v0
	v_add3_u32 v1, v6, v0, v132
	v_lshl_add_u32 v1, v1, 3, 0
	v_lshl_add_u32 v2, v0, 3, 0
	ds_read_b64 v[0:1], v1 offset:8320
	ds_read_b64 v[2:3], v2 offset:4224
	v_add_lshl_u32 v134, v4, v6, 3
	v_add_u32_e32 v4, 0, v134
	ds_read_b64 v[4:5], v4 offset:6272
	v_add3_u32 v135, v6, v7, v132
	s_waitcnt lgkmcnt(1)
	v_pk_mul_f32 v[6:7], v[0:1], v[2:3] op_sel:[1,1] op_sel_hi:[1,0]
	s_nop 0
	v_pk_fma_f32 v[132:133], v[0:1], v[2:3], v[6:7] op_sel_hi:[0,1,1] neg_lo:[0,0,1]
	s_waitcnt lgkmcnt(0)
	v_pk_add_f32 v[0:1], v[4:5], v[132:133]
	v_add_u32_e32 v2, s18, v134
	ds_write_b64 v2, v[0:1]
	v_pk_add_f32 v[0:1], v[4:5], v[132:133] neg_lo:[0,1] neg_hi:[0,1]
	v_lshl_add_u32 v2, v135, 3, s18
	v_mov_b32_e32 v4, v180
	ds_write_b64 v2, v[0:1]
	s_waitcnt lgkmcnt(0)
	s_barrier
	s_nop 0
	v_cmp_gt_i32_e32 vcc, s16, v4
	s_and_saveexec_b64 s[2:3], vcc
	s_cbranch_execz .LBB0_495
	v_ashrrev_i32_e32 v5, 31, v4
	v_lshrrev_b32_e32 v5, 27, v5
	v_add_u32_e32 v5, v4, v5
	v_pk_mul_f32 v[132:133], v[100:101], s[34:35] op_sel_hi:[1,0]
	v_lshrrev_b32_e32 v100, 5, v5
	v_and_b32_e32 v5, 0xffffffe0, v5
	v_sub_u32_e32 v138, v4, v5
	v_mul_lo_u32 v139, v100, s17
	v_ashrrev_i32_e32 v5, 4, v138
	v_add_u32_e32 v4, s18, v139
	v_lshlrev_b32_e32 v140, 3, v138
	v_lshlrev_b32_e32 v5, 3, v5
	v_add3_u32 v141, v4, v140, v5
	v_pk_mul_f32 v[134:135], v[102:103], s[34:35] op_sel_hi:[1,0]
	v_pk_mul_f32 v[136:137], v[104:105], s[34:35] op_sel_hi:[1,0]
	ds_read2_b64 v[102:105], v141 offset1:34
	v_pk_mul_f32 v[6:7], v[126:127], s[34:35] op_sel_hi:[1,0]
	v_pk_mul_f32 v[106:107], v[106:107], s[34:35] op_sel_hi:[1,0]
	v_pk_mul_f32 v[2:3], v[128:129], s[34:35] op_sel_hi:[1,0]
	v_pk_mul_f32 v[108:109], v[108:109], s[34:35] op_sel_hi:[1,0]
	s_waitcnt lgkmcnt(0)
	v_pk_mul_f32 v[4:5], v[132:133], v[102:103] op_sel:[1,1] op_sel_hi:[0,1]
	v_pk_fma_f32 v[100:101], v[132:133], v[102:103], v[4:5] op_sel_hi:[1,0,1] neg_lo:[0,0,1]
	v_pk_mul_f32 v[102:103], v[134:135], v[104:105] op_sel:[1,1] op_sel_hi:[0,1]
	v_pk_fma_f32 v[4:5], v[134:135], v[104:105], v[102:103] op_sel_hi:[1,0,1] neg_lo:[0,0,1]
	v_pk_mul_f32 v[110:111], v[110:111], s[34:35] op_sel_hi:[1,0]
	ds_read2_b64 v[102:105], v141 offset0:68 offset1:102
	v_pk_mul_f32 v[0:1], v[130:131], s[34:35] op_sel_hi:[1,0]
	v_pk_mul_f32 v[112:113], v[112:113], s[34:35] op_sel_hi:[1,0]
	v_pk_mul_f32 v[114:115], v[114:115], s[34:35] op_sel_hi:[1,0]
	v_add_u32_e32 v132, 0x800, v141
	s_waitcnt lgkmcnt(0)
	v_pk_mul_f32 v[126:127], v[136:137], v[102:103] op_sel:[1,1] op_sel_hi:[0,1]
	v_pk_fma_f32 v[128:129], v[136:137], v[102:103], v[126:127] op_sel_hi:[1,0,1] neg_lo:[0,0,1]
	v_pk_mul_f32 v[116:117], v[116:117], s[34:35] op_sel_hi:[1,0]
	v_pk_mul_f32 v[102:103], v[106:107], v[104:105] op_sel:[1,1] op_sel_hi:[0,1]
	v_pk_fma_f32 v[126:127], v[106:107], v[104:105], v[102:103] op_sel_hi:[1,0,1] neg_lo:[0,0,1]
	v_pk_mul_f32 v[118:119], v[118:119], s[34:35] op_sel_hi:[1,0]
	ds_read2_b64 v[102:105], v141 offset0:136 offset1:170
	v_pk_mul_f32 v[120:121], v[120:121], s[34:35] op_sel_hi:[1,0]
	v_pk_mul_f32 v[122:123], v[122:123], s[34:35] op_sel_hi:[1,0]
	v_pk_mul_f32 v[124:125], v[124:125], s[34:35] op_sel_hi:[1,0]
	s_mov_b32 s29, s30
	s_waitcnt lgkmcnt(0)
	v_pk_mul_f32 v[106:107], v[108:109], v[102:103] op_sel:[1,1] op_sel_hi:[0,1]
	v_pk_fma_f32 v[130:131], v[108:109], v[102:103], v[106:107] op_sel_hi:[1,0,1] neg_lo:[0,0,1]
	s_nop 0
	v_pk_mul_f32 v[102:103], v[110:111], v[104:105] op_sel:[1,1] op_sel_hi:[0,1]
	v_pk_fma_f32 v[106:107], v[110:111], v[104:105], v[102:103] op_sel_hi:[1,0,1] neg_lo:[0,0,1]
	s_nop 0
	ds_read2_b64 v[102:105], v141 offset0:204 offset1:238
	s_waitcnt lgkmcnt(0)
	v_pk_mul_f32 v[108:109], v[112:113], v[102:103] op_sel:[1,1] op_sel_hi:[0,1]
	v_pk_fma_f32 v[110:111], v[112:113], v[102:103], v[108:109] op_sel_hi:[1,0,1] neg_lo:[0,0,1]
	s_nop 0
	v_pk_mul_f32 v[102:103], v[114:115], v[104:105] op_sel:[1,1] op_sel_hi:[0,1]
	v_pk_fma_f32 v[108:109], v[114:115], v[104:105], v[102:103] op_sel_hi:[1,0,1] neg_lo:[0,0,1]
	s_nop 0
	ds_read2_b64 v[102:105], v132 offset0:16 offset1:50
	s_waitcnt lgkmcnt(0)
	v_pk_mul_f32 v[112:113], v[116:117], v[102:103] op_sel:[1,1] op_sel_hi:[0,1]
	v_pk_fma_f32 v[114:115], v[116:117], v[102:103], v[112:113] op_sel_hi:[1,0,1] neg_lo:[0,0,1]
	s_nop 0
	v_pk_mul_f32 v[102:103], v[118:119], v[104:105] op_sel:[1,1] op_sel_hi:[0,1]
	v_pk_fma_f32 v[112:113], v[118:119], v[104:105], v[102:103] op_sel_hi:[1,0,1] neg_lo:[0,0,1]
	s_nop 0
	ds_read2_b64 v[102:105], v132 offset0:84 offset1:118
	s_waitcnt lgkmcnt(0)
	v_pk_mul_f32 v[116:117], v[120:121], v[102:103] op_sel:[1,1] op_sel_hi:[0,1]
	v_pk_fma_f32 v[118:119], v[120:121], v[102:103], v[116:117] op_sel_hi:[1,0,1] neg_lo:[0,0,1]
	s_nop 0
	v_pk_mul_f32 v[102:103], v[122:123], v[104:105] op_sel:[1,1] op_sel_hi:[0,1]
	v_pk_fma_f32 v[116:117], v[122:123], v[104:105], v[102:103] op_sel_hi:[1,0,1] neg_lo:[0,0,1]
	s_nop 0
	ds_read2_b64 v[102:105], v132 offset0:152 offset1:186
	s_waitcnt lgkmcnt(0)
	v_pk_mul_f32 v[120:121], v[124:125], v[102:103] op_sel:[1,1] op_sel_hi:[0,1]
	v_pk_fma_f32 v[122:123], v[124:125], v[102:103], v[120:121] op_sel_hi:[1,0,1] neg_lo:[0,0,1]
	s_nop 0
	v_pk_mul_f32 v[102:103], v[6:7], v[104:105] op_sel:[1,1] op_sel_hi:[0,1]
	v_pk_fma_f32 v[120:121], v[6:7], v[104:105], v[102:103] op_sel_hi:[1,0,1] neg_lo:[0,0,1]
	ds_read2_b64 v[102:105], v132 offset0:220 offset1:254
	s_waitcnt lgkmcnt(0)
	v_pk_mul_f32 v[6:7], v[2:3], v[102:103] op_sel:[1,1] op_sel_hi:[0,1]
	v_pk_fma_f32 v[124:125], v[2:3], v[102:103], v[6:7] op_sel_hi:[1,0,1] neg_lo:[0,0,1]
	v_pk_add_f32 v[102:103], v[130:131], v[122:123] neg_lo:[0,1] neg_hi:[0,1]
	v_pk_mul_f32 v[2:3], v[0:1], v[104:105] op_sel:[1,1] op_sel_hi:[0,1]
	v_pk_fma_f32 v[6:7], v[0:1], v[104:105], v[2:3] op_sel_hi:[1,0,1] neg_lo:[0,0,1]
	v_pk_add_f32 v[2:3], v[100:101], v[114:115] neg_lo:[0,1] neg_hi:[0,1]
	v_xor_b32_e32 v104, 0x80000000, v103
	v_mov_b32_e32 v105, v102
	v_pk_add_f32 v[0:1], v[100:101], v[114:115]
	v_pk_add_f32 v[100:101], v[130:131], v[122:123]
	v_pk_add_f32 v[114:115], v[2:3], v[104:105]
	v_pk_add_f32 v[2:3], v[2:3], v[104:105] neg_lo:[0,1] neg_hi:[0,1]
	v_pk_add_f32 v[104:105], v[106:107], v[120:121]
	v_pk_add_f32 v[106:107], v[106:107], v[120:121] neg_lo:[0,1] neg_hi:[0,1]
	v_pk_add_f32 v[102:103], v[0:1], v[100:101]
	v_pk_add_f32 v[0:1], v[0:1], v[100:101] neg_lo:[0,1] neg_hi:[0,1]
	v_pk_add_f32 v[100:101], v[4:5], v[112:113]
	v_pk_add_f32 v[4:5], v[4:5], v[112:113] neg_lo:[0,1] neg_hi:[0,1]
	v_xor_b32_e32 v112, 0x80000000, v107
	v_mov_b32_e32 v113, v106
	v_pk_add_f32 v[106:107], v[100:101], v[104:105]
	v_pk_add_f32 v[120:121], v[4:5], v[112:113]
	v_pk_add_f32 v[100:101], v[100:101], v[104:105] neg_lo:[0,1] neg_hi:[0,1]
	v_pk_add_f32 v[4:5], v[4:5], v[112:113] neg_lo:[0,1] neg_hi:[0,1]
	v_pk_add_f32 v[104:105], v[128:129], v[118:119]
	v_pk_add_f32 v[112:113], v[128:129], v[118:119] neg_lo:[0,1] neg_hi:[0,1]
	v_pk_add_f32 v[118:119], v[110:111], v[124:125]
	v_pk_add_f32 v[110:111], v[110:111], v[124:125] neg_lo:[0,1] neg_hi:[0,1]
	s_nop 0
	v_xor_b32_e32 v122, 0x80000000, v111
	v_mov_b32_e32 v123, v110
	v_pk_add_f32 v[124:125], v[112:113], v[122:123]
	v_pk_add_f32 v[112:113], v[112:113], v[122:123] neg_lo:[0,1] neg_hi:[0,1]
	v_pk_add_f32 v[122:123], v[108:109], v[6:7]
	v_pk_add_f32 v[6:7], v[108:109], v[6:7] neg_lo:[0,1] neg_hi:[0,1]
	v_pk_add_f32 v[110:111], v[104:105], v[118:119]
	v_pk_add_f32 v[104:105], v[104:105], v[118:119] neg_lo:[0,1] neg_hi:[0,1]
	v_pk_add_f32 v[118:119], v[126:127], v[116:117]
	v_pk_add_f32 v[116:117], v[126:127], v[116:117] neg_lo:[0,1] neg_hi:[0,1]
	v_xor_b32_e32 v108, 0x80000000, v7
	v_mov_b32_e32 v109, v6
	v_pk_add_f32 v[126:127], v[116:117], v[108:109]
	v_pk_add_f32 v[108:109], v[116:117], v[108:109] neg_lo:[0,1] neg_hi:[0,1]
	v_pk_mul_f32 v[116:117], v[120:121], s[14:15] op_sel_hi:[1,0]
	v_pk_add_f32 v[6:7], v[118:119], v[122:123]
	v_pk_add_f32 v[118:119], v[118:119], v[122:123] neg_lo:[0,1] neg_hi:[0,1]
	v_pk_fma_f32 v[122:123], v[120:121], s[22:23], v[116:117] op_sel:[0,0,1] op_sel_hi:[1,0,0] neg_lo:[0,0,1]
	s_nop 0
	v_pk_mul_f32 v[116:117], v[100:101], s[24:25] op_sel_hi:[1,0]
	s_nop 0
	v_pk_fma_f32 v[120:121], v[100:101], s[24:25], v[116:117] op_sel:[0,0,1] op_sel_hi:[1,0,0] neg_lo:[0,0,1]
	v_pk_mul_f32 v[116:117], v[4:5], s[22:23] op_sel_hi:[1,0]
	v_pk_fma_f32 v[128:129], v[4:5], s[14:15], v[116:117] op_sel:[0,0,1] op_sel_hi:[1,0,0] neg_lo:[0,0,1]
	s_nop 0
	v_pk_mul_f32 v[4:5], v[124:125], s[24:25] op_sel_hi:[1,0]
	s_nop 0
	v_pk_fma_f32 v[116:117], v[124:125], s[24:25], v[4:5] op_sel:[0,0,1] op_sel_hi:[1,0,0] neg_lo:[0,0,1]
	s_nop 0
	v_pk_fma_f32 v[4:5], v[104:105], 0, v[104:105] op_sel:[0,0,1] op_sel_hi:[1,0,0] neg_lo:[0,0,1]
	s_nop 0
	v_pk_mul_f32 v[104:105], v[112:113], s[26:27] op_sel_hi:[1,0]
	s_nop 0
	v_pk_fma_f32 v[124:125], v[112:113], s[26:27], v[104:105] op_sel:[0,0,1] op_sel_hi:[1,0,0] neg_hi:[0,0,1]
	v_pk_mul_f32 v[112:113], v[126:127], s[22:23] op_sel_hi:[1,0]
	v_pk_fma_f32 v[130:131], v[126:127], s[14:15], v[112:113] op_sel:[0,0,1] op_sel_hi:[1,0,0] neg_lo:[0,0,1]
	s_mov_b32 s15, s28
	v_pk_mul_f32 v[112:113], v[118:119], s[26:27] op_sel_hi:[1,0]
	v_pk_add_f32 v[104:105], v[2:3], v[124:125]
	v_pk_fma_f32 v[126:127], v[118:119], s[26:27], v[112:113] op_sel:[0,0,1] op_sel_hi:[1,0,0] neg_hi:[0,0,1]
	v_pk_add_f32 v[2:3], v[2:3], v[124:125] neg_lo:[0,1] neg_hi:[0,1]
	v_pk_mul_f32 v[112:113], v[108:109], s[28:29] op_sel_hi:[0,1]
	v_pk_fma_f32 v[108:109], v[108:109], s[14:15], v[112:113] op_sel:[1,0,0]
	v_pk_add_f32 v[112:113], v[102:103], v[110:111]
	v_pk_add_f32 v[102:103], v[102:103], v[110:111] neg_lo:[0,1] neg_hi:[0,1]
	v_pk_add_f32 v[110:111], v[106:107], v[6:7]
	v_pk_add_f32 v[6:7], v[106:107], v[6:7] neg_lo:[0,1] neg_hi:[0,1]
	v_pk_add_f32 v[100:101], v[120:121], v[126:127] neg_lo:[0,1] neg_hi:[0,1]
	v_xor_b32_e32 v106, 0x80000000, v7
	v_mov_b32_e32 v107, v6
	v_pk_add_f32 v[6:7], v[112:113], v[110:111]
	v_pk_add_f32 v[118:119], v[102:103], v[106:107]
	v_pk_add_f32 v[110:111], v[112:113], v[110:111] neg_lo:[0,1] neg_hi:[0,1]
	v_pk_add_f32 v[102:103], v[102:103], v[106:107] neg_lo:[0,1] neg_hi:[0,1]
	v_pk_add_f32 v[106:107], v[114:115], v[116:117]
	v_pk_add_f32 v[112:113], v[114:115], v[116:117] neg_lo:[0,1] neg_hi:[0,1]
	v_pk_add_f32 v[114:115], v[122:123], v[130:131]
	v_pk_add_f32 v[116:117], v[122:123], v[130:131] neg_lo:[0,1] neg_hi:[0,1]
	s_nop 0
	v_xor_b32_e32 v122, 0x80000000, v117
	v_mov_b32_e32 v123, v116
	v_pk_add_f32 v[116:117], v[106:107], v[114:115]
	v_pk_add_f32 v[106:107], v[106:107], v[114:115] neg_lo:[0,1] neg_hi:[0,1]
	v_pk_add_f32 v[114:115], v[0:1], v[4:5]
	v_pk_add_f32 v[0:1], v[0:1], v[4:5] neg_lo:[0,1] neg_hi:[0,1]
	v_pk_add_f32 v[4:5], v[120:121], v[126:127]
	v_xor_b32_e32 v120, 0x80000000, v101
	v_mov_b32_e32 v121, v100
	v_pk_add_f32 v[100:101], v[114:115], v[4:5]
	v_pk_add_f32 v[4:5], v[114:115], v[4:5] neg_lo:[0,1] neg_hi:[0,1]
	v_pk_add_f32 v[114:115], v[128:129], v[108:109]
	v_pk_add_f32 v[108:109], v[128:129], v[108:109] neg_lo:[0,1] neg_hi:[0,1]
	v_pk_add_f32 v[130:131], v[112:113], v[122:123]
	v_pk_add_f32 v[112:113], v[112:113], v[122:123] neg_lo:[0,1] neg_hi:[0,1]
	v_pk_add_f32 v[122:123], v[0:1], v[120:121]
	v_pk_add_f32 v[0:1], v[0:1], v[120:121] neg_lo:[0,1] neg_hi:[0,1]
	v_xor_b32_e32 v120, 0x80000000, v109
	v_mov_b32_e32 v121, v108
	v_pk_add_f32 v[108:109], v[104:105], v[114:115]
	v_pk_add_f32 v[104:105], v[104:105], v[114:115] neg_lo:[0,1] neg_hi:[0,1]
	v_add_u32_e32 v114, 0, v139
	v_lshlrev_b32_e32 v115, 7, v138
	v_add3_u32 v114, v114, v115, v140
	v_add_u32_e32 v115, 0x1880, v114
	ds_write2_b64 v115, v[6:7], v[116:117] offset1:1
	v_add_u32_e32 v6, 0x1890, v114
	ds_write2_b64 v6, v[100:101], v[108:109] offset1:1
	v_add_u32_e32 v6, 0x18a0, v114
	v_pk_add_f32 v[124:125], v[2:3], v[120:121]
	ds_write2_b64 v6, v[118:119], v[130:131] offset1:1
	v_add_u32_e32 v6, 0x18b0, v114
	ds_write2_b64 v6, v[122:123], v[124:125] offset1:1
	v_add_u32_e32 v6, 0x18c0, v114
	ds_write2_b64 v6, v[110:111], v[106:107] offset1:1
	v_add_u32_e32 v6, 0x18d0, v114
	ds_write2_b64 v6, v[4:5], v[104:105] offset1:1
	v_add_u32_e32 v4, 0x18e0, v114
	v_pk_add_f32 v[2:3], v[2:3], v[120:121] neg_lo:[0,1] neg_hi:[0,1]
	ds_write2_b64 v4, v[102:103], v[112:113] offset1:1
	v_add_u32_e32 v4, 0x18f0, v114
	ds_write2_b64 v4, v[0:1], v[2:3] offset1:1
.LBB0_495:
	s_or_b64 exec, exec, s[2:3]
	v_mov_b32_e32 v0, v180
	s_waitcnt lgkmcnt(0)
	s_barrier
	s_nop 0
	v_cmp_gt_i32_e32 vcc, s16, v0
	s_and_saveexec_b64 s[2:3], vcc
	s_cbranch_execz .LBB0_497
	v_ashrrev_i32_e32 v1, 31, v0
	v_lshrrev_b32_e32 v1, 27, v1
	v_add_u32_e32 v1, v0, v1
	v_lshrrev_b32_e32 v2, 5, v1
	v_and_b32_e32 v1, 0xffffffe0, v1
	v_sub_u32_e32 v0, v0, v1
	v_lshrrev_b16_sdwa v1, v175, sext(v0) dst_sel:DWORD dst_unused:UNUSED_PAD src0_sel:DWORD src1_sel:BYTE_0
	v_and_b32_e32 v1, 15, v1
	v_add_u16_e32 v1, v0, v1
	v_ashrrev_i16_sdwa v126, v176, sext(v1) dst_sel:DWORD dst_unused:UNUSED_PAD src0_sel:DWORD src1_sel:BYTE_0
	v_and_b32_e32 v1, 0xf0, v1
	v_sub_u16_e32 v100, v0, v1
	v_mul_lo_u32 v127, v2, s17
	v_lshlrev_b32_e32 v2, 3, v0
	v_ashrrev_i32_e32 v0, 4, v0
	v_add_u32_e32 v1, 0, v127
	v_lshlrev_b32_e32 v0, 3, v0
	v_add3_u32 v4, v1, v2, v0
	v_bfe_i32 v128, v100, 0, 8
	v_add_u32_e32 v5, 0x1800, v4
	v_mad_i32_i24 v129, v128, s19, 0
	ds_read2_b64 v[0:3], v5 offset0:16 offset1:50
	ds_read2_b64 v[104:107], v5 offset0:84 offset1:118
	ds_read2_b64 v[112:115], v5 offset0:152 offset1:186
	ds_read2_b64 v[116:119], v5 offset0:220 offset1:254
	v_add_u32_e32 v5, 0x2000, v4
	v_add_u32_e32 v100, 0x808, v129
	ds_read2_b64 v[120:123], v5 offset0:32 offset1:66
	ds_read2_b64 v[130:133], v5 offset0:100 offset1:134
	ds_read2_b64 v[134:137], v5 offset0:168 offset1:202
	ds_read2_b64 v[108:111], v100 offset1:1
	v_add_u32_e32 v4, 0x2400, v4
	ds_read2_b64 v[4:7], v4 offset0:108 offset1:142
	s_mov_b32 s29, s30
	s_waitcnt lgkmcnt(1)
	v_pk_mul_f32 v[100:101], v[2:3], v[108:109] op_sel:[1,1] op_sel_hi:[0,1]
	v_pk_fma_f32 v[102:103], v[2:3], v[108:109], v[100:101]
	v_pk_fma_f32 v[2:3], v[2:3], v[108:109], v[100:101] op_sel_hi:[1,0,1] neg_lo:[0,0,1] neg_hi:[0,0,1]
	s_nop 0
	v_mov_b32_e32 v2, v111
	v_mov_b32_e32 v103, v3
	v_pk_mul_f32 v[2:3], v[104:105], v[2:3] op_sel:[1,0] op_sel_hi:[0,0]
	v_pk_fma_f32 v[100:101], v[104:105], v[110:111], v[2:3] op_sel_hi:[1,0,1] neg_hi:[0,0,1]
	s_nop 0
	v_add_u32_e32 v2, 0x818, v129
	ds_read2_b64 v[138:141], v2 offset1:1
	s_waitcnt lgkmcnt(0)
	v_pk_mul_f32 v[104:105], v[106:107], v[138:139] op_sel:[1,1] op_sel_hi:[0,1]
	v_pk_fma_f32 v[2:3], v[106:107], v[138:139], v[104:105]
	v_pk_fma_f32 v[104:105], v[106:107], v[138:139], v[104:105] op_sel_hi:[1,0,1] neg_lo:[0,0,1] neg_hi:[0,0,1]
	s_nop 0
	v_mov_b32_e32 v104, v141
	v_mov_b32_e32 v3, v105
	v_pk_mul_f32 v[104:105], v[112:113], v[104:105] op_sel:[1,0] op_sel_hi:[0,0]
	v_pk_fma_f32 v[110:111], v[112:113], v[140:141], v[104:105] op_sel_hi:[1,0,1] neg_hi:[0,0,1]
	s_nop 0
	v_add_u32_e32 v104, 0x828, v129
	ds_read2_b64 v[138:141], v104 offset1:1
	s_waitcnt lgkmcnt(0)
	v_pk_mul_f32 v[104:105], v[114:115], v[138:139] op_sel:[1,1] op_sel_hi:[0,1]
	v_pk_fma_f32 v[108:109], v[114:115], v[138:139], v[104:105]
	v_pk_fma_f32 v[104:105], v[114:115], v[138:139], v[104:105] op_sel_hi:[1,0,1] neg_lo:[0,0,1] neg_hi:[0,0,1]
	s_nop 0
	v_mov_b32_e32 v104, v141
	v_mov_b32_e32 v109, v105
	v_pk_mul_f32 v[104:105], v[116:117], v[104:105] op_sel:[1,0] op_sel_hi:[0,0]
	v_pk_fma_f32 v[106:107], v[116:117], v[140:141], v[104:105] op_sel_hi:[1,0,1] neg_hi:[0,0,1]
	s_nop 0
	v_add_u32_e32 v104, 0x838, v129
	ds_read2_b64 v[112:115], v104 offset1:1
	s_waitcnt lgkmcnt(0)
	v_pk_mul_f32 v[116:117], v[118:119], v[112:113] op_sel:[1,1] op_sel_hi:[0,1]
	v_pk_fma_f32 v[104:105], v[118:119], v[112:113], v[116:117]
	v_pk_fma_f32 v[112:113], v[118:119], v[112:113], v[116:117] op_sel_hi:[1,0,1] neg_lo:[0,0,1] neg_hi:[0,0,1]
	s_nop 0
	v_mov_b32_e32 v112, v115
	v_mov_b32_e32 v105, v113
	v_pk_mul_f32 v[112:113], v[120:121], v[112:113] op_sel:[1,0] op_sel_hi:[0,0]
	v_pk_fma_f32 v[118:119], v[120:121], v[114:115], v[112:113] op_sel_hi:[1,0,1] neg_hi:[0,0,1]
	s_nop 0
	v_add_u32_e32 v112, 0x848, v129
	ds_read2_b64 v[138:141], v112 offset1:1
	s_waitcnt lgkmcnt(0)
	v_pk_mul_f32 v[112:113], v[122:123], v[138:139] op_sel:[1,1] op_sel_hi:[0,1]
	v_pk_fma_f32 v[116:117], v[122:123], v[138:139], v[112:113]
	v_pk_fma_f32 v[112:113], v[122:123], v[138:139], v[112:113] op_sel_hi:[1,0,1] neg_lo:[0,0,1] neg_hi:[0,0,1]
	s_nop 0
	v_mov_b32_e32 v112, v141
	v_mov_b32_e32 v117, v113
	v_pk_mul_f32 v[112:113], v[130:131], v[112:113] op_sel:[1,0] op_sel_hi:[0,0]
	v_pk_fma_f32 v[114:115], v[130:131], v[140:141], v[112:113] op_sel_hi:[1,0,1] neg_hi:[0,0,1]
	s_nop 0
	v_add_u32_e32 v112, 0x858, v129
	ds_read2_b64 v[120:123], v112 offset1:1
	s_waitcnt lgkmcnt(0)
	v_pk_mul_f32 v[124:125], v[132:133], v[120:121] op_sel:[1,1] op_sel_hi:[0,1]
	v_pk_fma_f32 v[112:113], v[132:133], v[120:121], v[124:125]
	v_pk_fma_f32 v[120:121], v[132:133], v[120:121], v[124:125] op_sel_hi:[1,0,1] neg_lo:[0,0,1] neg_hi:[0,0,1]
	s_nop 0
	v_mov_b32_e32 v120, v123
	v_mov_b32_e32 v113, v121
	v_pk_mul_f32 v[120:121], v[134:135], v[120:121] op_sel:[1,0] op_sel_hi:[0,0]
	v_pk_fma_f32 v[124:125], v[134:135], v[122:123], v[120:121] op_sel_hi:[1,0,1] neg_hi:[0,0,1]
	s_nop 0
	v_add_u32_e32 v120, 0x868, v129
	ds_read2_b64 v[130:133], v120 offset1:1
	s_waitcnt lgkmcnt(0)
	v_pk_mul_f32 v[120:121], v[136:137], v[130:131] op_sel:[1,1] op_sel_hi:[0,1]
	v_pk_fma_f32 v[122:123], v[136:137], v[130:131], v[120:121]
	v_pk_fma_f32 v[120:121], v[136:137], v[130:131], v[120:121] op_sel_hi:[1,0,1] neg_lo:[0,0,1] neg_hi:[0,0,1]
	s_nop 0
	v_mov_b32_e32 v120, v133
	v_pk_mul_f32 v[130:131], v[4:5], v[120:121] op_sel:[1,0] op_sel_hi:[0,0]
	v_mov_b32_e32 v123, v121
	v_pk_fma_f32 v[120:121], v[4:5], v[132:133], v[130:131] op_sel_hi:[1,0,1] neg_hi:[0,0,1]
	s_nop 0
	ds_read_b64 v[4:5], v129 offset:2168
	s_waitcnt lgkmcnt(0)
	v_pk_mul_f32 v[130:131], v[6:7], v[4:5] op_sel:[1,1] op_sel_hi:[0,1]
	v_pk_fma_f32 v[132:133], v[6:7], v[4:5], v[130:131] op_sel_hi:[1,0,1] neg_hi:[0,0,1]
	v_pk_add_f32 v[6:7], v[110:111], v[124:125]
	v_pk_add_f32 v[4:5], v[0:1], v[118:119]
	v_pk_add_f32 v[110:111], v[110:111], v[124:125] neg_lo:[0,1] neg_hi:[0,1]
	v_pk_add_f32 v[0:1], v[0:1], v[118:119] neg_lo:[0,1] neg_hi:[0,1]
	v_xor_b32_e32 v118, 0x80000000, v111
	v_mov_b32_e32 v119, v110
	v_pk_add_f32 v[110:111], v[4:5], v[6:7]
	v_pk_add_f32 v[4:5], v[4:5], v[6:7] neg_lo:[0,1] neg_hi:[0,1]
	v_pk_add_f32 v[6:7], v[102:103], v[116:117]
	v_pk_add_f32 v[102:103], v[102:103], v[116:117] neg_lo:[0,1] neg_hi:[0,1]
	v_pk_add_f32 v[116:117], v[108:109], v[122:123]
	v_pk_add_f32 v[108:109], v[108:109], v[122:123] neg_lo:[0,1] neg_hi:[0,1]
	v_pk_add_f32 v[124:125], v[0:1], v[118:119]
	v_pk_add_f32 v[0:1], v[0:1], v[118:119] neg_lo:[0,1] neg_hi:[0,1]
	v_xor_b32_e32 v118, 0x80000000, v109
	v_mov_b32_e32 v119, v108
	v_pk_add_f32 v[108:109], v[6:7], v[116:117]
	v_pk_add_f32 v[6:7], v[6:7], v[116:117] neg_lo:[0,1] neg_hi:[0,1]
	v_pk_add_f32 v[116:117], v[100:101], v[114:115]
	v_pk_add_f32 v[100:101], v[100:101], v[114:115] neg_lo:[0,1] neg_hi:[0,1]
	v_pk_add_f32 v[114:115], v[106:107], v[120:121]
	v_pk_add_f32 v[106:107], v[106:107], v[120:121] neg_lo:[0,1] neg_hi:[0,1]
	v_pk_add_f32 v[122:123], v[102:103], v[118:119]
	v_pk_add_f32 v[102:103], v[102:103], v[118:119] neg_lo:[0,1] neg_hi:[0,1]
	v_xor_b32_e32 v118, 0x80000000, v107
	v_mov_b32_e32 v119, v106
	v_pk_add_f32 v[106:107], v[116:117], v[114:115]
	v_pk_add_f32 v[114:115], v[116:117], v[114:115] neg_lo:[0,1] neg_hi:[0,1]
	v_pk_add_f32 v[116:117], v[2:3], v[112:113]
	v_pk_add_f32 v[2:3], v[2:3], v[112:113] neg_lo:[0,1] neg_hi:[0,1]
	v_pk_add_f32 v[112:113], v[104:105], v[132:133]
	v_pk_add_f32 v[104:105], v[104:105], v[132:133] neg_lo:[0,1] neg_hi:[0,1]
	v_pk_add_f32 v[120:121], v[100:101], v[118:119]
	v_pk_add_f32 v[100:101], v[100:101], v[118:119] neg_lo:[0,1] neg_hi:[0,1]
	v_xor_b32_e32 v118, 0x80000000, v105
	v_mov_b32_e32 v119, v104
	v_pk_add_f32 v[104:105], v[116:117], v[112:113]
	v_pk_add_f32 v[112:113], v[116:117], v[112:113] neg_lo:[0,1] neg_hi:[0,1]
	v_pk_mul_f32 v[116:117], v[122:123], s[14:15] op_sel_hi:[1,0]
	v_pk_add_f32 v[130:131], v[2:3], v[118:119]
	v_pk_add_f32 v[2:3], v[2:3], v[118:119] neg_lo:[0,1] neg_hi:[0,1]
	v_pk_fma_f32 v[118:119], v[122:123], s[22:23], v[116:117] op_sel:[0,0,1] op_sel_hi:[1,0,0] neg_lo:[0,0,1]
	s_nop 0
	v_pk_mul_f32 v[116:117], v[6:7], s[24:25] op_sel_hi:[1,0]
	s_nop 0
	v_pk_fma_f32 v[122:123], v[6:7], s[24:25], v[116:117] op_sel:[0,0,1] op_sel_hi:[1,0,0] neg_lo:[0,0,1]
	v_pk_mul_f32 v[116:117], v[102:103], s[22:23] op_sel_hi:[1,0]
	v_pk_fma_f32 v[132:133], v[102:103], s[14:15], v[116:117] op_sel:[0,0,1] op_sel_hi:[1,0,0] neg_lo:[0,0,1]
	s_nop 0
	v_pk_mul_f32 v[102:103], v[120:121], s[24:25] op_sel_hi:[1,0]
	s_nop 0
	v_pk_fma_f32 v[116:117], v[120:121], s[24:25], v[102:103] op_sel:[0,0,1] op_sel_hi:[1,0,0] neg_lo:[0,0,1]
	s_nop 0
	v_pk_fma_f32 v[102:103], v[114:115], 0, v[114:115] op_sel:[0,0,1] op_sel_hi:[1,0,0] neg_lo:[0,0,1]
	s_nop 0
	v_pk_mul_f32 v[114:115], v[100:101], s[26:27] op_sel_hi:[1,0]
	s_nop 0
	v_pk_fma_f32 v[120:121], v[100:101], s[26:27], v[114:115] op_sel:[0,0,1] op_sel_hi:[1,0,0] neg_hi:[0,0,1]
	v_pk_mul_f32 v[114:115], v[130:131], s[22:23] op_sel_hi:[1,0]
	v_pk_fma_f32 v[134:135], v[130:131], s[14:15], v[114:115] op_sel:[0,0,1] op_sel_hi:[1,0,0] neg_lo:[0,0,1]
	s_mov_b32 s15, s28
	v_pk_mul_f32 v[114:115], v[112:113], s[26:27] op_sel_hi:[1,0]
	v_pk_add_f32 v[100:101], v[0:1], v[120:121]
	v_pk_fma_f32 v[130:131], v[112:113], s[26:27], v[114:115] op_sel:[0,0,1] op_sel_hi:[1,0,0] neg_hi:[0,0,1]
	v_pk_add_f32 v[0:1], v[0:1], v[120:121] neg_lo:[0,1] neg_hi:[0,1]
	v_pk_mul_f32 v[112:113], v[2:3], s[28:29] op_sel_hi:[0,1]
	v_pk_fma_f32 v[2:3], v[2:3], s[14:15], v[112:113] op_sel:[1,0,0]
	v_pk_add_f32 v[112:113], v[110:111], v[106:107]
	v_pk_add_f32 v[106:107], v[110:111], v[106:107] neg_lo:[0,1] neg_hi:[0,1]
	v_pk_add_f32 v[110:111], v[108:109], v[104:105]
	v_pk_add_f32 v[104:105], v[108:109], v[104:105] neg_lo:[0,1] neg_hi:[0,1]
	v_pk_add_f32 v[6:7], v[122:123], v[130:131]
	v_xor_b32_e32 v108, 0x80000000, v105
	v_mov_b32_e32 v109, v104
	v_pk_add_f32 v[104:105], v[112:113], v[110:111]
	v_pk_add_f32 v[114:115], v[106:107], v[108:109]
	v_pk_add_f32 v[110:111], v[112:113], v[110:111] neg_lo:[0,1] neg_hi:[0,1]
	v_pk_add_f32 v[106:107], v[106:107], v[108:109] neg_lo:[0,1] neg_hi:[0,1]
	v_pk_add_f32 v[108:109], v[124:125], v[116:117]
	v_pk_add_f32 v[112:113], v[124:125], v[116:117] neg_lo:[0,1] neg_hi:[0,1]
	v_pk_add_f32 v[116:117], v[118:119], v[134:135]
	v_pk_add_f32 v[118:119], v[118:119], v[134:135] neg_lo:[0,1] neg_hi:[0,1]
	s_nop 0
	v_xor_b32_e32 v124, 0x80000000, v119
	v_mov_b32_e32 v125, v118
	v_pk_add_f32 v[118:119], v[108:109], v[116:117]
	v_pk_add_f32 v[108:109], v[108:109], v[116:117] neg_lo:[0,1] neg_hi:[0,1]
	v_pk_add_f32 v[116:117], v[4:5], v[102:103]
	v_pk_add_f32 v[4:5], v[4:5], v[102:103] neg_lo:[0,1] neg_hi:[0,1]
	v_pk_add_f32 v[102:103], v[122:123], v[130:131] neg_lo:[0,1] neg_hi:[0,1]
	v_pk_add_f32 v[134:135], v[112:113], v[124:125]
	v_xor_b32_e32 v122, 0x80000000, v103
	v_mov_b32_e32 v123, v102
	v_pk_add_f32 v[102:103], v[116:117], v[6:7]
	v_pk_add_f32 v[6:7], v[116:117], v[6:7] neg_lo:[0,1] neg_hi:[0,1]
	v_pk_add_f32 v[116:117], v[132:133], v[2:3]
	v_pk_add_f32 v[2:3], v[132:133], v[2:3] neg_lo:[0,1] neg_hi:[0,1]
	v_pk_add_f32 v[112:113], v[112:113], v[124:125] neg_lo:[0,1] neg_hi:[0,1]
	v_xor_b32_e32 v120, 0x80000000, v3
	v_mov_b32_e32 v121, v2
	v_pk_add_f32 v[2:3], v[100:101], v[116:117]
	v_pk_add_f32 v[100:101], v[100:101], v[116:117] neg_lo:[0,1] neg_hi:[0,1]
	v_bfe_i32 v116, v126, 0, 16
	v_lshl_add_u32 v116, v116, 8, v128
	v_pk_add_f32 v[124:125], v[4:5], v[122:123]
	v_pk_add_f32 v[4:5], v[4:5], v[122:123] neg_lo:[0,1] neg_hi:[0,1]
	v_pk_add_f32 v[122:123], v[0:1], v[120:121]
	v_pk_add_f32 v[0:1], v[0:1], v[120:121] neg_lo:[0,1] neg_hi:[0,1]
	v_lshlrev_b32_e32 v120, 3, v116
	v_ashrrev_i32_e32 v116, 4, v116
	v_add_u32_e32 v117, s18, v127
	v_lshlrev_b32_e32 v116, 3, v116
	v_add3_u32 v116, v117, v120, v116
	ds_write2_b64 v116, v[104:105], v[118:119] offset1:17
	ds_write2_b64 v116, v[102:103], v[2:3] offset0:34 offset1:51
	ds_write2_b64 v116, v[114:115], v[134:135] offset0:68 offset1:85
	ds_write2_b64 v116, v[124:125], v[122:123] offset0:102 offset1:119
	ds_write2_b64 v116, v[110:111], v[108:109] offset0:136 offset1:153
	ds_write2_b64 v116, v[6:7], v[100:101] offset0:170 offset1:187
	ds_write2_b64 v116, v[106:107], v[112:113] offset0:204 offset1:221
	ds_write2_b64 v116, v[4:5], v[0:1] offset0:238 offset1:255
.LBB0_497:
	s_or_b64 exec, exec, s[2:3]
	s_waitcnt vmcnt(1)
	v_lshlrev_b32_e32 v0, 16, v82
	v_mul_f32_e32 v4, v185, v193
	v_and_b32_e32 v1, 0xffff0000, v82
	v_fmac_f32_e32 v4, v186, v0
	v_fmac_f32_e32 v4, v184, v1
	v_lshlrev_b32_e32 v2, 16, v83
	v_add_f32_e32 v5, v183, v4
	v_mul_f32_e32 v4, v186, v1
	v_fmac_f32_e32 v4, v185, v0
	v_mul_f32_e32 v0, v186, v2
	v_and_b32_e32 v3, 0xffff0000, v83
	v_fmac_f32_e32 v0, v185, v1
	v_fmac_f32_e32 v0, v184, v3
	v_add_f32_e32 v1, v183, v0
	v_mul_f32_e32 v0, v186, v3
	v_fmac_f32_e32 v0, v185, v2
	v_fmac_f32_e32 v4, v184, v2
	v_fmac_f32_e32 v0, v184, v194
	v_and_b32_e32 v2, 0xffff0000, v80
	v_add_f32_e32 v7, v183, v4
	v_add_f32_e32 v3, v183, v0
	v_lshlrev_b32_e32 v0, 16, v80
	v_lshlrev_b32_e32 v80, 16, v81
	v_mul_f32_e32 v4, v185, v191
	v_mul_f32_e32 v6, v186, v2
	v_and_b32_e32 v81, 0xffff0000, v81
	v_fmac_f32_e32 v4, v186, v0
	v_fmac_f32_e32 v6, v185, v0
	v_mul_f32_e32 v0, v186, v80
	v_fmac_f32_e32 v4, v184, v2
	v_fmac_f32_e32 v0, v185, v2
	v_mul_f32_e32 v2, v186, v81
	v_fmac_f32_e32 v6, v184, v80
	v_fmac_f32_e32 v2, v185, v80
	v_lshlrev_b32_e32 v80, 16, v78
	v_and_b32_e32 v78, 0xffff0000, v78
	v_fmac_f32_e32 v0, v184, v81
	v_lshlrev_b32_e32 v82, 16, v79
	v_and_b32_e32 v83, 0xffff0000, v79
	v_mul_f32_e32 v79, v182, v189
	v_mul_f32_e32 v81, v42, v78
	v_fmac_f32_e32 v79, v42, v80
	v_fmac_f32_e32 v81, v182, v80
	v_mul_f32_e32 v80, v42, v82
	v_fmac_f32_e32 v79, v38, v78
	v_fmac_f32_e32 v80, v182, v78
	v_mul_f32_e32 v78, v42, v83
	v_fmac_f32_e32 v81, v38, v82
	v_fmac_f32_e32 v80, v38, v83
	v_fmac_f32_e32 v78, v182, v82
	v_add_f32_e32 v101, v27, v81
	v_add_f32_e32 v81, v27, v80
	v_fmac_f32_e32 v78, v38, v190
	v_lshlrev_b32_e32 v80, 16, v68
	v_and_b32_e32 v68, 0xffff0000, v68
	v_add_f32_e32 v83, v27, v78
	v_lshlrev_b32_e32 v82, 16, v69
	v_and_b32_e32 v69, 0xffff0000, v69
	v_mul_f32_e32 v78, v182, v187
	v_mul_f32_e32 v100, v42, v68
	v_fmac_f32_e32 v78, v42, v80
	v_fmac_f32_e32 v100, v182, v80
	v_mul_f32_e32 v80, v42, v82
	v_mul_f32_e32 v42, v42, v69
	v_fmac_f32_e32 v80, v182, v68
	v_fmac_f32_e32 v42, v182, v82
	v_fmac_f32_e32 v78, v38, v68
	v_fmac_f32_e32 v100, v38, v82
	v_fmac_f32_e32 v80, v38, v69
	v_fmac_f32_e32 v42, v38, v188
	v_add_f32_e32 v79, v27, v79
	v_add_f32_e32 v78, v27, v78
	v_add_f32_e32 v100, v27, v100
	v_add_f32_e32 v80, v27, v80
	v_add_f32_e32 v82, v27, v42
	v_mov_b32_e32 v27, v180
	s_waitcnt lgkmcnt(0)
	s_barrier
	v_lshl_add_u32 v102, v197, 3, 0
	v_ashrrev_i32_e32 v38, 31, v27
	v_add_u32_sdwa v38, v27, v38 dst_sel:DWORD dst_unused:UNUSED_PAD src0_sel:DWORD src1_sel:BYTE_3
	v_ashrrev_i32_e32 v38, 8, v38
	v_mul_i32_i24_e32 v42, 0x100, v38
	v_sub_u32_e32 v42, v27, v42
	v_ashrrev_i32_e32 v68, 4, v42
	v_add_u32_e32 v104, 0x100, v42
	v_mul_i32_i24_e32 v38, 0x220, v38
	v_add_u32_e32 v68, v68, v42
	v_lshrrev_b32_e32 v112, 4, v104
	v_add_lshl_u32 v103, v68, v38, 3
	v_add3_u32 v104, v38, v104, v112
	v_add_u32_e32 v68, s18, v103
	v_lshl_add_u32 v104, v104, 3, s18
	v_lshl_add_u32 v106, v42, 3, 0
	ds_read_b64 v[68:69], v68
	ds_read_b64 v[104:105], v104
	ds_read_b64 v[106:107], v106 offset:4224
	v_add3_u32 v38, v38, v42, v112
	v_add_u32_e32 v103, 0, v103
	v_lshl_add_u32 v38, v38, 3, 0
	v_add_f32_e32 v4, v183, v4
	s_waitcnt lgkmcnt(0)
	v_pk_mul_f32 v[108:109], v[104:105], v[106:107] op_sel:[1,1] op_sel_hi:[0,1]
	v_pk_fma_f32 v[110:111], v[104:105], v[106:107], v[108:109] op_sel_hi:[1,0,1] neg_hi:[0,0,1]
	v_add_f32_e32 v6, v183, v6
	v_pk_add_f32 v[104:105], v[68:69], v[110:111]
	v_pk_add_f32 v[68:69], v[68:69], v[110:111] neg_lo:[0,1] neg_hi:[0,1]
	ds_write_b64 v103, v[104:105] offset:6272
	ds_write_b64 v38, v[68:69] offset:8320
	v_add_u32_e32 v38, 0x200, v27
	v_ashrrev_i32_e32 v42, 31, v38
	v_add_u32_sdwa v42, v38, v42 dst_sel:DWORD dst_unused:UNUSED_PAD src0_sel:DWORD src1_sel:BYTE_3
	v_ashrrev_i32_e32 v42, 8, v42
	v_mul_i32_i24_e32 v68, 0x100, v42
	v_sub_u32_e32 v38, v38, v68
	v_ashrrev_i32_e32 v68, 4, v38
	v_add_u32_e32 v104, 0x100, v38
	v_mul_i32_i24_e32 v42, 0x220, v42
	v_add_u32_e32 v68, v68, v38
	v_lshrrev_b32_e32 v112, 4, v104
	v_add_lshl_u32 v103, v68, v42, 3
	v_add3_u32 v104, v42, v104, v112
	v_add_u32_e32 v68, s18, v103
	v_lshl_add_u32 v104, v104, 3, s18
	v_lshl_add_u32 v106, v38, 3, 0
	ds_read_b64 v[68:69], v68
	ds_read_b64 v[104:105], v104
	ds_read_b64 v[106:107], v106 offset:4224
	v_add3_u32 v38, v42, v38, v112
	v_add_u32_e32 v103, 0, v103
	v_lshl_add_u32 v38, v38, 3, 0
	v_add_f32_e32 v0, v183, v0
	s_waitcnt lgkmcnt(0)
	v_pk_mul_f32 v[108:109], v[104:105], v[106:107] op_sel:[1,1] op_sel_hi:[0,1]
	v_pk_fma_f32 v[110:111], v[104:105], v[106:107], v[108:109] op_sel_hi:[1,0,1] neg_hi:[0,0,1]
	v_fmac_f32_e32 v2, v184, v192
	v_pk_add_f32 v[104:105], v[68:69], v[110:111]
	v_pk_add_f32 v[68:69], v[68:69], v[110:111] neg_lo:[0,1] neg_hi:[0,1]
	ds_write_b64 v103, v[104:105] offset:6272
	ds_write_b64 v38, v[68:69] offset:8320
	v_add_u32_e32 v38, 0x400, v27
	v_ashrrev_i32_e32 v42, 31, v38
	v_add_u32_sdwa v42, v38, v42 dst_sel:DWORD dst_unused:UNUSED_PAD src0_sel:DWORD src1_sel:BYTE_3
	v_ashrrev_i32_e32 v42, 8, v42
	v_mul_i32_i24_e32 v68, 0x100, v42
	v_sub_u32_e32 v38, v38, v68
	v_ashrrev_i32_e32 v68, 4, v38
	v_add_u32_e32 v104, 0x100, v38
	v_mul_i32_i24_e32 v42, 0x220, v42
	v_add_u32_e32 v68, v68, v38
	v_lshrrev_b32_e32 v112, 4, v104
	v_add_lshl_u32 v103, v68, v42, 3
	v_add3_u32 v104, v42, v104, v112
	v_add_u32_e32 v68, s18, v103
	v_lshl_add_u32 v104, v104, 3, s18
	v_lshl_add_u32 v106, v38, 3, 0
	ds_read_b64 v[68:69], v68
	ds_read_b64 v[104:105], v104
	ds_read_b64 v[106:107], v106 offset:4224
	v_add3_u32 v38, v42, v38, v112
	v_add_u32_e32 v103, 0, v103
	v_lshl_add_u32 v38, v38, 3, 0
	v_add_f32_e32 v2, v183, v2
	s_waitcnt lgkmcnt(0)
	v_pk_mul_f32 v[108:109], v[104:105], v[106:107] op_sel:[1,1] op_sel_hi:[0,1]
	v_pk_fma_f32 v[110:111], v[104:105], v[106:107], v[108:109] op_sel_hi:[1,0,1] neg_hi:[0,0,1]
	s_nop 0
	v_pk_add_f32 v[104:105], v[68:69], v[110:111]
	v_pk_add_f32 v[68:69], v[68:69], v[110:111] neg_lo:[0,1] neg_hi:[0,1]
	ds_write_b64 v103, v[104:105] offset:6272
	ds_write_b64 v38, v[68:69] offset:8320
	v_add_u32_e32 v38, 0x600, v27
	v_ashrrev_i32_e32 v42, 31, v38
	v_add_u32_sdwa v42, v38, v42 dst_sel:DWORD dst_unused:UNUSED_PAD src0_sel:DWORD src1_sel:BYTE_3
	v_ashrrev_i32_e32 v42, 8, v42
	v_mul_i32_i24_e32 v68, 0x100, v42
	v_sub_u32_e32 v38, v38, v68
	v_ashrrev_i32_e32 v68, 4, v38
	v_add_u32_e32 v104, 0x100, v38
	v_mul_i32_i24_e32 v42, 0x220, v42
	v_add_u32_e32 v68, v68, v38
	v_lshrrev_b32_e32 v112, 4, v104
	v_add_lshl_u32 v103, v68, v42, 3
	v_add3_u32 v104, v42, v104, v112
	v_add_u32_e32 v68, s18, v103
	v_lshl_add_u32 v104, v104, 3, s18
	v_lshl_add_u32 v106, v38, 3, 0
	ds_read_b64 v[68:69], v68
	ds_read_b64 v[104:105], v104
	ds_read_b64 v[106:107], v106 offset:4224
	v_add3_u32 v38, v42, v38, v112
	v_add_u32_e32 v103, 0, v103
	v_lshl_add_u32 v38, v38, 3, 0
	s_waitcnt lgkmcnt(0)
	v_pk_mul_f32 v[108:109], v[104:105], v[106:107] op_sel:[1,1] op_sel_hi:[0,1]
	v_pk_fma_f32 v[110:111], v[104:105], v[106:107], v[108:109] op_sel_hi:[1,0,1] neg_hi:[0,0,1]
	s_nop 0
	v_pk_add_f32 v[104:105], v[68:69], v[110:111]
	v_pk_add_f32 v[68:69], v[68:69], v[110:111] neg_lo:[0,1] neg_hi:[0,1]
	ds_write_b64 v103, v[104:105] offset:6272
	ds_write_b64 v38, v[68:69] offset:8320
	v_add_u32_e32 v38, 0x800, v27
	v_ashrrev_i32_e32 v42, 31, v38
	v_add_u32_sdwa v42, v38, v42 dst_sel:DWORD dst_unused:UNUSED_PAD src0_sel:DWORD src1_sel:BYTE_3
	v_ashrrev_i32_e32 v42, 8, v42
	v_mul_i32_i24_e32 v68, 0x100, v42
	v_sub_u32_e32 v38, v38, v68
	v_ashrrev_i32_e32 v68, 4, v38
	v_add_u32_e32 v104, 0x100, v38
	v_mul_i32_i24_e32 v42, 0x220, v42
	v_add_u32_e32 v68, v68, v38
	v_lshrrev_b32_e32 v112, 4, v104
	v_add_lshl_u32 v103, v68, v42, 3
	v_add3_u32 v104, v42, v104, v112
	v_add_u32_e32 v68, s18, v103
	v_lshl_add_u32 v104, v104, 3, s18
	v_lshl_add_u32 v106, v38, 3, 0
	ds_read_b64 v[68:69], v68
	ds_read_b64 v[104:105], v104
	ds_read_b64 v[106:107], v106 offset:4224
	v_add3_u32 v38, v42, v38, v112
	v_add_u32_e32 v103, 0, v103
	v_lshl_add_u32 v38, v38, 3, 0
	s_waitcnt lgkmcnt(0)
	v_pk_mul_f32 v[108:109], v[104:105], v[106:107] op_sel:[1,1] op_sel_hi:[0,1]
	v_pk_fma_f32 v[110:111], v[104:105], v[106:107], v[108:109] op_sel_hi:[1,0,1] neg_hi:[0,0,1]
	s_nop 0
	v_pk_add_f32 v[104:105], v[68:69], v[110:111]
	v_pk_add_f32 v[68:69], v[68:69], v[110:111] neg_lo:[0,1] neg_hi:[0,1]
	ds_write_b64 v103, v[104:105] offset:6272
	ds_write_b64 v38, v[68:69] offset:8320
	v_add_u32_e32 v38, 0xa00, v27
	v_ashrrev_i32_e32 v42, 31, v38
	v_add_u32_sdwa v42, v38, v42 dst_sel:DWORD dst_unused:UNUSED_PAD src0_sel:DWORD src1_sel:BYTE_3
	v_ashrrev_i32_e32 v42, 8, v42
	v_mul_i32_i24_e32 v68, 0x100, v42
	v_sub_u32_e32 v38, v38, v68
	v_ashrrev_i32_e32 v68, 4, v38
	v_add_u32_e32 v104, 0x100, v38
	v_mul_i32_i24_e32 v42, 0x220, v42
	v_add_u32_e32 v68, v68, v38
	v_lshrrev_b32_e32 v112, 4, v104
	v_add_lshl_u32 v103, v68, v42, 3
	v_add3_u32 v104, v42, v104, v112
	v_add_u32_e32 v68, s18, v103
	v_lshl_add_u32 v104, v104, 3, s18
	v_lshl_add_u32 v106, v38, 3, 0
	ds_read_b64 v[68:69], v68
	ds_read_b64 v[104:105], v104
	ds_read_b64 v[106:107], v106 offset:4224
	v_add3_u32 v38, v42, v38, v112
	v_add_u32_e32 v103, 0, v103
	v_lshl_add_u32 v38, v38, 3, 0
	s_waitcnt lgkmcnt(0)
	v_pk_mul_f32 v[108:109], v[104:105], v[106:107] op_sel:[1,1] op_sel_hi:[0,1]
	v_pk_fma_f32 v[110:111], v[104:105], v[106:107], v[108:109] op_sel_hi:[1,0,1] neg_hi:[0,0,1]
	s_nop 0
	v_pk_add_f32 v[104:105], v[68:69], v[110:111]
	v_pk_add_f32 v[68:69], v[68:69], v[110:111] neg_lo:[0,1] neg_hi:[0,1]
	ds_write_b64 v103, v[104:105] offset:6272
	ds_write_b64 v38, v[68:69] offset:8320
	v_add_u32_e32 v38, 0xc00, v27
	v_ashrrev_i32_e32 v42, 31, v38
	v_add_u32_sdwa v42, v38, v42 dst_sel:DWORD dst_unused:UNUSED_PAD src0_sel:DWORD src1_sel:BYTE_3
	v_ashrrev_i32_e32 v42, 8, v42
	v_mul_i32_i24_e32 v68, 0x100, v42
	v_sub_u32_e32 v38, v38, v68
	v_ashrrev_i32_e32 v68, 4, v38
	v_add_u32_e32 v104, 0x100, v38
	v_mul_i32_i24_e32 v42, 0x220, v42
	v_add_u32_e32 v68, v68, v38
	v_lshrrev_b32_e32 v112, 4, v104
	v_add_lshl_u32 v103, v68, v42, 3
	v_add3_u32 v104, v42, v104, v112
	v_add_u32_e32 v68, s18, v103
	v_lshl_add_u32 v104, v104, 3, s18
	v_lshl_add_u32 v106, v38, 3, 0
	ds_read_b64 v[68:69], v68
	ds_read_b64 v[104:105], v104
	ds_read_b64 v[106:107], v106 offset:4224
	v_add3_u32 v38, v42, v38, v112
	v_add_u32_e32 v103, 0, v103
	v_lshl_add_u32 v38, v38, 3, 0
	v_add_u32_e32 v27, 0xe00, v27
	s_waitcnt lgkmcnt(0)
	v_pk_mul_f32 v[108:109], v[104:105], v[106:107] op_sel:[1,1] op_sel_hi:[0,1]
	v_pk_fma_f32 v[110:111], v[104:105], v[106:107], v[108:109] op_sel_hi:[1,0,1] neg_hi:[0,0,1]
	s_nop 0
	v_pk_add_f32 v[104:105], v[68:69], v[110:111]
	v_pk_add_f32 v[68:69], v[68:69], v[110:111] neg_lo:[0,1] neg_hi:[0,1]
	ds_write_b64 v103, v[104:105] offset:6272
	ds_write_b64 v38, v[68:69] offset:8320
	v_ashrrev_i32_e32 v38, 31, v27
	v_add_u32_sdwa v38, v27, v38 dst_sel:DWORD dst_unused:UNUSED_PAD src0_sel:DWORD src1_sel:BYTE_3
	v_ashrrev_i32_e32 v38, 8, v38
	v_mul_i32_i24_e32 v42, 0x100, v38
	v_sub_u32_e32 v27, v27, v42
	v_ashrrev_i32_e32 v42, 4, v27
	v_add_u32_e32 v103, 0x100, v27
	v_mul_i32_i24_e32 v38, 0x220, v38
	v_add_u32_e32 v42, v42, v27
	v_lshrrev_b32_e32 v112, 4, v103
	v_add_lshl_u32 v42, v42, v38, 3
	v_add3_u32 v103, v38, v103, v112
	v_add_u32_e32 v68, s18, v42
	v_lshl_add_u32 v103, v103, 3, s18
	ds_read_b64 v[68:69], v68
	ds_read_b64 v[104:105], v103
	v_lshl_add_u32 v103, v27, 3, 0
	ds_read_b64 v[106:107], v103 offset:4224
	v_add_u32_e32 v42, 0, v42
	v_add3_u32 v27, v38, v27, v112
	v_lshl_add_u32 v27, v27, 3, 0
	s_waitcnt lgkmcnt(0)
	v_pk_mul_f32 v[108:109], v[104:105], v[106:107] op_sel:[1,1] op_sel_hi:[0,1]
	v_pk_fma_f32 v[110:111], v[104:105], v[106:107], v[108:109] op_sel_hi:[1,0,1] neg_hi:[0,0,1]
	s_nop 0
	v_pk_add_f32 v[104:105], v[68:69], v[110:111]
	ds_write_b64 v42, v[104:105] offset:6272
	v_pk_add_f32 v[68:69], v[68:69], v[110:111] neg_lo:[0,1] neg_hi:[0,1]
	v_add_u32_e32 v42, v102, v196
	ds_write_b64 v27, v[68:69] offset:8320
	v_add_u32_e32 v27, 0x1880, v42
	s_waitcnt lgkmcnt(0)
	s_barrier
	ds_read2_b64 v[102:105], v27 offset1:1
	v_add_u32_e32 v38, 0x1890, v42
	s_waitcnt lgkmcnt(0)
	v_pk_fma_f32 v[68:69], v[22:23], v[94:95], v[102:103] op_sel_hi:[0,1,1]
	v_pk_mul_f32 v[68:69], v[78:79], v[68:69]
	v_pk_fma_f32 v[78:79], v[22:23], v[96:97], v[104:105] op_sel_hi:[0,1,1]
	ds_read2_b64 v[94:97], v38 offset1:1
	v_pk_mul_f32 v[78:79], v[100:101], v[78:79]
	s_waitcnt lgkmcnt(0)
	v_pk_fma_f32 v[92:93], v[22:23], v[92:93], v[94:95] op_sel_hi:[0,1,1]
	v_pk_mul_f32 v[80:81], v[80:81], v[92:93]
	v_pk_fma_f32 v[92:93], v[22:23], v[98:99], v[96:97] op_sel_hi:[0,1,1]
	v_add_u32_e32 v22, 0xa080, v42
	v_pk_mul_f32 v[82:83], v[82:83], v[92:93]
	ds_read2_b64 v[92:95], v22 offset1:1
	v_add_u32_e32 v42, 0xa090, v42
	s_waitcnt lgkmcnt(0)
	v_pk_fma_f32 v[88:89], v[10:11], v[88:89], v[92:93] op_sel_hi:[0,1,1]
	v_pk_mul_f32 v[88:89], v[4:5], v[88:89]
	v_pk_fma_f32 v[4:5], v[10:11], v[90:91], v[94:95] op_sel_hi:[0,1,1]
	v_pk_mul_f32 v[90:91], v[6:7], v[4:5]
	ds_read2_b64 v[4:7], v42 offset1:1
	s_waitcnt lgkmcnt(0)
	s_barrier
	v_pk_fma_f32 v[4:5], v[10:11], v[84:85], v[4:5] op_sel_hi:[0,1,1]
	v_pk_mul_f32 v[84:85], v[0:1], v[4:5]
	v_pk_fma_f32 v[0:1], v[10:11], v[86:87], v[6:7] op_sel_hi:[0,1,1]
	v_pk_mul_f32 v[86:87], v[2:3], v[0:1]
	v_mov_b32_e32 v0, v180
	ds_write_b64 v8, v[68:69] offset:6272
	ds_write_b64 v195, v[202:203] offset:8320
	ds_write_b64 v8, v[78:79] offset:6280
	ds_write_b64 v195, v[202:203] offset:8328
	ds_write_b64 v8, v[80:81] offset:6288
	ds_write_b64 v195, v[202:203] offset:8336
	ds_write_b64 v8, v[82:83] offset:6296
	ds_write_b64 v195, v[202:203] offset:8344
	ds_write_b64 v8, v[88:89] offset:41088
	ds_write_b64 v195, v[202:203] offset:43136
	ds_write_b64 v8, v[90:91] offset:41096
	ds_write_b64 v195, v[202:203] offset:43144
	ds_write_b64 v8, v[84:85] offset:41104
	ds_write_b64 v195, v[202:203] offset:43152
	ds_write_b64 v8, v[86:87] offset:41112
	ds_write_b64 v195, v[202:203] offset:43160
	s_waitcnt lgkmcnt(0)
	s_barrier
	s_nop 0
	v_cmp_gt_i32_e32 vcc, s16, v0
	s_and_saveexec_b64 s[2:3], vcc
	s_cbranch_execz .LBB0_499
	v_ashrrev_i32_e32 v1, 31, v0
	v_lshrrev_b32_e32 v1, 27, v1
	v_add_u32_e32 v1, v0, v1
	v_lshrrev_b32_e32 v2, 5, v1
	v_and_b32_e32 v1, 0xffffffe0, v1
	v_sub_u32_e32 v8, v0, v1
	v_mul_lo_u32 v10, v2, s17
	v_ashrrev_i32_e32 v1, 4, v8
	v_add_u32_e32 v0, 0, v10
	v_lshlrev_b32_e32 v124, 3, v8
	v_lshlrev_b32_e32 v1, 3, v1
	v_add3_u32 v112, v0, v124, v1
	v_add_u32_e32 v96, 0x1800, v112
	v_add_u32_e32 v108, 0x2000, v112
	ds_read2_b64 v[0:3], v96 offset0:16 offset1:50
	ds_read2_b64 v[4:7], v96 offset0:84 offset1:118
	ds_read2_b64 v[92:95], v96 offset0:152 offset1:186
	ds_read2_b64 v[96:99], v96 offset0:220 offset1:254
	ds_read2_b64 v[100:103], v108 offset0:32 offset1:66
	ds_read2_b64 v[104:107], v108 offset0:100 offset1:134
	ds_read2_b64 v[108:111], v108 offset0:168 offset1:202
	v_add_u32_e32 v112, 0x2400, v112
	ds_read2_b64 v[112:115], v112 offset0:108 offset1:142
	s_waitcnt lgkmcnt(3)
	v_pk_add_f32 v[116:117], v[0:1], v[100:101]
	v_pk_add_f32 v[0:1], v[0:1], v[100:101] neg_lo:[0,1] neg_hi:[0,1]
	s_waitcnt lgkmcnt(1)
	v_pk_add_f32 v[100:101], v[92:93], v[108:109]
	v_pk_add_f32 v[92:93], v[92:93], v[108:109] neg_lo:[0,1] neg_hi:[0,1]
	s_mov_b32 s31, s28
	v_xor_b32_e32 v109, 0x80000000, v92
	v_mov_b32_e32 v108, v93
	v_pk_add_f32 v[118:119], v[0:1], v[108:109]
	v_pk_add_f32 v[0:1], v[0:1], v[108:109] neg_lo:[0,1] neg_hi:[0,1]
	v_pk_add_f32 v[108:109], v[2:3], v[102:103]
	v_pk_add_f32 v[2:3], v[2:3], v[102:103] neg_lo:[0,1] neg_hi:[0,1]
	v_pk_add_f32 v[102:103], v[94:95], v[110:111]
	v_pk_add_f32 v[94:95], v[94:95], v[110:111] neg_lo:[0,1] neg_hi:[0,1]
	v_pk_add_f32 v[92:93], v[116:117], v[100:101]
	v_xor_b32_e32 v111, 0x80000000, v94
	v_mov_b32_e32 v110, v95
	v_pk_add_f32 v[94:95], v[108:109], v[102:103]
	v_pk_add_f32 v[102:103], v[108:109], v[102:103] neg_lo:[0,1] neg_hi:[0,1]
	v_pk_add_f32 v[108:109], v[4:5], v[104:105]
	v_pk_add_f32 v[4:5], v[4:5], v[104:105] neg_lo:[0,1] neg_hi:[0,1]
	s_waitcnt lgkmcnt(0)
	v_pk_add_f32 v[104:105], v[96:97], v[112:113]
	v_pk_add_f32 v[96:97], v[96:97], v[112:113] neg_lo:[0,1] neg_hi:[0,1]
	v_pk_add_f32 v[100:101], v[116:117], v[100:101] neg_lo:[0,1] neg_hi:[0,1]
	v_pk_add_f32 v[116:117], v[2:3], v[110:111]
	v_pk_add_f32 v[2:3], v[2:3], v[110:111] neg_lo:[0,1] neg_hi:[0,1]
	v_xor_b32_e32 v111, 0x80000000, v96
	v_mov_b32_e32 v110, v97
	v_pk_add_f32 v[96:97], v[108:109], v[104:105]
	v_pk_add_f32 v[104:105], v[108:109], v[104:105] neg_lo:[0,1] neg_hi:[0,1]
	v_pk_add_f32 v[108:109], v[6:7], v[106:107]
	v_pk_add_f32 v[6:7], v[6:7], v[106:107] neg_lo:[0,1] neg_hi:[0,1]
	v_pk_add_f32 v[106:107], v[98:99], v[114:115]
	v_pk_add_f32 v[98:99], v[98:99], v[114:115] neg_lo:[0,1] neg_hi:[0,1]
	v_pk_add_f32 v[112:113], v[4:5], v[110:111]
	v_pk_add_f32 v[4:5], v[4:5], v[110:111] neg_lo:[0,1] neg_hi:[0,1]
	v_xor_b32_e32 v111, 0x80000000, v98
	v_mov_b32_e32 v110, v99
	v_pk_add_f32 v[98:99], v[108:109], v[106:107]
	v_pk_add_f32 v[106:107], v[108:109], v[106:107] neg_lo:[0,1] neg_hi:[0,1]
	v_pk_mul_f32 v[108:109], v[116:117], s[14:15] op_sel_hi:[1,0]
	v_pk_add_f32 v[114:115], v[6:7], v[110:111]
	v_pk_add_f32 v[6:7], v[6:7], v[110:111] neg_lo:[0,1] neg_hi:[0,1]
	v_pk_fma_f32 v[110:111], v[116:117], s[22:23], v[108:109] op_sel:[0,0,1] op_sel_hi:[1,0,0] neg_hi:[0,0,1]
	s_mov_b32 s29, s14
	v_pk_mul_f32 v[108:109], v[102:103], s[24:25] op_sel_hi:[1,0]
	v_add_u32_e32 v10, s18, v10
	v_pk_fma_f32 v[116:117], v[102:103], s[24:25], v[108:109] op_sel:[0,0,1] op_sel_hi:[1,0,0] neg_hi:[0,0,1]
	v_pk_mul_f32 v[108:109], v[2:3], s[22:23] op_sel_hi:[1,0]
	v_pk_fma_f32 v[120:121], v[2:3], s[14:15], v[108:109] op_sel:[0,0,1] op_sel_hi:[1,0,0] neg_hi:[0,0,1]
	v_lshlrev_b32_e32 v8, 7, v8
	v_pk_mul_f32 v[2:3], v[112:113], s[24:25] op_sel_hi:[1,0]
	v_add3_u32 v8, v10, v8, v124
	v_pk_fma_f32 v[108:109], v[112:113], s[24:25], v[2:3] op_sel:[0,0,1] op_sel_hi:[1,0,0] neg_hi:[0,0,1]
	s_nop 0
	v_pk_fma_f32 v[2:3], v[104:105], 0, v[104:105] op_sel:[0,0,1] op_sel_hi:[1,0,0] neg_hi:[0,0,1]
	s_nop 0
	v_pk_mul_f32 v[104:105], v[4:5], s[26:27] op_sel_hi:[1,0]
	s_nop 0
	v_pk_fma_f32 v[112:113], v[4:5], s[26:27], v[104:105] op_sel:[0,0,1] op_sel_hi:[1,0,0] neg_lo:[0,0,1]
	v_pk_mul_f32 v[104:105], v[114:115], s[22:23] op_sel_hi:[1,0]
	v_pk_fma_f32 v[122:123], v[114:115], s[14:15], v[104:105] op_sel:[0,0,1] op_sel_hi:[1,0,0] neg_hi:[0,0,1]
	v_pk_add_f32 v[4:5], v[0:1], v[112:113]
	v_pk_mul_f32 v[104:105], v[106:107], s[26:27] op_sel_hi:[1,0]
	v_pk_add_f32 v[0:1], v[0:1], v[112:113] neg_lo:[0,1] neg_hi:[0,1]
	v_pk_fma_f32 v[114:115], v[106:107], s[26:27], v[104:105] op_sel:[0,0,1] op_sel_hi:[1,0,0] neg_lo:[0,0,1]
	s_nop 0
	v_pk_mul_f32 v[104:105], v[6:7], s[30:31] op_sel:[1,0]
	v_pk_add_f32 v[102:103], v[116:117], v[114:115] neg_lo:[0,1] neg_hi:[0,1]
	v_pk_fma_f32 v[6:7], v[6:7], s[28:29], v[104:105] op_sel_hi:[0,1,1]
	v_pk_add_f32 v[104:105], v[92:93], v[96:97]
	v_pk_add_f32 v[92:93], v[92:93], v[96:97] neg_lo:[0,1] neg_hi:[0,1]
	v_pk_add_f32 v[96:97], v[94:95], v[98:99]
	v_pk_add_f32 v[94:95], v[94:95], v[98:99] neg_lo:[0,1] neg_hi:[0,1]
	s_nop 0
	v_xor_b32_e32 v99, 0x80000000, v94
	v_mov_b32_e32 v98, v95
	v_pk_add_f32 v[94:95], v[104:105], v[96:97]
	v_pk_add_f32 v[106:107], v[92:93], v[98:99]
	v_pk_add_f32 v[96:97], v[104:105], v[96:97] neg_lo:[0,1] neg_hi:[0,1]
	v_pk_add_f32 v[92:93], v[92:93], v[98:99] neg_lo:[0,1] neg_hi:[0,1]
	v_pk_add_f32 v[98:99], v[118:119], v[108:109]
	v_pk_add_f32 v[104:105], v[118:119], v[108:109] neg_lo:[0,1] neg_hi:[0,1]
	v_pk_add_f32 v[108:109], v[110:111], v[122:123]
	v_pk_add_f32 v[110:111], v[110:111], v[122:123] neg_lo:[0,1] neg_hi:[0,1]
	s_nop 0
	v_xor_b32_e32 v119, 0x80000000, v110
	v_mov_b32_e32 v118, v111
	v_pk_add_f32 v[110:111], v[98:99], v[108:109]
	v_pk_add_f32 v[98:99], v[98:99], v[108:109] neg_lo:[0,1] neg_hi:[0,1]
	v_pk_add_f32 v[108:109], v[100:101], v[2:3]
	v_pk_add_f32 v[2:3], v[100:101], v[2:3] neg_lo:[0,1] neg_hi:[0,1]
	v_pk_add_f32 v[100:101], v[116:117], v[114:115]
	v_xor_b32_e32 v115, 0x80000000, v102
	v_mov_b32_e32 v114, v103
	v_pk_add_f32 v[102:103], v[108:109], v[100:101]
	v_pk_add_f32 v[100:101], v[108:109], v[100:101] neg_lo:[0,1] neg_hi:[0,1]
	v_pk_add_f32 v[108:109], v[120:121], v[6:7]
	v_pk_add_f32 v[6:7], v[120:121], v[6:7] neg_lo:[0,1] neg_hi:[0,1]
	v_pk_add_f32 v[122:123], v[104:105], v[118:119]
	v_xor_b32_e32 v113, 0x80000000, v6
	v_mov_b32_e32 v112, v7
	v_pk_add_f32 v[104:105], v[104:105], v[118:119] neg_lo:[0,1] neg_hi:[0,1]
	v_pk_add_f32 v[116:117], v[2:3], v[114:115]
	v_pk_add_f32 v[2:3], v[2:3], v[114:115] neg_lo:[0,1] neg_hi:[0,1]
	v_pk_add_f32 v[6:7], v[4:5], v[108:109]
	v_pk_add_f32 v[114:115], v[0:1], v[112:113]
	v_pk_add_f32 v[4:5], v[4:5], v[108:109] neg_lo:[0,1] neg_hi:[0,1]
	v_pk_add_f32 v[0:1], v[0:1], v[112:113] neg_lo:[0,1] neg_hi:[0,1]
	ds_write2_b64 v8, v[94:95], v[110:111] offset1:1
	ds_write2_b64 v8, v[102:103], v[6:7] offset0:2 offset1:3
	ds_write2_b64 v8, v[106:107], v[122:123] offset0:4 offset1:5
	ds_write2_b64 v8, v[116:117], v[114:115] offset0:6 offset1:7
	ds_write2_b64 v8, v[96:97], v[98:99] offset0:8 offset1:9
	ds_write2_b64 v8, v[100:101], v[4:5] offset0:10 offset1:11
	ds_write2_b64 v8, v[92:93], v[104:105] offset0:12 offset1:13
	ds_write2_b64 v8, v[2:3], v[0:1] offset0:14 offset1:15
.LBB0_499:
	s_or_b64 exec, exec, s[2:3]
	v_mov_b32_e32 v0, v180
	s_waitcnt lgkmcnt(0)
	s_barrier
	s_nop 0
	v_cmp_gt_i32_e32 vcc, s16, v0
	s_and_saveexec_b64 s[2:3], vcc
	s_cbranch_execz .LBB0_501
	v_ashrrev_i32_e32 v1, 31, v0
	v_lshrrev_b32_e32 v1, 27, v1
	v_add_u32_e32 v1, v0, v1
	v_lshrrev_b32_e32 v2, 5, v1
	v_and_b32_e32 v1, 0xffffffe0, v1
	v_sub_u32_e32 v0, v0, v1
	v_lshrrev_b16_sdwa v1, v175, sext(v0) dst_sel:DWORD dst_unused:UNUSED_PAD src0_sel:DWORD src1_sel:BYTE_0
	v_and_b32_e32 v1, 15, v1
	v_add_u16_e32 v1, v0, v1
	v_ashrrev_i16_sdwa v8, v176, sext(v1) dst_sel:DWORD dst_unused:UNUSED_PAD src0_sel:DWORD src1_sel:BYTE_0
	v_and_b32_e32 v1, 0xf0, v1
	v_sub_u16_e32 v92, v0, v1
	v_mul_lo_u32 v10, v2, s17
	v_lshlrev_b32_e32 v2, 3, v0
	v_ashrrev_i32_e32 v0, 4, v0
	v_add_u32_e32 v1, s18, v10
	v_lshlrev_b32_e32 v0, 3, v0
	v_bfe_i32 v118, v92, 0, 8
	v_add3_u32 v4, v1, v2, v0
	v_mad_i32_i24 v119, v118, s19, 0
	ds_read2_b64 v[0:3], v4 offset1:34
	ds_read2_b64 v[96:99], v4 offset0:68 offset1:102
	ds_read2_b64 v[104:107], v4 offset0:136 offset1:170
	ds_read2_b64 v[108:111], v4 offset0:204 offset1:238
	v_add_u32_e32 v4, 0x800, v4
	v_add_u32_e32 v92, 0x808, v119
	ds_read2_b64 v[112:115], v4 offset0:16 offset1:50
	ds_read2_b64 v[120:123], v4 offset0:84 offset1:118
	ds_read2_b64 v[124:127], v4 offset0:152 offset1:186
	ds_read2_b64 v[4:7], v4 offset0:220 offset1:254
	ds_read2_b64 v[100:103], v92 offset1:1
	s_mov_b32 s31, s28
	s_mov_b32 s29, s14
	v_bfe_i32 v8, v8, 0, 16
	v_lshl_add_u32 v8, v8, 8, v118
	s_waitcnt lgkmcnt(0)
	v_pk_mul_f32 v[92:93], v[2:3], v[100:101] op_sel:[1,1] op_sel_hi:[1,0]
	v_add_u32_e32 v10, 0, v10
	v_pk_fma_f32 v[94:95], v[2:3], v[100:101], v[92:93] op_sel_hi:[0,1,1] neg_lo:[0,0,1]
	v_pk_mul_f32 v[2:3], v[96:97], v[102:103] op_sel:[1,1] op_sel_hi:[1,0]
	s_nop 0
	v_pk_fma_f32 v[92:93], v[96:97], v[102:103], v[2:3] op_sel_hi:[0,1,1] neg_lo:[0,0,1]
	v_add_u32_e32 v2, 0x818, v119
	ds_read2_b64 v[128:131], v2 offset1:1
	s_waitcnt lgkmcnt(0)
	v_pk_mul_f32 v[96:97], v[98:99], v[128:129] op_sel:[1,1] op_sel_hi:[1,0]
	s_nop 0
	v_pk_fma_f32 v[2:3], v[98:99], v[128:129], v[96:97] op_sel_hi:[0,1,1] neg_lo:[0,0,1]
	v_pk_mul_f32 v[96:97], v[104:105], v[130:131] op_sel:[1,1] op_sel_hi:[1,0]
	s_nop 0
	v_pk_fma_f32 v[102:103], v[104:105], v[130:131], v[96:97] op_sel_hi:[0,1,1] neg_lo:[0,0,1]
	v_add_u32_e32 v96, 0x828, v119
	ds_read2_b64 v[128:131], v96 offset1:1
	s_waitcnt lgkmcnt(0)
	v_pk_mul_f32 v[96:97], v[106:107], v[128:129] op_sel:[1,1] op_sel_hi:[1,0]
	s_nop 0
	v_pk_fma_f32 v[100:101], v[106:107], v[128:129], v[96:97] op_sel_hi:[0,1,1] neg_lo:[0,0,1]
	v_pk_mul_f32 v[96:97], v[108:109], v[130:131] op_sel:[1,1] op_sel_hi:[1,0]
	s_nop 0
	v_pk_fma_f32 v[98:99], v[108:109], v[130:131], v[96:97] op_sel_hi:[0,1,1] neg_lo:[0,0,1]
	v_add_u32_e32 v96, 0x838, v119
	ds_read2_b64 v[104:107], v96 offset1:1
	s_waitcnt lgkmcnt(0)
	v_pk_mul_f32 v[108:109], v[110:111], v[104:105] op_sel:[1,1] op_sel_hi:[1,0]
	s_nop 0
	v_pk_fma_f32 v[96:97], v[110:111], v[104:105], v[108:109] op_sel_hi:[0,1,1] neg_lo:[0,0,1]
	v_pk_mul_f32 v[104:105], v[112:113], v[106:107] op_sel:[1,1] op_sel_hi:[1,0]
	s_nop 0
	v_pk_fma_f32 v[110:111], v[112:113], v[106:107], v[104:105] op_sel_hi:[0,1,1] neg_lo:[0,0,1]
	v_add_u32_e32 v104, 0x848, v119
	ds_read2_b64 v[128:131], v104 offset1:1
	s_waitcnt lgkmcnt(0)
	v_pk_mul_f32 v[104:105], v[114:115], v[128:129] op_sel:[1,1] op_sel_hi:[1,0]
	s_nop 0
	v_pk_fma_f32 v[108:109], v[114:115], v[128:129], v[104:105] op_sel_hi:[0,1,1] neg_lo:[0,0,1]
	v_pk_mul_f32 v[104:105], v[120:121], v[130:131] op_sel:[1,1] op_sel_hi:[1,0]
	s_nop 0
	v_pk_fma_f32 v[106:107], v[120:121], v[130:131], v[104:105] op_sel_hi:[0,1,1] neg_lo:[0,0,1]
	v_add_u32_e32 v104, 0x858, v119
	ds_read2_b64 v[112:115], v104 offset1:1
	s_waitcnt lgkmcnt(0)
	v_pk_mul_f32 v[116:117], v[122:123], v[112:113] op_sel:[1,1] op_sel_hi:[1,0]
	s_nop 0
	v_pk_fma_f32 v[104:105], v[122:123], v[112:113], v[116:117] op_sel_hi:[0,1,1] neg_lo:[0,0,1]
	v_pk_mul_f32 v[112:113], v[124:125], v[114:115] op_sel:[1,1] op_sel_hi:[1,0]
	s_nop 0
	v_pk_fma_f32 v[116:117], v[124:125], v[114:115], v[112:113] op_sel_hi:[0,1,1] neg_lo:[0,0,1]
	v_add_u32_e32 v112, 0x868, v119
	ds_read2_b64 v[120:123], v112 offset1:1
	s_waitcnt lgkmcnt(0)
	v_pk_mul_f32 v[112:113], v[126:127], v[120:121] op_sel:[1,1] op_sel_hi:[1,0]
	s_nop 0
	v_pk_fma_f32 v[114:115], v[126:127], v[120:121], v[112:113] op_sel_hi:[0,1,1] neg_lo:[0,0,1]
	v_pk_mul_f32 v[120:121], v[4:5], v[122:123] op_sel:[1,1] op_sel_hi:[1,0]
	v_pk_fma_f32 v[112:113], v[4:5], v[122:123], v[120:121] op_sel_hi:[0,1,1] neg_lo:[0,0,1]
	ds_read_b64 v[4:5], v119 offset:2168
	s_waitcnt lgkmcnt(0)
	v_pk_mul_f32 v[120:121], v[6:7], v[4:5] op_sel:[1,1] op_sel_hi:[1,0]
	s_nop 0
	v_pk_fma_f32 v[122:123], v[6:7], v[4:5], v[120:121] op_sel_hi:[0,1,1] neg_lo:[0,0,1]
	v_pk_add_f32 v[4:5], v[0:1], v[110:111]
	v_pk_add_f32 v[6:7], v[102:103], v[116:117]
	v_pk_add_f32 v[102:103], v[102:103], v[116:117] neg_lo:[0,1] neg_hi:[0,1]
	v_pk_add_f32 v[0:1], v[0:1], v[110:111] neg_lo:[0,1] neg_hi:[0,1]
	v_xor_b32_e32 v111, 0x80000000, v102
	v_mov_b32_e32 v110, v103
	v_pk_add_f32 v[102:103], v[4:5], v[6:7]
	v_pk_add_f32 v[4:5], v[4:5], v[6:7] neg_lo:[0,1] neg_hi:[0,1]
	v_pk_add_f32 v[6:7], v[94:95], v[108:109]
	v_pk_add_f32 v[94:95], v[94:95], v[108:109] neg_lo:[0,1] neg_hi:[0,1]
	v_pk_add_f32 v[108:109], v[100:101], v[114:115]
	v_pk_add_f32 v[100:101], v[100:101], v[114:115] neg_lo:[0,1] neg_hi:[0,1]
	v_pk_add_f32 v[116:117], v[0:1], v[110:111]
	v_pk_add_f32 v[0:1], v[0:1], v[110:111] neg_lo:[0,1] neg_hi:[0,1]
	v_xor_b32_e32 v111, 0x80000000, v100
	v_mov_b32_e32 v110, v101
	v_pk_add_f32 v[100:101], v[6:7], v[108:109]
	v_pk_add_f32 v[6:7], v[6:7], v[108:109] neg_lo:[0,1] neg_hi:[0,1]
	v_pk_add_f32 v[108:109], v[92:93], v[106:107]
	v_pk_add_f32 v[92:93], v[92:93], v[106:107] neg_lo:[0,1] neg_hi:[0,1]
	v_pk_add_f32 v[106:107], v[98:99], v[112:113]
	v_pk_add_f32 v[98:99], v[98:99], v[112:113] neg_lo:[0,1] neg_hi:[0,1]
	v_pk_add_f32 v[114:115], v[94:95], v[110:111]
	v_pk_add_f32 v[94:95], v[94:95], v[110:111] neg_lo:[0,1] neg_hi:[0,1]
	v_xor_b32_e32 v111, 0x80000000, v98
	v_mov_b32_e32 v110, v99
	v_pk_add_f32 v[98:99], v[108:109], v[106:107]
	v_pk_add_f32 v[106:107], v[108:109], v[106:107] neg_lo:[0,1] neg_hi:[0,1]
	v_pk_add_f32 v[108:109], v[2:3], v[104:105]
	v_pk_add_f32 v[2:3], v[2:3], v[104:105] neg_lo:[0,1] neg_hi:[0,1]
	v_pk_add_f32 v[104:105], v[96:97], v[122:123]
	v_pk_add_f32 v[96:97], v[96:97], v[122:123] neg_lo:[0,1] neg_hi:[0,1]
	v_pk_add_f32 v[112:113], v[92:93], v[110:111]
	v_pk_add_f32 v[92:93], v[92:93], v[110:111] neg_lo:[0,1] neg_hi:[0,1]
	v_xor_b32_e32 v111, 0x80000000, v96
	v_mov_b32_e32 v110, v97
	v_pk_add_f32 v[96:97], v[108:109], v[104:105]
	v_pk_add_f32 v[104:105], v[108:109], v[104:105] neg_lo:[0,1] neg_hi:[0,1]
	v_pk_mul_f32 v[108:109], v[114:115], s[14:15] op_sel_hi:[1,0]
	v_pk_add_f32 v[120:121], v[2:3], v[110:111]
	v_pk_add_f32 v[2:3], v[2:3], v[110:111] neg_lo:[0,1] neg_hi:[0,1]
	v_pk_fma_f32 v[110:111], v[114:115], s[22:23], v[108:109] op_sel:[0,0,1] op_sel_hi:[1,0,0] neg_hi:[0,0,1]
	s_nop 0
	v_pk_mul_f32 v[108:109], v[6:7], s[24:25] op_sel_hi:[1,0]
	s_nop 0
	v_pk_fma_f32 v[114:115], v[6:7], s[24:25], v[108:109] op_sel:[0,0,1] op_sel_hi:[1,0,0] neg_hi:[0,0,1]
	v_pk_mul_f32 v[108:109], v[94:95], s[22:23] op_sel_hi:[1,0]
	v_pk_fma_f32 v[122:123], v[94:95], s[14:15], v[108:109] op_sel:[0,0,1] op_sel_hi:[1,0,0] neg_hi:[0,0,1]
	s_nop 0
	v_pk_mul_f32 v[94:95], v[112:113], s[24:25] op_sel_hi:[1,0]
	s_nop 0
	v_pk_fma_f32 v[108:109], v[112:113], s[24:25], v[94:95] op_sel:[0,0,1] op_sel_hi:[1,0,0] neg_hi:[0,0,1]
	s_nop 0
	v_pk_fma_f32 v[94:95], v[106:107], 0, v[106:107] op_sel:[0,0,1] op_sel_hi:[1,0,0] neg_hi:[0,0,1]
	s_nop 0
	v_pk_mul_f32 v[106:107], v[92:93], s[26:27] op_sel_hi:[1,0]
	s_nop 0
	v_pk_fma_f32 v[112:113], v[92:93], s[26:27], v[106:107] op_sel:[0,0,1] op_sel_hi:[1,0,0] neg_lo:[0,0,1]
	v_pk_mul_f32 v[106:107], v[120:121], s[22:23] op_sel_hi:[1,0]
	v_pk_fma_f32 v[124:125], v[120:121], s[14:15], v[106:107] op_sel:[0,0,1] op_sel_hi:[1,0,0] neg_hi:[0,0,1]
	v_pk_add_f32 v[92:93], v[0:1], v[112:113]
	v_pk_mul_f32 v[106:107], v[104:105], s[26:27] op_sel_hi:[1,0]
	v_pk_add_f32 v[0:1], v[0:1], v[112:113] neg_lo:[0,1] neg_hi:[0,1]
	v_pk_fma_f32 v[120:121], v[104:105], s[26:27], v[106:107] op_sel:[0,0,1] op_sel_hi:[1,0,0] neg_lo:[0,0,1]
	s_nop 0
	v_pk_mul_f32 v[104:105], v[2:3], s[30:31] op_sel:[1,0]
	v_pk_add_f32 v[6:7], v[114:115], v[120:121]
	v_pk_fma_f32 v[2:3], v[2:3], s[28:29], v[104:105] op_sel_hi:[0,1,1]
	v_pk_add_f32 v[104:105], v[102:103], v[98:99]
	v_pk_add_f32 v[98:99], v[102:103], v[98:99] neg_lo:[0,1] neg_hi:[0,1]
	v_pk_add_f32 v[102:103], v[100:101], v[96:97]
	v_pk_add_f32 v[96:97], v[100:101], v[96:97] neg_lo:[0,1] neg_hi:[0,1]
	s_nop 0
	v_xor_b32_e32 v101, 0x80000000, v96
	v_mov_b32_e32 v100, v97
	v_pk_add_f32 v[96:97], v[104:105], v[102:103]
	v_pk_add_f32 v[106:107], v[98:99], v[100:101]
	v_pk_add_f32 v[102:103], v[104:105], v[102:103] neg_lo:[0,1] neg_hi:[0,1]
	v_pk_add_f32 v[98:99], v[98:99], v[100:101] neg_lo:[0,1] neg_hi:[0,1]
	v_pk_add_f32 v[100:101], v[116:117], v[108:109]
	v_pk_add_f32 v[104:105], v[116:117], v[108:109] neg_lo:[0,1] neg_hi:[0,1]
	v_pk_add_f32 v[108:109], v[110:111], v[124:125]
	v_pk_add_f32 v[110:111], v[110:111], v[124:125] neg_lo:[0,1] neg_hi:[0,1]
	s_nop 0
	v_xor_b32_e32 v117, 0x80000000, v110
	v_mov_b32_e32 v116, v111
	v_pk_add_f32 v[110:111], v[100:101], v[108:109]
	v_pk_add_f32 v[100:101], v[100:101], v[108:109] neg_lo:[0,1] neg_hi:[0,1]
	v_pk_add_f32 v[108:109], v[4:5], v[94:95]
	v_pk_add_f32 v[4:5], v[4:5], v[94:95] neg_lo:[0,1] neg_hi:[0,1]
	v_pk_add_f32 v[94:95], v[114:115], v[120:121] neg_lo:[0,1] neg_hi:[0,1]
	v_pk_add_f32 v[124:125], v[104:105], v[116:117]
	v_xor_b32_e32 v115, 0x80000000, v94
	v_mov_b32_e32 v114, v95
	v_pk_add_f32 v[94:95], v[108:109], v[6:7]
	v_pk_add_f32 v[6:7], v[108:109], v[6:7] neg_lo:[0,1] neg_hi:[0,1]
	v_pk_add_f32 v[108:109], v[122:123], v[2:3]
	v_pk_add_f32 v[2:3], v[122:123], v[2:3] neg_lo:[0,1] neg_hi:[0,1]
	v_pk_add_f32 v[104:105], v[104:105], v[116:117] neg_lo:[0,1] neg_hi:[0,1]
	v_xor_b32_e32 v113, 0x80000000, v2
	v_mov_b32_e32 v112, v3
	v_pk_add_f32 v[2:3], v[92:93], v[108:109]
	v_pk_add_f32 v[92:93], v[92:93], v[108:109] neg_lo:[0,1] neg_hi:[0,1]
	v_lshlrev_b32_e32 v108, 3, v8
	v_ashrrev_i32_e32 v8, 4, v8
	v_lshlrev_b32_e32 v8, 3, v8
	v_add3_u32 v8, v10, v108, v8
	v_add_u32_e32 v10, 0x1800, v8
	v_pk_add_f32 v[116:117], v[4:5], v[114:115]
	v_pk_add_f32 v[4:5], v[4:5], v[114:115] neg_lo:[0,1] neg_hi:[0,1]
	v_pk_add_f32 v[114:115], v[0:1], v[112:113]
	v_pk_add_f32 v[0:1], v[0:1], v[112:113] neg_lo:[0,1] neg_hi:[0,1]
	ds_write2_b64 v10, v[96:97], v[110:111] offset0:16 offset1:33
	ds_write2_b64 v10, v[94:95], v[2:3] offset0:50 offset1:67
	ds_write2_b64 v10, v[106:107], v[124:125] offset0:84 offset1:101
	ds_write2_b64 v10, v[116:117], v[114:115] offset0:118 offset1:135
	ds_write2_b64 v10, v[102:103], v[100:101] offset0:152 offset1:169
	ds_write2_b64 v10, v[6:7], v[92:93] offset0:186 offset1:203
	ds_write2_b64 v10, v[98:99], v[104:105] offset0:220 offset1:237
	v_add_u32_e32 v2, 0x1c00, v8
	ds_write2_b64 v2, v[4:5], v[0:1] offset0:126 offset1:143
.LBB0_501:
	s_or_b64 exec, exec, s[2:3]
	v_mov_b32_e32 v8, v180
	s_waitcnt lgkmcnt(0)
	s_barrier
	s_nop 0
	v_ashrrev_i32_e32 v0, 31, v8
	v_add_u32_sdwa v0, v8, v0 dst_sel:DWORD dst_unused:UNUSED_PAD src0_sel:DWORD src1_sel:BYTE_3
	v_ashrrev_i32_e32 v0, 8, v0
	v_mul_i32_i24_e32 v1, 0x100, v0
	v_sub_u32_e32 v1, v8, v1
	v_add_u32_e32 v7, 0x100, v1
	v_mul_i32_i24_e32 v6, 0x220, v0
	v_ashrrev_i32_e32 v0, 4, v1
	v_lshrrev_b32_e32 v10, 4, v7
	v_add_u32_e32 v4, v0, v1
	v_add3_u32 v0, v6, v1, v10
	v_lshl_add_u32 v0, v0, 3, 0
	v_lshl_add_u32 v2, v1, 3, 0
	ds_read_b64 v[0:1], v0 offset:8320
	ds_read_b64 v[2:3], v2 offset:4224
	v_add_lshl_u32 v94, v4, v6, 3
	v_add_u32_e32 v4, 0, v94
	ds_read_b64 v[4:5], v4 offset:6272
	v_add3_u32 v10, v6, v7, v10
	s_waitcnt lgkmcnt(1)
	v_pk_mul_f32 v[6:7], v[0:1], v[2:3] op_sel:[1,1] op_sel_hi:[1,0]
	s_nop 0
	v_pk_fma_f32 v[92:93], v[0:1], v[2:3], v[6:7] op_sel_hi:[0,1,1] neg_lo:[0,0,1]
	s_waitcnt lgkmcnt(0)
	v_pk_add_f32 v[0:1], v[4:5], v[92:93]
	v_add_u32_e32 v2, s18, v94
	ds_write_b64 v2, v[0:1]
	v_pk_add_f32 v[0:1], v[4:5], v[92:93] neg_lo:[0,1] neg_hi:[0,1]
	v_lshl_add_u32 v2, v10, 3, s18
	ds_write_b64 v2, v[0:1]
	v_add_u32_e32 v0, 0x200, v8
	v_ashrrev_i32_e32 v1, 31, v0
	v_add_u32_sdwa v1, v0, v1 dst_sel:DWORD dst_unused:UNUSED_PAD src0_sel:DWORD src1_sel:BYTE_3
	v_ashrrev_i32_e32 v1, 8, v1
	v_mul_i32_i24_e32 v2, 0x100, v1
	v_sub_u32_e32 v0, v0, v2
	v_add_u32_e32 v7, 0x100, v0
	v_mul_i32_i24_e32 v6, 0x220, v1
	v_ashrrev_i32_e32 v1, 4, v0
	v_lshrrev_b32_e32 v10, 4, v7
	v_add_u32_e32 v4, v1, v0
	v_add3_u32 v1, v6, v0, v10
	v_lshl_add_u32 v1, v1, 3, 0
	v_lshl_add_u32 v2, v0, 3, 0
	ds_read_b64 v[0:1], v1 offset:8320
	ds_read_b64 v[2:3], v2 offset:4224
	v_add_lshl_u32 v94, v4, v6, 3
	v_add_u32_e32 v4, 0, v94
	ds_read_b64 v[4:5], v4 offset:6272
	v_add3_u32 v10, v6, v7, v10
	s_waitcnt lgkmcnt(1)
	v_pk_mul_f32 v[6:7], v[0:1], v[2:3] op_sel:[1,1] op_sel_hi:[1,0]
	s_nop 0
	v_pk_fma_f32 v[92:93], v[0:1], v[2:3], v[6:7] op_sel_hi:[0,1,1] neg_lo:[0,0,1]
	s_waitcnt lgkmcnt(0)
	v_pk_add_f32 v[0:1], v[4:5], v[92:93]
	v_add_u32_e32 v2, s18, v94
	ds_write_b64 v2, v[0:1]
	v_pk_add_f32 v[0:1], v[4:5], v[92:93] neg_lo:[0,1] neg_hi:[0,1]
	v_lshl_add_u32 v2, v10, 3, s18
	ds_write_b64 v2, v[0:1]
	v_add_u32_e32 v0, 0x400, v8
	v_ashrrev_i32_e32 v1, 31, v0
	v_add_u32_sdwa v1, v0, v1 dst_sel:DWORD dst_unused:UNUSED_PAD src0_sel:DWORD src1_sel:BYTE_3
	v_ashrrev_i32_e32 v1, 8, v1
	v_mul_i32_i24_e32 v2, 0x100, v1
	v_sub_u32_e32 v0, v0, v2
	v_add_u32_e32 v7, 0x100, v0
	v_mul_i32_i24_e32 v6, 0x220, v1
	v_ashrrev_i32_e32 v1, 4, v0
	v_lshrrev_b32_e32 v10, 4, v7
	v_add_u32_e32 v4, v1, v0
	v_add3_u32 v1, v6, v0, v10
	v_lshl_add_u32 v1, v1, 3, 0
	v_lshl_add_u32 v2, v0, 3, 0
	ds_read_b64 v[0:1], v1 offset:8320
	ds_read_b64 v[2:3], v2 offset:4224
	v_add_lshl_u32 v94, v4, v6, 3
	v_add_u32_e32 v4, 0, v94
	ds_read_b64 v[4:5], v4 offset:6272
	v_add3_u32 v10, v6, v7, v10
	s_waitcnt lgkmcnt(1)
	v_pk_mul_f32 v[6:7], v[0:1], v[2:3] op_sel:[1,1] op_sel_hi:[1,0]
	s_nop 0
	v_pk_fma_f32 v[92:93], v[0:1], v[2:3], v[6:7] op_sel_hi:[0,1,1] neg_lo:[0,0,1]
	s_waitcnt lgkmcnt(0)
	v_pk_add_f32 v[0:1], v[4:5], v[92:93]
	v_add_u32_e32 v2, s18, v94
	ds_write_b64 v2, v[0:1]
	v_pk_add_f32 v[0:1], v[4:5], v[92:93] neg_lo:[0,1] neg_hi:[0,1]
	v_lshl_add_u32 v2, v10, 3, s18
	ds_write_b64 v2, v[0:1]
	v_add_u32_e32 v0, 0x600, v8
	v_ashrrev_i32_e32 v1, 31, v0
	v_add_u32_sdwa v1, v0, v1 dst_sel:DWORD dst_unused:UNUSED_PAD src0_sel:DWORD src1_sel:BYTE_3
	v_ashrrev_i32_e32 v1, 8, v1
	v_mul_i32_i24_e32 v2, 0x100, v1
	v_sub_u32_e32 v0, v0, v2
	v_add_u32_e32 v7, 0x100, v0
	v_mul_i32_i24_e32 v6, 0x220, v1
	v_ashrrev_i32_e32 v1, 4, v0
	v_lshrrev_b32_e32 v10, 4, v7
	v_add_u32_e32 v4, v1, v0
	v_add3_u32 v1, v6, v0, v10
	v_lshl_add_u32 v1, v1, 3, 0
	v_lshl_add_u32 v2, v0, 3, 0
	ds_read_b64 v[0:1], v1 offset:8320
	ds_read_b64 v[2:3], v2 offset:4224
	v_add_lshl_u32 v94, v4, v6, 3
	v_add_u32_e32 v4, 0, v94
	ds_read_b64 v[4:5], v4 offset:6272
	v_add3_u32 v10, v6, v7, v10
	s_waitcnt lgkmcnt(1)
	v_pk_mul_f32 v[6:7], v[0:1], v[2:3] op_sel:[1,1] op_sel_hi:[1,0]
	s_nop 0
	v_pk_fma_f32 v[92:93], v[0:1], v[2:3], v[6:7] op_sel_hi:[0,1,1] neg_lo:[0,0,1]
	s_waitcnt lgkmcnt(0)
	v_pk_add_f32 v[0:1], v[4:5], v[92:93]
	v_add_u32_e32 v2, s18, v94
	ds_write_b64 v2, v[0:1]
	v_pk_add_f32 v[0:1], v[4:5], v[92:93] neg_lo:[0,1] neg_hi:[0,1]
	v_lshl_add_u32 v2, v10, 3, s18
	ds_write_b64 v2, v[0:1]
	v_add_u32_e32 v0, 0x800, v8
	v_ashrrev_i32_e32 v1, 31, v0
	v_add_u32_sdwa v1, v0, v1 dst_sel:DWORD dst_unused:UNUSED_PAD src0_sel:DWORD src1_sel:BYTE_3
	v_ashrrev_i32_e32 v1, 8, v1
	v_mul_i32_i24_e32 v2, 0x100, v1
	v_sub_u32_e32 v0, v0, v2
	v_add_u32_e32 v7, 0x100, v0
	v_mul_i32_i24_e32 v6, 0x220, v1
	v_ashrrev_i32_e32 v1, 4, v0
	v_lshrrev_b32_e32 v10, 4, v7
	v_add_u32_e32 v4, v1, v0
	v_add3_u32 v1, v6, v0, v10
	v_lshl_add_u32 v1, v1, 3, 0
	v_lshl_add_u32 v2, v0, 3, 0
	ds_read_b64 v[0:1], v1 offset:8320
	ds_read_b64 v[2:3], v2 offset:4224
	v_add_lshl_u32 v94, v4, v6, 3
	v_add_u32_e32 v4, 0, v94
	ds_read_b64 v[4:5], v4 offset:6272
	v_add3_u32 v10, v6, v7, v10
	s_waitcnt lgkmcnt(1)
	v_pk_mul_f32 v[6:7], v[0:1], v[2:3] op_sel:[1,1] op_sel_hi:[1,0]
	s_nop 0
	v_pk_fma_f32 v[92:93], v[0:1], v[2:3], v[6:7] op_sel_hi:[0,1,1] neg_lo:[0,0,1]
	s_waitcnt lgkmcnt(0)
	v_pk_add_f32 v[0:1], v[4:5], v[92:93]
	v_add_u32_e32 v2, s18, v94
	ds_write_b64 v2, v[0:1]
	v_pk_add_f32 v[0:1], v[4:5], v[92:93] neg_lo:[0,1] neg_hi:[0,1]
	v_lshl_add_u32 v2, v10, 3, s18
	ds_write_b64 v2, v[0:1]
	v_add_u32_e32 v0, 0xa00, v8
	v_ashrrev_i32_e32 v1, 31, v0
	v_add_u32_sdwa v1, v0, v1 dst_sel:DWORD dst_unused:UNUSED_PAD src0_sel:DWORD src1_sel:BYTE_3
	v_ashrrev_i32_e32 v1, 8, v1
	v_mul_i32_i24_e32 v2, 0x100, v1
	v_sub_u32_e32 v0, v0, v2
	v_add_u32_e32 v7, 0x100, v0
	v_mul_i32_i24_e32 v6, 0x220, v1
	v_ashrrev_i32_e32 v1, 4, v0
	v_lshrrev_b32_e32 v10, 4, v7
	v_add_u32_e32 v4, v1, v0
	v_add3_u32 v1, v6, v0, v10
	v_lshl_add_u32 v1, v1, 3, 0
	v_lshl_add_u32 v2, v0, 3, 0
	ds_read_b64 v[0:1], v1 offset:8320
	ds_read_b64 v[2:3], v2 offset:4224
	v_add_lshl_u32 v94, v4, v6, 3
	v_add_u32_e32 v4, 0, v94
	ds_read_b64 v[4:5], v4 offset:6272
	v_add3_u32 v10, v6, v7, v10
	s_waitcnt lgkmcnt(1)
	v_pk_mul_f32 v[6:7], v[0:1], v[2:3] op_sel:[1,1] op_sel_hi:[1,0]
	s_nop 0
	v_pk_fma_f32 v[92:93], v[0:1], v[2:3], v[6:7] op_sel_hi:[0,1,1] neg_lo:[0,0,1]
	s_waitcnt lgkmcnt(0)
	v_pk_add_f32 v[0:1], v[4:5], v[92:93]
	v_add_u32_e32 v2, s18, v94
	ds_write_b64 v2, v[0:1]
	v_pk_add_f32 v[0:1], v[4:5], v[92:93] neg_lo:[0,1] neg_hi:[0,1]
	v_lshl_add_u32 v2, v10, 3, s18
	ds_write_b64 v2, v[0:1]
	v_add_u32_e32 v0, 0xc00, v8
	v_ashrrev_i32_e32 v1, 31, v0
	v_add_u32_sdwa v1, v0, v1 dst_sel:DWORD dst_unused:UNUSED_PAD src0_sel:DWORD src1_sel:BYTE_3
	v_ashrrev_i32_e32 v1, 8, v1
	v_mul_i32_i24_e32 v2, 0x100, v1
	v_sub_u32_e32 v0, v0, v2
	v_add_u32_e32 v7, 0x100, v0
	v_mul_i32_i24_e32 v6, 0x220, v1
	v_ashrrev_i32_e32 v1, 4, v0
	v_lshrrev_b32_e32 v10, 4, v7
	v_add_u32_e32 v4, v1, v0
	v_add3_u32 v1, v6, v0, v10
	v_lshl_add_u32 v1, v1, 3, 0
	v_lshl_add_u32 v2, v0, 3, 0
	ds_read_b64 v[0:1], v1 offset:8320
	ds_read_b64 v[2:3], v2 offset:4224
	v_add_lshl_u32 v94, v4, v6, 3
	v_add_u32_e32 v4, 0, v94
	ds_read_b64 v[4:5], v4 offset:6272
	v_add3_u32 v10, v6, v7, v10
	s_waitcnt lgkmcnt(1)
	v_pk_mul_f32 v[6:7], v[0:1], v[2:3] op_sel:[1,1] op_sel_hi:[1,0]
	s_nop 0
	v_pk_fma_f32 v[92:93], v[0:1], v[2:3], v[6:7] op_sel_hi:[0,1,1] neg_lo:[0,0,1]
	s_waitcnt lgkmcnt(0)
	v_pk_add_f32 v[0:1], v[4:5], v[92:93]
	v_add_u32_e32 v2, s18, v94
	ds_write_b64 v2, v[0:1]
	v_pk_add_f32 v[0:1], v[4:5], v[92:93] neg_lo:[0,1] neg_hi:[0,1]
	v_lshl_add_u32 v2, v10, 3, s18
	ds_write_b64 v2, v[0:1]
	v_add_u32_e32 v0, 0xe00, v8
	v_ashrrev_i32_e32 v1, 31, v0
	v_add_u32_sdwa v1, v0, v1 dst_sel:DWORD dst_unused:UNUSED_PAD src0_sel:DWORD src1_sel:BYTE_3
	v_ashrrev_i32_e32 v1, 8, v1
	v_mul_i32_i24_e32 v2, 0x100, v1
	v_sub_u32_e32 v0, v0, v2
	v_add_u32_e32 v7, 0x100, v0
	v_mul_i32_i24_e32 v6, 0x220, v1
	v_ashrrev_i32_e32 v1, 4, v0
	v_lshrrev_b32_e32 v8, 4, v7
	v_add_u32_e32 v4, v1, v0
	v_add3_u32 v1, v6, v0, v8
	v_lshl_add_u32 v1, v1, 3, 0
	v_lshl_add_u32 v2, v0, 3, 0
	ds_read_b64 v[0:1], v1 offset:8320
	ds_read_b64 v[2:3], v2 offset:4224
	v_add_lshl_u32 v10, v4, v6, 3
	v_add_u32_e32 v4, 0, v10
	ds_read_b64 v[4:5], v4 offset:6272
	v_add3_u32 v8, v6, v7, v8
	s_waitcnt lgkmcnt(1)
	v_pk_mul_f32 v[6:7], v[0:1], v[2:3] op_sel:[1,1] op_sel_hi:[1,0]
	s_nop 0
	v_pk_fma_f32 v[92:93], v[0:1], v[2:3], v[6:7] op_sel_hi:[0,1,1] neg_lo:[0,0,1]
	s_waitcnt lgkmcnt(0)
	v_pk_add_f32 v[0:1], v[4:5], v[92:93]
	v_add_u32_e32 v2, s18, v10
	ds_write_b64 v2, v[0:1]
	v_pk_add_f32 v[0:1], v[4:5], v[92:93] neg_lo:[0,1] neg_hi:[0,1]
	v_lshl_add_u32 v2, v8, 3, s18
	v_mov_b32_e32 v4, v180
	ds_write_b64 v2, v[0:1]
	s_waitcnt lgkmcnt(0)
	s_barrier
	s_nop 0
	v_cmp_gt_i32_e32 vcc, s16, v4
	s_and_saveexec_b64 s[2:3], vcc
	s_cbranch_execz .LBB0_503
	v_ashrrev_i32_e32 v5, 31, v4
	v_lshrrev_b32_e32 v5, 27, v5
	v_add_u32_e32 v5, v4, v5
	v_lshrrev_b32_e32 v8, 5, v5
	v_and_b32_e32 v5, 0xffffffe0, v5
	v_sub_u32_e32 v10, v4, v5
	v_mul_lo_u32 v8, v8, s17
	v_ashrrev_i32_e32 v5, 4, v10
	v_add_u32_e32 v4, s18, v8
	v_lshlrev_b32_e32 v98, 3, v10
	v_lshlrev_b32_e32 v5, 3, v5
	v_add3_u32 v99, v4, v98, v5
	v_pk_mul_f32 v[94:95], v[46:47], s[34:35] op_sel_hi:[1,0]
	v_pk_mul_f32 v[96:97], v[48:49], s[34:35] op_sel_hi:[1,0]
	ds_read2_b64 v[46:49], v99 offset1:34
	v_pk_mul_f32 v[92:93], v[44:45], s[34:35] op_sel_hi:[1,0]
	v_pk_mul_f32 v[6:7], v[72:73], s[34:35] op_sel_hi:[1,0]
	v_pk_mul_f32 v[50:51], v[50:51], s[34:35] op_sel_hi:[1,0]
	v_pk_mul_f32 v[2:3], v[74:75], s[34:35] op_sel_hi:[1,0]
	s_waitcnt lgkmcnt(0)
	v_pk_mul_f32 v[4:5], v[92:93], v[46:47] op_sel:[1,1] op_sel_hi:[0,1]
	v_pk_fma_f32 v[44:45], v[92:93], v[46:47], v[4:5] op_sel_hi:[1,0,1] neg_lo:[0,0,1]
	v_pk_mul_f32 v[46:47], v[94:95], v[48:49] op_sel:[1,1] op_sel_hi:[0,1]
	v_pk_fma_f32 v[4:5], v[94:95], v[48:49], v[46:47] op_sel_hi:[1,0,1] neg_lo:[0,0,1]
	v_pk_mul_f32 v[52:53], v[52:53], s[34:35] op_sel_hi:[1,0]
	ds_read2_b64 v[46:49], v99 offset0:68 offset1:102
	v_pk_mul_f32 v[54:55], v[54:55], s[34:35] op_sel_hi:[1,0]
	v_pk_mul_f32 v[0:1], v[76:77], s[34:35] op_sel_hi:[1,0]
	v_pk_mul_f32 v[56:57], v[56:57], s[34:35] op_sel_hi:[1,0]
	v_pk_mul_f32 v[58:59], v[58:59], s[34:35] op_sel_hi:[1,0]
	s_waitcnt lgkmcnt(0)
	v_pk_mul_f32 v[72:73], v[96:97], v[46:47] op_sel:[1,1] op_sel_hi:[0,1]
	v_pk_fma_f32 v[74:75], v[96:97], v[46:47], v[72:73] op_sel_hi:[1,0,1] neg_lo:[0,0,1]
	v_add_u32_e32 v92, 0x800, v99
	v_pk_mul_f32 v[46:47], v[50:51], v[48:49] op_sel:[1,1] op_sel_hi:[0,1]
	v_pk_fma_f32 v[72:73], v[50:51], v[48:49], v[46:47] op_sel_hi:[1,0,1] neg_lo:[0,0,1]
	v_pk_mul_f32 v[60:61], v[60:61], s[34:35] op_sel_hi:[1,0]
	ds_read2_b64 v[46:49], v99 offset0:136 offset1:170
	v_pk_mul_f32 v[62:63], v[62:63], s[34:35] op_sel_hi:[1,0]
	v_pk_mul_f32 v[64:65], v[64:65], s[34:35] op_sel_hi:[1,0]
	v_pk_mul_f32 v[66:67], v[66:67], s[34:35] op_sel_hi:[1,0]
	v_pk_mul_f32 v[70:71], v[70:71], s[34:35] op_sel_hi:[1,0]
	s_waitcnt lgkmcnt(0)
	v_pk_mul_f32 v[50:51], v[52:53], v[46:47] op_sel:[1,1] op_sel_hi:[0,1]
	v_pk_fma_f32 v[76:77], v[52:53], v[46:47], v[50:51] op_sel_hi:[1,0,1] neg_lo:[0,0,1]
	s_mov_b32 s29, s30
	v_pk_mul_f32 v[46:47], v[54:55], v[48:49] op_sel:[1,1] op_sel_hi:[0,1]
	v_pk_fma_f32 v[50:51], v[54:55], v[48:49], v[46:47] op_sel_hi:[1,0,1] neg_lo:[0,0,1]
	v_add_u32_e32 v8, 0, v8
	ds_read2_b64 v[46:49], v99 offset0:204 offset1:238
	v_lshlrev_b32_e32 v10, 7, v10
	v_add3_u32 v8, v8, v10, v98
	v_add_u32_e32 v10, 0x1880, v8
	s_waitcnt lgkmcnt(0)
	v_pk_mul_f32 v[52:53], v[56:57], v[46:47] op_sel:[1,1] op_sel_hi:[0,1]
	v_pk_fma_f32 v[54:55], v[56:57], v[46:47], v[52:53] op_sel_hi:[1,0,1] neg_lo:[0,0,1]
	s_nop 0
	v_pk_mul_f32 v[46:47], v[58:59], v[48:49] op_sel:[1,1] op_sel_hi:[0,1]
	v_pk_fma_f32 v[52:53], v[58:59], v[48:49], v[46:47] op_sel_hi:[1,0,1] neg_lo:[0,0,1]
	s_nop 0
	ds_read2_b64 v[46:49], v92 offset0:16 offset1:50
	s_waitcnt lgkmcnt(0)
	v_pk_mul_f32 v[56:57], v[60:61], v[46:47] op_sel:[1,1] op_sel_hi:[0,1]
	v_pk_fma_f32 v[58:59], v[60:61], v[46:47], v[56:57] op_sel_hi:[1,0,1] neg_lo:[0,0,1]
	s_nop 0
	v_pk_mul_f32 v[46:47], v[62:63], v[48:49] op_sel:[1,1] op_sel_hi:[0,1]
	v_pk_fma_f32 v[56:57], v[62:63], v[48:49], v[46:47] op_sel_hi:[1,0,1] neg_lo:[0,0,1]
	s_nop 0
	ds_read2_b64 v[46:49], v92 offset0:84 offset1:118
	s_waitcnt lgkmcnt(0)
	v_pk_mul_f32 v[60:61], v[64:65], v[46:47] op_sel:[1,1] op_sel_hi:[0,1]
	v_pk_fma_f32 v[62:63], v[64:65], v[46:47], v[60:61] op_sel_hi:[1,0,1] neg_lo:[0,0,1]
	s_nop 0
	v_pk_mul_f32 v[46:47], v[66:67], v[48:49] op_sel:[1,1] op_sel_hi:[0,1]
	v_pk_fma_f32 v[60:61], v[66:67], v[48:49], v[46:47] op_sel_hi:[1,0,1] neg_lo:[0,0,1]
	s_nop 0
	ds_read2_b64 v[46:49], v92 offset0:152 offset1:186
	s_waitcnt lgkmcnt(0)
	v_pk_mul_f32 v[64:65], v[70:71], v[46:47] op_sel:[1,1] op_sel_hi:[0,1]
	v_pk_fma_f32 v[66:67], v[70:71], v[46:47], v[64:65] op_sel_hi:[1,0,1] neg_lo:[0,0,1]
	s_nop 0
	v_pk_mul_f32 v[46:47], v[6:7], v[48:49] op_sel:[1,1] op_sel_hi:[0,1]
	v_pk_fma_f32 v[64:65], v[6:7], v[48:49], v[46:47] op_sel_hi:[1,0,1] neg_lo:[0,0,1]
	ds_read2_b64 v[46:49], v92 offset0:220 offset1:254
	s_waitcnt lgkmcnt(0)
	v_pk_mul_f32 v[6:7], v[2:3], v[46:47] op_sel:[1,1] op_sel_hi:[0,1]
	v_pk_fma_f32 v[70:71], v[2:3], v[46:47], v[6:7] op_sel_hi:[1,0,1] neg_lo:[0,0,1]
	v_pk_add_f32 v[46:47], v[76:77], v[66:67] neg_lo:[0,1] neg_hi:[0,1]
	v_pk_mul_f32 v[2:3], v[0:1], v[48:49] op_sel:[1,1] op_sel_hi:[0,1]
	v_pk_fma_f32 v[6:7], v[0:1], v[48:49], v[2:3] op_sel_hi:[1,0,1] neg_lo:[0,0,1]
	v_pk_add_f32 v[2:3], v[44:45], v[58:59] neg_lo:[0,1] neg_hi:[0,1]
	v_xor_b32_e32 v48, 0x80000000, v47
	v_mov_b32_e32 v49, v46
	v_pk_add_f32 v[0:1], v[44:45], v[58:59]
	v_pk_add_f32 v[44:45], v[76:77], v[66:67]
	v_pk_add_f32 v[58:59], v[2:3], v[48:49]
	v_pk_add_f32 v[2:3], v[2:3], v[48:49] neg_lo:[0,1] neg_hi:[0,1]
	v_pk_add_f32 v[48:49], v[50:51], v[64:65]
	v_pk_add_f32 v[50:51], v[50:51], v[64:65] neg_lo:[0,1] neg_hi:[0,1]
	v_pk_add_f32 v[46:47], v[0:1], v[44:45]
	v_pk_add_f32 v[0:1], v[0:1], v[44:45] neg_lo:[0,1] neg_hi:[0,1]
	v_pk_add_f32 v[44:45], v[4:5], v[56:57]
	v_pk_add_f32 v[4:5], v[4:5], v[56:57] neg_lo:[0,1] neg_hi:[0,1]
	v_xor_b32_e32 v56, 0x80000000, v51
	v_mov_b32_e32 v57, v50
	v_pk_add_f32 v[50:51], v[44:45], v[48:49]
	v_pk_add_f32 v[64:65], v[4:5], v[56:57]
	v_pk_add_f32 v[44:45], v[44:45], v[48:49] neg_lo:[0,1] neg_hi:[0,1]
	v_pk_add_f32 v[4:5], v[4:5], v[56:57] neg_lo:[0,1] neg_hi:[0,1]
	v_pk_add_f32 v[48:49], v[74:75], v[62:63]
	v_pk_add_f32 v[56:57], v[74:75], v[62:63] neg_lo:[0,1] neg_hi:[0,1]
	v_pk_add_f32 v[62:63], v[54:55], v[70:71]
	v_pk_add_f32 v[54:55], v[54:55], v[70:71] neg_lo:[0,1] neg_hi:[0,1]
	s_nop 0
	v_xor_b32_e32 v66, 0x80000000, v55
	v_mov_b32_e32 v67, v54
	v_pk_add_f32 v[70:71], v[56:57], v[66:67]
	v_pk_add_f32 v[56:57], v[56:57], v[66:67] neg_lo:[0,1] neg_hi:[0,1]
	v_pk_add_f32 v[66:67], v[52:53], v[6:7]
	v_pk_add_f32 v[6:7], v[52:53], v[6:7] neg_lo:[0,1] neg_hi:[0,1]
	v_pk_add_f32 v[54:55], v[48:49], v[62:63]
	v_pk_add_f32 v[48:49], v[48:49], v[62:63] neg_lo:[0,1] neg_hi:[0,1]
	v_pk_add_f32 v[62:63], v[72:73], v[60:61]
	v_pk_add_f32 v[60:61], v[72:73], v[60:61] neg_lo:[0,1] neg_hi:[0,1]
	v_xor_b32_e32 v52, 0x80000000, v7
	v_mov_b32_e32 v53, v6
	v_pk_add_f32 v[72:73], v[60:61], v[52:53]
	v_pk_add_f32 v[52:53], v[60:61], v[52:53] neg_lo:[0,1] neg_hi:[0,1]
	v_pk_mul_f32 v[60:61], v[64:65], s[14:15] op_sel_hi:[1,0]
	v_pk_add_f32 v[6:7], v[62:63], v[66:67]
	v_pk_add_f32 v[62:63], v[62:63], v[66:67] neg_lo:[0,1] neg_hi:[0,1]
	v_pk_fma_f32 v[66:67], v[64:65], s[22:23], v[60:61] op_sel:[0,0,1] op_sel_hi:[1,0,0] neg_lo:[0,0,1]
	s_nop 0
	v_pk_mul_f32 v[60:61], v[44:45], s[24:25] op_sel_hi:[1,0]
	s_nop 0
	v_pk_fma_f32 v[64:65], v[44:45], s[24:25], v[60:61] op_sel:[0,0,1] op_sel_hi:[1,0,0] neg_lo:[0,0,1]
	v_pk_mul_f32 v[60:61], v[4:5], s[22:23] op_sel_hi:[1,0]
	v_pk_fma_f32 v[74:75], v[4:5], s[14:15], v[60:61] op_sel:[0,0,1] op_sel_hi:[1,0,0] neg_lo:[0,0,1]
	s_nop 0
	v_pk_mul_f32 v[4:5], v[70:71], s[24:25] op_sel_hi:[1,0]
	s_nop 0
	v_pk_fma_f32 v[60:61], v[70:71], s[24:25], v[4:5] op_sel:[0,0,1] op_sel_hi:[1,0,0] neg_lo:[0,0,1]
	s_nop 0
	v_pk_fma_f32 v[4:5], v[48:49], 0, v[48:49] op_sel:[0,0,1] op_sel_hi:[1,0,0] neg_lo:[0,0,1]
	s_nop 0
	v_pk_mul_f32 v[48:49], v[56:57], s[26:27] op_sel_hi:[1,0]
	s_nop 0
	v_pk_fma_f32 v[70:71], v[56:57], s[26:27], v[48:49] op_sel:[0,0,1] op_sel_hi:[1,0,0] neg_hi:[0,0,1]
	v_pk_mul_f32 v[56:57], v[72:73], s[22:23] op_sel_hi:[1,0]
	v_pk_fma_f32 v[76:77], v[72:73], s[14:15], v[56:57] op_sel:[0,0,1] op_sel_hi:[1,0,0] neg_lo:[0,0,1]
	s_mov_b32 s15, s28
	v_pk_mul_f32 v[56:57], v[62:63], s[26:27] op_sel_hi:[1,0]
	v_pk_add_f32 v[48:49], v[2:3], v[70:71]
	v_pk_fma_f32 v[72:73], v[62:63], s[26:27], v[56:57] op_sel:[0,0,1] op_sel_hi:[1,0,0] neg_hi:[0,0,1]
	v_pk_add_f32 v[2:3], v[2:3], v[70:71] neg_lo:[0,1] neg_hi:[0,1]
	v_pk_mul_f32 v[56:57], v[52:53], s[28:29] op_sel_hi:[0,1]
	v_pk_fma_f32 v[52:53], v[52:53], s[14:15], v[56:57] op_sel:[1,0,0]
	v_pk_add_f32 v[56:57], v[46:47], v[54:55]
	v_pk_add_f32 v[46:47], v[46:47], v[54:55] neg_lo:[0,1] neg_hi:[0,1]
	v_pk_add_f32 v[54:55], v[50:51], v[6:7]
	v_pk_add_f32 v[6:7], v[50:51], v[6:7] neg_lo:[0,1] neg_hi:[0,1]
	v_pk_add_f32 v[44:45], v[64:65], v[72:73] neg_lo:[0,1] neg_hi:[0,1]
	v_xor_b32_e32 v50, 0x80000000, v7
	v_mov_b32_e32 v51, v6
	v_pk_add_f32 v[6:7], v[56:57], v[54:55]
	v_pk_add_f32 v[62:63], v[46:47], v[50:51]
	v_pk_add_f32 v[54:55], v[56:57], v[54:55] neg_lo:[0,1] neg_hi:[0,1]
	v_pk_add_f32 v[46:47], v[46:47], v[50:51] neg_lo:[0,1] neg_hi:[0,1]
	v_pk_add_f32 v[50:51], v[58:59], v[60:61]
	v_pk_add_f32 v[56:57], v[58:59], v[60:61] neg_lo:[0,1] neg_hi:[0,1]
	v_pk_add_f32 v[58:59], v[66:67], v[76:77]
	v_pk_add_f32 v[60:61], v[66:67], v[76:77] neg_lo:[0,1] neg_hi:[0,1]
	s_nop 0
	v_xor_b32_e32 v66, 0x80000000, v61
	v_mov_b32_e32 v67, v60
	v_pk_add_f32 v[60:61], v[50:51], v[58:59]
	v_pk_add_f32 v[50:51], v[50:51], v[58:59] neg_lo:[0,1] neg_hi:[0,1]
	v_pk_add_f32 v[58:59], v[0:1], v[4:5]
	v_pk_add_f32 v[0:1], v[0:1], v[4:5] neg_lo:[0,1] neg_hi:[0,1]
	v_pk_add_f32 v[4:5], v[64:65], v[72:73]
	v_xor_b32_e32 v64, 0x80000000, v45
	v_mov_b32_e32 v65, v44
	v_pk_add_f32 v[44:45], v[58:59], v[4:5]
	v_pk_add_f32 v[4:5], v[58:59], v[4:5] neg_lo:[0,1] neg_hi:[0,1]
	v_pk_add_f32 v[58:59], v[74:75], v[52:53]
	v_pk_add_f32 v[52:53], v[74:75], v[52:53] neg_lo:[0,1] neg_hi:[0,1]
	v_pk_add_f32 v[76:77], v[56:57], v[66:67]
	v_pk_add_f32 v[56:57], v[56:57], v[66:67] neg_lo:[0,1] neg_hi:[0,1]
	v_pk_add_f32 v[66:67], v[0:1], v[64:65]
	v_pk_add_f32 v[0:1], v[0:1], v[64:65] neg_lo:[0,1] neg_hi:[0,1]
	v_xor_b32_e32 v64, 0x80000000, v53
	v_mov_b32_e32 v65, v52
	v_pk_add_f32 v[52:53], v[48:49], v[58:59]
	ds_write2_b64 v10, v[6:7], v[60:61] offset1:1
	v_add_u32_e32 v6, 0x1890, v8
	ds_write2_b64 v6, v[44:45], v[52:53] offset1:1
	v_add_u32_e32 v6, 0x18a0, v8
	v_pk_add_f32 v[70:71], v[2:3], v[64:65]
	ds_write2_b64 v6, v[62:63], v[76:77] offset1:1
	v_add_u32_e32 v6, 0x18b0, v8
	ds_write2_b64 v6, v[66:67], v[70:71] offset1:1
	v_add_u32_e32 v6, 0x18c0, v8
	v_pk_add_f32 v[48:49], v[48:49], v[58:59] neg_lo:[0,1] neg_hi:[0,1]
	ds_write2_b64 v6, v[54:55], v[50:51] offset1:1
	v_add_u32_e32 v6, 0x18d0, v8
	ds_write2_b64 v6, v[4:5], v[48:49] offset1:1
	v_add_u32_e32 v4, 0x18e0, v8
	v_pk_add_f32 v[2:3], v[2:3], v[64:65] neg_lo:[0,1] neg_hi:[0,1]
	ds_write2_b64 v4, v[46:47], v[56:57] offset1:1
	v_add_u32_e32 v4, 0x18f0, v8
	ds_write2_b64 v4, v[0:1], v[2:3] offset1:1
.LBB0_503:
	s_or_b64 exec, exec, s[2:3]
	v_mov_b32_e32 v0, v180
	s_waitcnt lgkmcnt(0)
	s_barrier
	s_nop 0
	v_cmp_gt_i32_e32 vcc, s16, v0
	s_and_saveexec_b64 s[2:3], vcc
	s_cbranch_execz .LBB0_431
	v_ashrrev_i32_e32 v1, 31, v0
	v_lshrrev_b32_e32 v1, 27, v1
	v_add_u32_e32 v1, v0, v1
	v_lshrrev_b32_e32 v2, 5, v1
	v_and_b32_e32 v1, 0xffffffe0, v1
	v_sub_u32_e32 v0, v0, v1
	v_lshrrev_b16_sdwa v1, v175, sext(v0) dst_sel:DWORD dst_unused:UNUSED_PAD src0_sel:DWORD src1_sel:BYTE_0
	v_and_b32_e32 v1, 15, v1
	v_add_u16_e32 v1, v0, v1
	v_ashrrev_i16_sdwa v8, v176, sext(v1) dst_sel:DWORD dst_unused:UNUSED_PAD src0_sel:DWORD src1_sel:BYTE_0
	v_and_b32_e32 v1, 0xf0, v1
	v_sub_u16_e32 v44, v0, v1
	v_mul_lo_u32 v10, v2, s17
	v_lshlrev_b32_e32 v2, 3, v0
	v_ashrrev_i32_e32 v0, 4, v0
	v_add_u32_e32 v1, 0, v10
	v_lshlrev_b32_e32 v0, 3, v0
	v_add3_u32 v4, v1, v2, v0
	v_bfe_i32 v72, v44, 0, 8
	v_add_u32_e32 v5, 0x1800, v4
	v_mad_i32_i24 v73, v72, s19, 0
	ds_read2_b64 v[0:3], v5 offset0:16 offset1:50
	ds_read2_b64 v[48:51], v5 offset0:84 offset1:118
	ds_read2_b64 v[56:59], v5 offset0:152 offset1:186
	ds_read2_b64 v[60:63], v5 offset0:220 offset1:254
	v_add_u32_e32 v5, 0x2000, v4
	v_add_u32_e32 v44, 0x808, v73
	ds_read2_b64 v[64:67], v5 offset0:32 offset1:66
	ds_read2_b64 v[74:77], v5 offset0:100 offset1:134
	ds_read2_b64 v[92:95], v5 offset0:168 offset1:202
	ds_read2_b64 v[52:55], v44 offset1:1
	v_add_u32_e32 v4, 0x2400, v4
	ds_read2_b64 v[4:7], v4 offset0:108 offset1:142
	s_mov_b32 s29, s30
	v_bfe_i32 v8, v8, 0, 16
	s_waitcnt lgkmcnt(1)
	v_pk_mul_f32 v[44:45], v[2:3], v[52:53] op_sel:[1,1] op_sel_hi:[0,1]
	v_pk_fma_f32 v[46:47], v[2:3], v[52:53], v[44:45]
	v_pk_fma_f32 v[2:3], v[2:3], v[52:53], v[44:45] op_sel_hi:[1,0,1] neg_lo:[0,0,1] neg_hi:[0,0,1]
	v_lshl_add_u32 v8, v8, 8, v72
	v_mov_b32_e32 v2, v55
	v_mov_b32_e32 v47, v3
	v_pk_mul_f32 v[2:3], v[48:49], v[2:3] op_sel:[1,0] op_sel_hi:[0,0]
	v_pk_fma_f32 v[44:45], v[48:49], v[54:55], v[2:3] op_sel_hi:[1,0,1] neg_hi:[0,0,1]
	v_add_u32_e32 v10, s18, v10
	v_add_u32_e32 v2, 0x818, v73
	ds_read2_b64 v[96:99], v2 offset1:1
	s_waitcnt lgkmcnt(0)
	v_pk_mul_f32 v[48:49], v[50:51], v[96:97] op_sel:[1,1] op_sel_hi:[0,1]
	v_pk_fma_f32 v[2:3], v[50:51], v[96:97], v[48:49]
	v_pk_fma_f32 v[48:49], v[50:51], v[96:97], v[48:49] op_sel_hi:[1,0,1] neg_lo:[0,0,1] neg_hi:[0,0,1]
	s_nop 0
	v_mov_b32_e32 v48, v99
	v_mov_b32_e32 v3, v49
	v_pk_mul_f32 v[48:49], v[56:57], v[48:49] op_sel:[1,0] op_sel_hi:[0,0]
	v_pk_fma_f32 v[54:55], v[56:57], v[98:99], v[48:49] op_sel_hi:[1,0,1] neg_hi:[0,0,1]
	s_nop 0
	v_add_u32_e32 v48, 0x828, v73
	ds_read2_b64 v[96:99], v48 offset1:1
	s_waitcnt lgkmcnt(0)
	v_pk_mul_f32 v[48:49], v[58:59], v[96:97] op_sel:[1,1] op_sel_hi:[0,1]
	v_pk_fma_f32 v[52:53], v[58:59], v[96:97], v[48:49]
	v_pk_fma_f32 v[48:49], v[58:59], v[96:97], v[48:49] op_sel_hi:[1,0,1] neg_lo:[0,0,1] neg_hi:[0,0,1]
	s_nop 0
	v_mov_b32_e32 v48, v99
	v_mov_b32_e32 v53, v49
	v_pk_mul_f32 v[48:49], v[60:61], v[48:49] op_sel:[1,0] op_sel_hi:[0,0]
	v_pk_fma_f32 v[50:51], v[60:61], v[98:99], v[48:49] op_sel_hi:[1,0,1] neg_hi:[0,0,1]
	s_nop 0
	v_add_u32_e32 v48, 0x838, v73
	ds_read2_b64 v[56:59], v48 offset1:1
	s_waitcnt lgkmcnt(0)
	v_pk_mul_f32 v[60:61], v[62:63], v[56:57] op_sel:[1,1] op_sel_hi:[0,1]
	v_pk_fma_f32 v[48:49], v[62:63], v[56:57], v[60:61]
	v_pk_fma_f32 v[56:57], v[62:63], v[56:57], v[60:61] op_sel_hi:[1,0,1] neg_lo:[0,0,1] neg_hi:[0,0,1]
	s_nop 0
	v_mov_b32_e32 v56, v59
	v_mov_b32_e32 v49, v57
	v_pk_mul_f32 v[56:57], v[64:65], v[56:57] op_sel:[1,0] op_sel_hi:[0,0]
	v_pk_fma_f32 v[62:63], v[64:65], v[58:59], v[56:57] op_sel_hi:[1,0,1] neg_hi:[0,0,1]
	s_nop 0
	v_add_u32_e32 v56, 0x848, v73
	ds_read2_b64 v[96:99], v56 offset1:1
	s_waitcnt lgkmcnt(0)
	v_pk_mul_f32 v[56:57], v[66:67], v[96:97] op_sel:[1,1] op_sel_hi:[0,1]
	v_pk_fma_f32 v[60:61], v[66:67], v[96:97], v[56:57]
	v_pk_fma_f32 v[56:57], v[66:67], v[96:97], v[56:57] op_sel_hi:[1,0,1] neg_lo:[0,0,1] neg_hi:[0,0,1]
	s_nop 0
	v_mov_b32_e32 v56, v99
	v_mov_b32_e32 v61, v57
	v_pk_mul_f32 v[56:57], v[74:75], v[56:57] op_sel:[1,0] op_sel_hi:[0,0]
	v_pk_fma_f32 v[58:59], v[74:75], v[98:99], v[56:57] op_sel_hi:[1,0,1] neg_hi:[0,0,1]
	s_nop 0
	v_add_u32_e32 v56, 0x858, v73
	ds_read2_b64 v[64:67], v56 offset1:1
	s_waitcnt lgkmcnt(0)
	v_pk_mul_f32 v[70:71], v[76:77], v[64:65] op_sel:[1,1] op_sel_hi:[0,1]
	v_pk_fma_f32 v[56:57], v[76:77], v[64:65], v[70:71]
	v_pk_fma_f32 v[64:65], v[76:77], v[64:65], v[70:71] op_sel_hi:[1,0,1] neg_lo:[0,0,1] neg_hi:[0,0,1]
	s_nop 0
	v_mov_b32_e32 v64, v67
	v_mov_b32_e32 v57, v65
	v_pk_mul_f32 v[64:65], v[92:93], v[64:65] op_sel:[1,0] op_sel_hi:[0,0]
	v_pk_fma_f32 v[70:71], v[92:93], v[66:67], v[64:65] op_sel_hi:[1,0,1] neg_hi:[0,0,1]
	s_nop 0
	v_add_u32_e32 v64, 0x868, v73
	ds_read2_b64 v[74:77], v64 offset1:1
	s_waitcnt lgkmcnt(0)
	v_pk_mul_f32 v[64:65], v[94:95], v[74:75] op_sel:[1,1] op_sel_hi:[0,1]
	v_pk_fma_f32 v[66:67], v[94:95], v[74:75], v[64:65]
	v_pk_fma_f32 v[64:65], v[94:95], v[74:75], v[64:65] op_sel_hi:[1,0,1] neg_lo:[0,0,1] neg_hi:[0,0,1]
	s_nop 0
	v_mov_b32_e32 v64, v77
	v_pk_mul_f32 v[74:75], v[4:5], v[64:65] op_sel:[1,0] op_sel_hi:[0,0]
	v_mov_b32_e32 v67, v65
	v_pk_fma_f32 v[64:65], v[4:5], v[76:77], v[74:75] op_sel_hi:[1,0,1] neg_hi:[0,0,1]
	s_nop 0
	ds_read_b64 v[4:5], v73 offset:2168
	s_waitcnt lgkmcnt(0)
	v_pk_mul_f32 v[74:75], v[6:7], v[4:5] op_sel:[1,1] op_sel_hi:[0,1]
	v_pk_fma_f32 v[76:77], v[6:7], v[4:5], v[74:75] op_sel_hi:[1,0,1] neg_hi:[0,0,1]
	v_pk_add_f32 v[6:7], v[54:55], v[70:71]
	v_pk_add_f32 v[4:5], v[0:1], v[62:63]
	v_pk_add_f32 v[54:55], v[54:55], v[70:71] neg_lo:[0,1] neg_hi:[0,1]
	v_pk_add_f32 v[0:1], v[0:1], v[62:63] neg_lo:[0,1] neg_hi:[0,1]
	v_xor_b32_e32 v62, 0x80000000, v55
	v_mov_b32_e32 v63, v54
	v_pk_add_f32 v[54:55], v[4:5], v[6:7]
	v_pk_add_f32 v[4:5], v[4:5], v[6:7] neg_lo:[0,1] neg_hi:[0,1]
	v_pk_add_f32 v[6:7], v[46:47], v[60:61]
	v_pk_add_f32 v[46:47], v[46:47], v[60:61] neg_lo:[0,1] neg_hi:[0,1]
	v_pk_add_f32 v[60:61], v[52:53], v[66:67]
	v_pk_add_f32 v[52:53], v[52:53], v[66:67] neg_lo:[0,1] neg_hi:[0,1]
	v_pk_add_f32 v[70:71], v[0:1], v[62:63]
	v_pk_add_f32 v[0:1], v[0:1], v[62:63] neg_lo:[0,1] neg_hi:[0,1]
	v_xor_b32_e32 v62, 0x80000000, v53
	v_mov_b32_e32 v63, v52
	v_pk_add_f32 v[52:53], v[6:7], v[60:61]
	v_pk_add_f32 v[6:7], v[6:7], v[60:61] neg_lo:[0,1] neg_hi:[0,1]
	v_pk_add_f32 v[60:61], v[44:45], v[58:59]
	v_pk_add_f32 v[44:45], v[44:45], v[58:59] neg_lo:[0,1] neg_hi:[0,1]
	v_pk_add_f32 v[58:59], v[50:51], v[64:65]
	v_pk_add_f32 v[50:51], v[50:51], v[64:65] neg_lo:[0,1] neg_hi:[0,1]
	v_pk_add_f32 v[66:67], v[46:47], v[62:63]
	v_pk_add_f32 v[46:47], v[46:47], v[62:63] neg_lo:[0,1] neg_hi:[0,1]
	v_xor_b32_e32 v62, 0x80000000, v51
	v_mov_b32_e32 v63, v50
	v_pk_add_f32 v[50:51], v[60:61], v[58:59]
	v_pk_add_f32 v[58:59], v[60:61], v[58:59] neg_lo:[0,1] neg_hi:[0,1]
	v_pk_add_f32 v[60:61], v[2:3], v[56:57]
	v_pk_add_f32 v[2:3], v[2:3], v[56:57] neg_lo:[0,1] neg_hi:[0,1]
	v_pk_add_f32 v[56:57], v[48:49], v[76:77]
	v_pk_add_f32 v[48:49], v[48:49], v[76:77] neg_lo:[0,1] neg_hi:[0,1]
	v_pk_add_f32 v[64:65], v[44:45], v[62:63]
	v_pk_add_f32 v[44:45], v[44:45], v[62:63] neg_lo:[0,1] neg_hi:[0,1]
	v_xor_b32_e32 v62, 0x80000000, v49
	v_mov_b32_e32 v63, v48
	v_pk_add_f32 v[48:49], v[60:61], v[56:57]
	v_pk_add_f32 v[56:57], v[60:61], v[56:57] neg_lo:[0,1] neg_hi:[0,1]
	v_pk_mul_f32 v[60:61], v[66:67], s[14:15] op_sel_hi:[1,0]
	v_pk_add_f32 v[74:75], v[2:3], v[62:63]
	v_pk_add_f32 v[2:3], v[2:3], v[62:63] neg_lo:[0,1] neg_hi:[0,1]
	v_pk_fma_f32 v[62:63], v[66:67], s[22:23], v[60:61] op_sel:[0,0,1] op_sel_hi:[1,0,0] neg_lo:[0,0,1]
	s_nop 0
	v_pk_mul_f32 v[60:61], v[6:7], s[24:25] op_sel_hi:[1,0]
	s_nop 0
	v_pk_fma_f32 v[66:67], v[6:7], s[24:25], v[60:61] op_sel:[0,0,1] op_sel_hi:[1,0,0] neg_lo:[0,0,1]
	v_pk_mul_f32 v[60:61], v[46:47], s[22:23] op_sel_hi:[1,0]
	v_pk_fma_f32 v[76:77], v[46:47], s[14:15], v[60:61] op_sel:[0,0,1] op_sel_hi:[1,0,0] neg_lo:[0,0,1]
	s_nop 0
	v_pk_mul_f32 v[46:47], v[64:65], s[24:25] op_sel_hi:[1,0]
	s_nop 0
	v_pk_fma_f32 v[60:61], v[64:65], s[24:25], v[46:47] op_sel:[0,0,1] op_sel_hi:[1,0,0] neg_lo:[0,0,1]
	s_nop 0
	v_pk_fma_f32 v[46:47], v[58:59], 0, v[58:59] op_sel:[0,0,1] op_sel_hi:[1,0,0] neg_lo:[0,0,1]
	s_nop 0
	v_pk_mul_f32 v[58:59], v[44:45], s[26:27] op_sel_hi:[1,0]
	s_nop 0
	v_pk_fma_f32 v[64:65], v[44:45], s[26:27], v[58:59] op_sel:[0,0,1] op_sel_hi:[1,0,0] neg_hi:[0,0,1]
	v_pk_mul_f32 v[58:59], v[74:75], s[22:23] op_sel_hi:[1,0]
	v_pk_fma_f32 v[92:93], v[74:75], s[14:15], v[58:59] op_sel:[0,0,1] op_sel_hi:[1,0,0] neg_lo:[0,0,1]
	s_mov_b32 s15, s28
	v_pk_mul_f32 v[58:59], v[56:57], s[26:27] op_sel_hi:[1,0]
	v_pk_add_f32 v[44:45], v[0:1], v[64:65]
	v_pk_fma_f32 v[74:75], v[56:57], s[26:27], v[58:59] op_sel:[0,0,1] op_sel_hi:[1,0,0] neg_hi:[0,0,1]
	v_pk_add_f32 v[0:1], v[0:1], v[64:65] neg_lo:[0,1] neg_hi:[0,1]
	v_pk_mul_f32 v[56:57], v[2:3], s[28:29] op_sel_hi:[0,1]
	v_pk_fma_f32 v[2:3], v[2:3], s[14:15], v[56:57] op_sel:[1,0,0]
	v_pk_add_f32 v[56:57], v[54:55], v[50:51]
	v_pk_add_f32 v[50:51], v[54:55], v[50:51] neg_lo:[0,1] neg_hi:[0,1]
	v_pk_add_f32 v[54:55], v[52:53], v[48:49]
	v_pk_add_f32 v[48:49], v[52:53], v[48:49] neg_lo:[0,1] neg_hi:[0,1]
	v_pk_add_f32 v[6:7], v[66:67], v[74:75]
	v_xor_b32_e32 v52, 0x80000000, v49
	v_mov_b32_e32 v53, v48
	v_pk_add_f32 v[48:49], v[56:57], v[54:55]
	v_pk_add_f32 v[58:59], v[50:51], v[52:53]
	v_pk_add_f32 v[54:55], v[56:57], v[54:55] neg_lo:[0,1] neg_hi:[0,1]
	v_pk_add_f32 v[50:51], v[50:51], v[52:53] neg_lo:[0,1] neg_hi:[0,1]
	v_pk_add_f32 v[52:53], v[70:71], v[60:61]
	v_pk_add_f32 v[56:57], v[70:71], v[60:61] neg_lo:[0,1] neg_hi:[0,1]
	v_pk_add_f32 v[60:61], v[62:63], v[92:93]
	v_pk_add_f32 v[62:63], v[62:63], v[92:93] neg_lo:[0,1] neg_hi:[0,1]
	s_nop 0
	v_xor_b32_e32 v70, 0x80000000, v63
	v_mov_b32_e32 v71, v62
	v_pk_add_f32 v[62:63], v[52:53], v[60:61]
	v_pk_add_f32 v[52:53], v[52:53], v[60:61] neg_lo:[0,1] neg_hi:[0,1]
	v_pk_add_f32 v[60:61], v[4:5], v[46:47]
	v_pk_add_f32 v[4:5], v[4:5], v[46:47] neg_lo:[0,1] neg_hi:[0,1]
	v_pk_add_f32 v[46:47], v[66:67], v[74:75] neg_lo:[0,1] neg_hi:[0,1]
	v_pk_add_f32 v[92:93], v[56:57], v[70:71]
	v_xor_b32_e32 v66, 0x80000000, v47
	v_mov_b32_e32 v67, v46
	v_pk_add_f32 v[46:47], v[60:61], v[6:7]
	v_pk_add_f32 v[6:7], v[60:61], v[6:7] neg_lo:[0,1] neg_hi:[0,1]
	v_pk_add_f32 v[60:61], v[76:77], v[2:3]
	v_pk_add_f32 v[2:3], v[76:77], v[2:3] neg_lo:[0,1] neg_hi:[0,1]
	v_pk_add_f32 v[56:57], v[56:57], v[70:71] neg_lo:[0,1] neg_hi:[0,1]
	v_xor_b32_e32 v64, 0x80000000, v3
	v_mov_b32_e32 v65, v2
	v_pk_add_f32 v[2:3], v[44:45], v[60:61]
	v_pk_add_f32 v[44:45], v[44:45], v[60:61] neg_lo:[0,1] neg_hi:[0,1]
	v_lshlrev_b32_e32 v60, 3, v8
	v_ashrrev_i32_e32 v8, 4, v8
	v_lshlrev_b32_e32 v8, 3, v8
	v_add3_u32 v8, v10, v60, v8
	v_pk_add_f32 v[70:71], v[4:5], v[66:67]
	v_pk_add_f32 v[4:5], v[4:5], v[66:67] neg_lo:[0,1] neg_hi:[0,1]
	v_pk_add_f32 v[66:67], v[0:1], v[64:65]
	v_pk_add_f32 v[0:1], v[0:1], v[64:65] neg_lo:[0,1] neg_hi:[0,1]
	ds_write2_b64 v8, v[48:49], v[62:63] offset1:17
	ds_write2_b64 v8, v[46:47], v[2:3] offset0:34 offset1:51
	ds_write2_b64 v8, v[58:59], v[92:93] offset0:68 offset1:85
	ds_write2_b64 v8, v[70:71], v[66:67] offset0:102 offset1:119
	ds_write2_b64 v8, v[54:55], v[52:53] offset0:136 offset1:153
	ds_write2_b64 v8, v[6:7], v[44:45] offset0:170 offset1:187
	ds_write2_b64 v8, v[50:51], v[56:57] offset0:204 offset1:221
	ds_write2_b64 v8, v[4:5], v[0:1] offset0:238 offset1:255
	s_branch .LBB0_431
